# GEMM K-loops: s_setprio 1 moved ahead of the s_barrier that opens each MFMA segment and the redundant post-barrier lgkmcnt(0) dropped (48 sites)
# speedup vs baseline: 1.0022x; 1.0004x over previous
; #define PG8_STAGE(bufoff, gbase, voff) do { _Pragma("unroll") for (int _i = 0; _i < 2; ++_i) \
;         __builtin_amdgcn_global_load_lds((const unsigned*)((const char*)(gbase) + (BYTE_ELEMS ? _i * r##voff + (v##voff)[0] : (v##voff)[_i])), (PG8_LAS unsigned*)(lds + (bufoff) + ldsw + _i * 8192), 16, 0, 0); } while (0)
; #define PG8_LDA(dst, b, h) do { _Pragma("unroll") for (int m = 0; m < 4; ++m) _Pragma("unroll") for (int k = 0; k < 2; ++k) dst[m][k] = *(const PG8_LAS bf16x8*)(lds + PG8_SA(b, h) + aoff + m * 2048 + k * 1024); } while (0)
; #define PG8_LDB(dst, b, h) do { _Pragma("unroll") for (int n = 0; n < 2; ++n) _Pragma("unroll") for (int k = 0; k < 2; ++k) dst[n][k] = *(const PG8_LAS bf16x8*)(lds + PG8_SB(b, h) + boff + n * 2048 + k * 1024); } while (0)
; #define PG8_WAIT_V(n) asm volatile("s_waitcnt vmcnt(" #n ")" ::: "memory")
; #define PG8_WAIT_L(n) asm volatile("s_waitcnt lgkmcnt(" #n ")" ::: "memory")
; #define PG8_BAR __builtin_amdgcn_s_barrier()
; #define PG8_SCHED __builtin_amdgcn_sched_barrier(0)
;     ...
;             PG8_LDB(B0, 0, 0); PG8_LDB(B1, 0, 1); PG8_SCHED; PG8_LDA(At, 0, 0); PG8_STAGE(PG8_SA(1, 1), a1 + hstepA, offA);
;             PG8_WAIT_V(8); PG8_WAIT_L(0); PG8_BAR; PG8_MMA(0, 0, At, B0); PG8_MMA(0, 1, At, B1); PG8_BAR; PG8_SCHED;
;             PG8_LDA(At, 0, 1); PG8_STAGE(PG8_SB(0, 0), b2, offB); PG8_STAGE(PG8_SB(0, 1), b2 + hstepB, offB); PG8_STAGE(PG8_SA(0, 0), a2, offA);
;             PG8_WAIT_V(8); PG8_WAIT_L(0); PG8_BAR; PG8_MMA(1, 0, At, B0); PG8_MMA(1, 1, At, B1); PG8_BAR; PG8_SCHED;
.LBB0_275:
	ds_read_b128 v[136:139], v149
	ds_read_b128 v[140:143], v149 offset:1024
	ds_read_b128 v[144:147], v149 offset:2048
	ds_read_b128 v[152:155], v149 offset:3072
	ds_read_b128 v[156:159], v150
	ds_read_b128 v[160:163], v150 offset:1024
	ds_read_b128 v[164:167], v150 offset:2048
	ds_read_b128 v[168:171], v150 offset:3072
	s_add_u32 s94, s70, 0xfffc0080
	s_addc_u32 s95, s71, -1
	s_cmp_eq_u32 s93, 12
	s_cselect_b32 s95, s61, s95
	s_cselect_b32 s94, s91, s94
	s_cselect_b32 s97, s59, s73
	s_cselect_b32 s96, s92, s72
	v_lshl_add_u64 v[204:205], s[70:71], 0, v[132:133]
	s_add_i32 m0, s69, 0xc000
	ds_read_b128 v[172:175], v151
	ds_read_b128 v[176:179], v151 offset:1024
	ds_read_b128 v[180:183], v151 offset:2048
	ds_read_b128 v[184:187], v151 offset:3072
	ds_read_b128 v[188:191], v151 offset:4096
	ds_read_b128 v[192:195], v151 offset:5120
	ds_read_b128 v[196:199], v151 offset:6144
	ds_read_b128 v[200:203], v151 offset:7168
	global_load_lds_dwordx4 v[204:205], off
	v_lshl_add_u64 v[204:205], v[204:205], 0, s[0:1]
	s_add_i32 m0, s69, 0xe000
	s_nop 0
	global_load_lds_dwordx4 v[204:205], off
	s_waitcnt vmcnt(8)
	s_waitcnt lgkmcnt(0)
	s_setprio 1
	s_barrier
	v_mfma_i32_16x16x64_i8 v[124:127], v[136:139], v[172:175], v[124:127]
	v_mfma_i32_16x16x64_i8 v[116:119], v[144:147], v[172:175], v[116:119]
	v_mfma_i32_16x16x64_i8 v[108:111], v[136:139], v[180:183], v[108:111]
	v_mfma_i32_16x16x64_i8 v[100:103], v[144:147], v[180:183], v[100:103]
	v_mfma_i32_16x16x64_i8 v[92:95], v[136:139], v[188:191], v[92:95]
	v_mfma_i32_16x16x64_i8 v[84:87], v[144:147], v[188:191], v[84:87]
	v_mfma_i32_16x16x64_i8 v[76:79], v[136:139], v[196:199], v[76:79]
	v_mfma_i32_16x16x64_i8 v[68:71], v[144:147], v[196:199], v[68:71]
	v_mfma_i32_16x16x64_i8 v[124:127], v[140:143], v[176:179], v[124:127]
	v_mfma_i32_16x16x64_i8 v[116:119], v[152:155], v[176:179], v[116:119]
	v_mfma_i32_16x16x64_i8 v[108:111], v[140:143], v[184:187], v[108:111]
	v_mfma_i32_16x16x64_i8 v[100:103], v[152:155], v[184:187], v[100:103]
	v_mfma_i32_16x16x64_i8 v[92:95], v[140:143], v[192:195], v[92:95]
	v_mfma_i32_16x16x64_i8 v[84:87], v[152:155], v[192:195], v[84:87]
	v_mfma_i32_16x16x64_i8 v[76:79], v[140:143], v[200:203], v[76:79]
	v_mfma_i32_16x16x64_i8 v[68:71], v[152:155], v[200:203], v[68:71]
	s_setprio 0
	s_setprio 1
	v_mfma_i32_16x16x64_i8 v[120:123], v[156:159], v[172:175], v[120:123]
	v_mfma_i32_16x16x64_i8 v[112:115], v[164:167], v[172:175], v[112:115]
	v_mfma_i32_16x16x64_i8 v[104:107], v[156:159], v[180:183], v[104:107]
	v_mfma_i32_16x16x64_i8 v[96:99], v[164:167], v[180:183], v[96:99]
	v_mfma_i32_16x16x64_i8 v[88:91], v[156:159], v[188:191], v[88:91]
	v_mfma_i32_16x16x64_i8 v[80:83], v[164:167], v[188:191], v[80:83]
	v_mfma_i32_16x16x64_i8 v[72:75], v[156:159], v[196:199], v[72:75]
	v_mfma_i32_16x16x64_i8 v[64:67], v[164:167], v[196:199], v[64:67]
	v_mfma_i32_16x16x64_i8 v[120:123], v[160:163], v[176:179], v[120:123]
	v_mfma_i32_16x16x64_i8 v[112:115], v[168:171], v[176:179], v[112:115]
	v_mfma_i32_16x16x64_i8 v[104:107], v[160:163], v[184:187], v[104:107]
	v_mfma_i32_16x16x64_i8 v[96:99], v[168:171], v[184:187], v[96:99]
	v_mfma_i32_16x16x64_i8 v[88:91], v[160:163], v[192:195], v[88:91]
	v_mfma_i32_16x16x64_i8 v[80:83], v[168:171], v[192:195], v[80:83]
	v_mfma_i32_16x16x64_i8 v[72:75], v[160:163], v[200:203], v[72:75]
	v_mfma_i32_16x16x64_i8 v[64:67], v[168:171], v[200:203], v[64:67]
	s_setprio 0
	s_barrier
	v_lshl_add_u64 v[204:205], s[96:97], 0, v[128:129]
	s_add_i32 s96, s87, s57
	s_mov_b32 m0, s96
	ds_read_b128 v[172:175], v151 offset:16384
	ds_read_b128 v[176:179], v151 offset:17408
	ds_read_b128 v[180:183], v151 offset:18432
	ds_read_b128 v[184:187], v151 offset:19456
	ds_read_b128 v[188:191], v151 offset:20480
	ds_read_b128 v[192:195], v151 offset:21504
	ds_read_b128 v[196:199], v151 offset:22528
	ds_read_b128 v[200:203], v151 offset:23552
	global_load_lds_dwordx4 v[204:205], off
	v_lshl_add_u64 v[206:207], v[204:205], 0, s[0:1]
	s_add_i32 m0, s96, 0x2000
	s_add_i32 s96, s88, s57
	global_load_lds_dwordx4 v[206:207], off
	v_lshl_add_u64 v[206:207], v[204:205], 0, s[2:3]
	s_mov_b32 m0, s96
	s_nop 0
	global_load_lds_dwordx4 v[206:207], off
	v_lshl_add_u64 v[206:207], v[204:205], 0, s[4:5]
	s_add_i32 m0, s96, 0x2000
	s_nop 0
	global_load_lds_dwordx4 v[206:207], off
	v_lshl_add_u64 v[206:207], s[94:95], 0, v[130:131]
	s_mov_b32 m0, s69
	v_lshl_add_u64 v[208:209], v[206:207], 0, s[0:1]
	global_load_lds_dwordx4 v[206:207], off
	s_mov_b32 m0, s78
	s_nop 0
	global_load_lds_dwordx4 v[208:209], off
	s_waitcnt vmcnt(8)
	s_waitcnt lgkmcnt(0)
	s_setprio 1
	s_barrier
; #define PG8_STAGE(bufoff, gbase, voff) do { _Pragma("unroll") for (int _i = 0; _i < 2; ++_i) \
;         __builtin_amdgcn_global_load_lds((const unsigned*)((const char*)(gbase) + (BYTE_ELEMS ? _i * r##voff + (v##voff)[0] : (v##voff)[_i])), (PG8_LAS unsigned*)(lds + (bufoff) + ldsw + _i * 8192), 16, 0, 0); } while (0)
; #define PG8_LDA(dst, b, h) do { _Pragma("unroll") for (int m = 0; m < 4; ++m) _Pragma("unroll") for (int k = 0; k < 2; ++k) dst[m][k] = *(const PG8_LAS bf16x8*)(lds + PG8_SA(b, h) + aoff + m * 2048 + k * 1024); } while (0)
; #define PG8_LDB(dst, b, h) do { _Pragma("unroll") for (int n = 0; n < 2; ++n) _Pragma("unroll") for (int k = 0; k < 2; ++k) dst[n][k] = *(const PG8_LAS bf16x8*)(lds + PG8_SB(b, h) + boff + n * 2048 + k * 1024); } while (0)
; #define PG8_WAIT_V(n) asm volatile("s_waitcnt vmcnt(" #n ")" ::: "memory")
; #define PG8_WAIT_L(n) asm volatile("s_waitcnt lgkmcnt(" #n ")" ::: "memory")
; #define PG8_BAR __builtin_amdgcn_s_barrier()
; #define PG8_SCHED __builtin_amdgcn_sched_barrier(0)
;     ...
;             PG8_WAIT_V(8); PG8_WAIT_L(0); PG8_BAR; PG8_MMA(1, 0, At, B0); PG8_MMA(1, 1, At, B1); PG8_BAR; PG8_SCHED;
;             PG8_LDB(B0, 1, 0); PG8_LDB(B1, 1, 1); PG8_SCHED; PG8_LDA(At, 1, 0); PG8_STAGE(PG8_SA(0, 1), a2 + hstepA, offA);
;             PG8_WAIT_V(8); PG8_WAIT_L(0); PG8_BAR; PG8_MMA(0, 0, At, B0); PG8_MMA(0, 1, At, B1); PG8_BAR; PG8_SCHED;
	v_mfma_i32_16x16x64_i8 v[60:63], v[136:139], v[172:175], v[60:63]
	v_mfma_i32_16x16x64_i8 v[52:55], v[144:147], v[172:175], v[52:55]
	v_mfma_i32_16x16x64_i8 v[44:47], v[136:139], v[180:183], v[44:47]
	v_mfma_i32_16x16x64_i8 v[36:39], v[144:147], v[180:183], v[36:39]
	v_mfma_i32_16x16x64_i8 v[28:31], v[136:139], v[188:191], v[28:31]
	v_mfma_i32_16x16x64_i8 v[20:23], v[144:147], v[188:191], v[20:23]
	v_mfma_i32_16x16x64_i8 v[12:15], v[136:139], v[196:199], v[12:15]
	v_mfma_i32_16x16x64_i8 v[4:7], v[144:147], v[196:199], v[4:7]
	v_mfma_i32_16x16x64_i8 v[60:63], v[140:143], v[176:179], v[60:63]
	v_mfma_i32_16x16x64_i8 v[52:55], v[152:155], v[176:179], v[52:55]
	v_mfma_i32_16x16x64_i8 v[44:47], v[140:143], v[184:187], v[44:47]
	v_mfma_i32_16x16x64_i8 v[36:39], v[152:155], v[184:187], v[36:39]
	v_mfma_i32_16x16x64_i8 v[28:31], v[140:143], v[192:195], v[28:31]
	v_mfma_i32_16x16x64_i8 v[20:23], v[152:155], v[192:195], v[20:23]
	v_mfma_i32_16x16x64_i8 v[12:15], v[140:143], v[200:203], v[12:15]
	v_mfma_i32_16x16x64_i8 v[4:7], v[152:155], v[200:203], v[4:7]
	s_setprio 0
	s_setprio 1
	v_mfma_i32_16x16x64_i8 v[56:59], v[156:159], v[172:175], v[56:59]
	v_mfma_i32_16x16x64_i8 v[48:51], v[164:167], v[172:175], v[48:51]
	v_mfma_i32_16x16x64_i8 v[40:43], v[156:159], v[180:183], v[40:43]
	v_mfma_i32_16x16x64_i8 v[32:35], v[164:167], v[180:183], v[32:35]
	v_mfma_i32_16x16x64_i8 v[24:27], v[156:159], v[188:191], v[24:27]
	v_mfma_i32_16x16x64_i8 v[16:19], v[164:167], v[188:191], v[16:19]
	v_mfma_i32_16x16x64_i8 v[8:11], v[156:159], v[196:199], v[8:11]
	v_mfma_i32_16x16x64_i8 v[0:3], v[164:167], v[196:199], v[0:3]
	v_mfma_i32_16x16x64_i8 v[56:59], v[160:163], v[176:179], v[56:59]
	v_mfma_i32_16x16x64_i8 v[48:51], v[168:171], v[176:179], v[48:51]
	v_mfma_i32_16x16x64_i8 v[40:43], v[160:163], v[184:187], v[40:43]
	v_mfma_i32_16x16x64_i8 v[32:35], v[168:171], v[184:187], v[32:35]
	v_mfma_i32_16x16x64_i8 v[24:27], v[160:163], v[192:195], v[24:27]
	v_mfma_i32_16x16x64_i8 v[16:19], v[168:171], v[192:195], v[16:19]
	v_mfma_i32_16x16x64_i8 v[8:11], v[160:163], v[200:203], v[8:11]
	v_mfma_i32_16x16x64_i8 v[0:3], v[168:171], v[200:203], v[0:3]
	s_setprio 0
	s_barrier
	s_add_i32 s94, 0, 0x18000
	s_add_i32 s95, 0, 0x1c000
	v_add_u32_e32 v152, s94, v148
	v_add_u32_e32 v168, s95, v148
	ds_read_b128 v[136:139], v152
	ds_read_b128 v[140:143], v152 offset:1024
	ds_read_b128 v[144:147], v152 offset:2048
	ds_read_b128 v[152:155], v152 offset:3072
	ds_read_b128 v[156:159], v168
	ds_read_b128 v[160:163], v168 offset:1024
	ds_read_b128 v[164:167], v168 offset:2048
	ds_read_b128 v[168:171], v168 offset:3072
	s_mov_b32 m0, s79
	v_lshl_add_u64 v[208:209], v[206:207], 0, s[2:3]
	ds_read_b128 v[172:175], v151 offset:32768
	ds_read_b128 v[176:179], v151 offset:33792
	ds_read_b128 v[180:183], v151 offset:34816
	ds_read_b128 v[184:187], v151 offset:35840
	ds_read_b128 v[188:191], v151 offset:36864
	ds_read_b128 v[192:195], v151 offset:37888
	ds_read_b128 v[196:199], v151 offset:38912
	ds_read_b128 v[200:203], v151 offset:39936
	global_load_lds_dwordx4 v[208:209], off
	v_lshl_add_u64 v[208:209], v[206:207], 0, s[4:5]
	s_mov_b32 m0, s80
	s_nop 0
	global_load_lds_dwordx4 v[208:209], off
	s_waitcnt vmcnt(8)
	s_waitcnt lgkmcnt(0)
	s_setprio 1
	s_barrier
	v_mfma_i32_16x16x64_i8 v[124:127], v[136:139], v[172:175], v[124:127]
	v_mfma_i32_16x16x64_i8 v[116:119], v[144:147], v[172:175], v[116:119]
	v_mfma_i32_16x16x64_i8 v[108:111], v[136:139], v[180:183], v[108:111]
	v_mfma_i32_16x16x64_i8 v[100:103], v[144:147], v[180:183], v[100:103]
	v_mfma_i32_16x16x64_i8 v[92:95], v[136:139], v[188:191], v[92:95]
	v_mfma_i32_16x16x64_i8 v[84:87], v[144:147], v[188:191], v[84:87]
	v_mfma_i32_16x16x64_i8 v[76:79], v[136:139], v[196:199], v[76:79]
	v_mfma_i32_16x16x64_i8 v[68:71], v[144:147], v[196:199], v[68:71]
	v_mfma_i32_16x16x64_i8 v[124:127], v[140:143], v[176:179], v[124:127]
	v_mfma_i32_16x16x64_i8 v[116:119], v[152:155], v[176:179], v[116:119]
	v_mfma_i32_16x16x64_i8 v[108:111], v[140:143], v[184:187], v[108:111]
	v_mfma_i32_16x16x64_i8 v[100:103], v[152:155], v[184:187], v[100:103]
	v_mfma_i32_16x16x64_i8 v[92:95], v[140:143], v[192:195], v[92:95]
	v_mfma_i32_16x16x64_i8 v[84:87], v[152:155], v[192:195], v[84:87]
	v_mfma_i32_16x16x64_i8 v[76:79], v[140:143], v[200:203], v[76:79]
	v_mfma_i32_16x16x64_i8 v[68:71], v[152:155], v[200:203], v[68:71]
	s_setprio 0
	s_setprio 1
	v_mfma_i32_16x16x64_i8 v[120:123], v[156:159], v[172:175], v[120:123]
	v_mfma_i32_16x16x64_i8 v[112:115], v[164:167], v[172:175], v[112:115]
	v_mfma_i32_16x16x64_i8 v[104:107], v[156:159], v[180:183], v[104:107]
	v_mfma_i32_16x16x64_i8 v[96:99], v[164:167], v[180:183], v[96:99]
	v_mfma_i32_16x16x64_i8 v[88:91], v[156:159], v[188:191], v[88:91]
	v_mfma_i32_16x16x64_i8 v[80:83], v[164:167], v[188:191], v[80:83]
	v_mfma_i32_16x16x64_i8 v[72:75], v[156:159], v[196:199], v[72:75]
	v_mfma_i32_16x16x64_i8 v[64:67], v[164:167], v[196:199], v[64:67]
	v_mfma_i32_16x16x64_i8 v[120:123], v[160:163], v[176:179], v[120:123]
	v_mfma_i32_16x16x64_i8 v[112:115], v[168:171], v[176:179], v[112:115]
	v_mfma_i32_16x16x64_i8 v[104:107], v[160:163], v[184:187], v[104:107]
	v_mfma_i32_16x16x64_i8 v[96:99], v[168:171], v[184:187], v[96:99]
	v_mfma_i32_16x16x64_i8 v[88:91], v[160:163], v[192:195], v[88:91]
	v_mfma_i32_16x16x64_i8 v[80:83], v[168:171], v[192:195], v[80:83]
	v_mfma_i32_16x16x64_i8 v[72:75], v[160:163], v[200:203], v[72:75]
	v_mfma_i32_16x16x64_i8 v[64:67], v[168:171], v[200:203], v[64:67]
	s_setprio 0
	s_barrier
; #define PG8_STAGE(bufoff, gbase, voff) do { _Pragma("unroll") for (int _i = 0; _i < 2; ++_i) \
;         __builtin_amdgcn_global_load_lds((const unsigned*)((const char*)(gbase) + (BYTE_ELEMS ? _i * r##voff + (v##voff)[0] : (v##voff)[_i])), (PG8_LAS unsigned*)(lds + (bufoff) + ldsw + _i * 8192), 16, 0, 0); } while (0)
; #define PG8_LDA(dst, b, h) do { _Pragma("unroll") for (int m = 0; m < 4; ++m) _Pragma("unroll") for (int k = 0; k < 2; ++k) dst[m][k] = *(const PG8_LAS bf16x8*)(lds + PG8_SA(b, h) + aoff + m * 2048 + k * 1024); } while (0)
; #define PG8_WAIT_V(n) asm volatile("s_waitcnt vmcnt(" #n ")" ::: "memory")
; #define PG8_WAIT_L(n) asm volatile("s_waitcnt lgkmcnt(" #n ")" ::: "memory")
; #define PG8_BAR __builtin_amdgcn_s_barrier()
; #define PG8_SCHED __builtin_amdgcn_sched_barrier(0)
;     ...
;             PG8_LDA(At, 1, 1); PG8_STAGE(PG8_SB(1, 0), b3, offB); PG8_STAGE(PG8_SB(1, 1), b3 + hstepB, offB); PG8_STAGE(PG8_SA(1, 0), a3, offA);
;             PG8_WAIT_V(8); PG8_WAIT_L(0); PG8_BAR; PG8_MMA(1, 0, At, B0); PG8_MMA(1, 1, At, B1); PG8_BAR; PG8_SCHED;
	s_add_i32 s94, s94, s57
	v_lshl_add_u64 v[208:209], v[204:205], 0, s[38:39]
	s_mov_b32 m0, s94
	ds_read_b128 v[172:175], v151 offset:49152
	ds_read_b128 v[176:179], v151 offset:50176
	ds_read_b128 v[180:183], v151 offset:51200
	ds_read_b128 v[184:187], v151 offset:52224
	ds_read_b128 v[188:191], v151 offset:53248
	ds_read_b128 v[192:195], v151 offset:54272
	ds_read_b128 v[196:199], v151 offset:55296
	ds_read_b128 v[200:203], v151 offset:56320
	global_load_lds_dwordx4 v[208:209], off
	v_lshl_add_u64 v[208:209], v[204:205], 0, s[40:41]
	s_add_i32 m0, s94, 0x2000
	s_add_i32 s94, s95, s57
	global_load_lds_dwordx4 v[208:209], off
	v_lshl_add_u64 v[208:209], v[204:205], 0, s[42:43]
	s_mov_b32 m0, s94
	v_lshl_add_u64 v[204:205], v[204:205], 0, s[46:47]
	global_load_lds_dwordx4 v[208:209], off
	s_add_i32 m0, s94, 0x2000
	s_nop 0
	global_load_lds_dwordx4 v[204:205], off
	v_lshl_add_u64 v[204:205], v[206:207], 0, s[38:39]
	s_mov_b32 m0, s82
	s_nop 0
	global_load_lds_dwordx4 v[204:205], off
	v_lshl_add_u64 v[204:205], v[206:207], 0, s[40:41]
	s_mov_b32 m0, s83
	s_nop 0
	global_load_lds_dwordx4 v[204:205], off
	s_waitcnt vmcnt(8)
	s_waitcnt lgkmcnt(0)
	s_setprio 1
	s_barrier
	v_mfma_i32_16x16x64_i8 v[60:63], v[136:139], v[172:175], v[60:63]
	v_mfma_i32_16x16x64_i8 v[52:55], v[144:147], v[172:175], v[52:55]
	v_mfma_i32_16x16x64_i8 v[44:47], v[136:139], v[180:183], v[44:47]
	v_mfma_i32_16x16x64_i8 v[36:39], v[144:147], v[180:183], v[36:39]
	v_mfma_i32_16x16x64_i8 v[28:31], v[136:139], v[188:191], v[28:31]
	v_mfma_i32_16x16x64_i8 v[20:23], v[144:147], v[188:191], v[20:23]
	v_mfma_i32_16x16x64_i8 v[12:15], v[136:139], v[196:199], v[12:15]
	v_mfma_i32_16x16x64_i8 v[4:7], v[144:147], v[196:199], v[4:7]
	v_mfma_i32_16x16x64_i8 v[60:63], v[140:143], v[176:179], v[60:63]
	v_mfma_i32_16x16x64_i8 v[52:55], v[152:155], v[176:179], v[52:55]
	v_mfma_i32_16x16x64_i8 v[44:47], v[140:143], v[184:187], v[44:47]
	v_mfma_i32_16x16x64_i8 v[36:39], v[152:155], v[184:187], v[36:39]
	v_mfma_i32_16x16x64_i8 v[28:31], v[140:143], v[192:195], v[28:31]
	v_mfma_i32_16x16x64_i8 v[20:23], v[152:155], v[192:195], v[20:23]
	v_mfma_i32_16x16x64_i8 v[12:15], v[140:143], v[200:203], v[12:15]
	v_mfma_i32_16x16x64_i8 v[4:7], v[152:155], v[200:203], v[4:7]
	s_setprio 0
	s_setprio 1
	v_mfma_i32_16x16x64_i8 v[56:59], v[156:159], v[172:175], v[56:59]
	v_mfma_i32_16x16x64_i8 v[48:51], v[164:167], v[172:175], v[48:51]
	v_mfma_i32_16x16x64_i8 v[40:43], v[156:159], v[180:183], v[40:43]
	v_mfma_i32_16x16x64_i8 v[32:35], v[164:167], v[180:183], v[32:35]
	v_mfma_i32_16x16x64_i8 v[24:27], v[156:159], v[188:191], v[24:27]
	v_mfma_i32_16x16x64_i8 v[16:19], v[164:167], v[188:191], v[16:19]
	v_mfma_i32_16x16x64_i8 v[8:11], v[156:159], v[196:199], v[8:11]
	v_mfma_i32_16x16x64_i8 v[0:3], v[164:167], v[196:199], v[0:3]
	v_mfma_i32_16x16x64_i8 v[56:59], v[160:163], v[176:179], v[56:59]
	v_mfma_i32_16x16x64_i8 v[48:51], v[168:171], v[176:179], v[48:51]
	v_mfma_i32_16x16x64_i8 v[40:43], v[160:163], v[184:187], v[40:43]
	v_mfma_i32_16x16x64_i8 v[32:35], v[168:171], v[184:187], v[32:35]
	v_mfma_i32_16x16x64_i8 v[24:27], v[160:163], v[192:195], v[24:27]
	v_mfma_i32_16x16x64_i8 v[16:19], v[168:171], v[192:195], v[16:19]
	v_mfma_i32_16x16x64_i8 v[8:11], v[160:163], v[200:203], v[8:11]
	v_mfma_i32_16x16x64_i8 v[0:3], v[168:171], v[200:203], v[0:3]
	s_setprio 0
	s_barrier
	s_add_i32 s93, s93, 2
	s_add_u32 s70, s70, 0x100
	s_addc_u32 s71, s71, 0
	s_add_u32 s72, s72, 0x100
	s_addc_u32 s73, s73, 0
	s_cmp_gt_u32 s93, 13
	s_cbranch_scc0 .LBB0_275
	s_and_b64 vcc, exec, s[50:51]
	s_cbranch_vccz .LBB0_278
	s_barrier

; #define PG8_STAGE(bufoff, gbase, voff) do { _Pragma("unroll") for (int _i = 0; _i < 2; ++_i) \
;         __builtin_amdgcn_global_load_lds((const unsigned*)((const char*)(gbase) + (BYTE_ELEMS ? _i * r##voff + (v##voff)[0] : (v##voff)[_i])), (PG8_LAS unsigned*)(lds + (bufoff) + ldsw + _i * 8192), 16, 0, 0); } while (0)
; #define PG8_LDA(dst, b, h) do { _Pragma("unroll") for (int m = 0; m < 4; ++m) _Pragma("unroll") for (int k = 0; k < 2; ++k) dst[m][k] = *(const PG8_LAS bf16x8*)(lds + PG8_SA(b, h) + aoff + m * 2048 + k * 1024); } while (0)
; #define PG8_LDB(dst, b, h) do { _Pragma("unroll") for (int n = 0; n < 2; ++n) _Pragma("unroll") for (int k = 0; k < 2; ++k) dst[n][k] = *(const PG8_LAS bf16x8*)(lds + PG8_SB(b, h) + boff + n * 2048 + k * 1024); } while (0)
; #define PG8_WAIT_V(n) asm volatile("s_waitcnt vmcnt(" #n ")" ::: "memory")
; #define PG8_WAIT_L(n) asm volatile("s_waitcnt lgkmcnt(" #n ")" ::: "memory")
; #define PG8_BAR __builtin_amdgcn_s_barrier()
; #define PG8_SCHED __builtin_amdgcn_sched_barrier(0)
;     ...
;             PG8_LDB(B0, 0, 0); PG8_LDB(B1, 0, 1); PG8_SCHED; PG8_LDA(At, 0, 0); PG8_STAGE(PG8_SA(1, 1), a1 + hstepA, offA);
;             PG8_WAIT_V(8); PG8_WAIT_L(0); PG8_BAR; PG8_MMA(0, 0, At, B0); PG8_MMA(0, 1, At, B1); PG8_BAR; PG8_SCHED;
;             PG8_LDA(At, 0, 1); PG8_STAGE(PG8_SB(0, 0), b2, offB); PG8_STAGE(PG8_SB(0, 1), b2 + hstepB, offB); PG8_STAGE(PG8_SA(0, 0), a2, offA);
;             PG8_WAIT_V(8); PG8_WAIT_L(0); PG8_BAR; PG8_MMA(1, 0, At, B0); PG8_MMA(1, 1, At, B1); PG8_BAR; PG8_SCHED;
.LBB0_350:
	ds_read_b128 v[142:145], v147
	ds_read_b128 v[150:153], v147 offset:1024
	ds_read_b128 v[154:157], v147 offset:2048
	ds_read_b128 v[158:161], v147 offset:3072
	ds_read_b128 v[162:165], v148
	ds_read_b128 v[166:169], v148 offset:1024
	ds_read_b128 v[170:173], v148 offset:2048
	ds_read_b128 v[174:177], v148 offset:3072
	s_add_u32 s40, s36, 0xffea0080
	s_addc_u32 s41, s37, -1
	s_cmpk_eq_i32 s72, 0x54
	s_cselect_b32 s43, s21, s41
	s_cselect_b32 s42, s20, s40
	s_cselect_b32 s41, s23, s71
	s_cselect_b32 s40, s22, s70
	v_lshl_add_u64 v[210:211], s[36:37], 0, v[136:137]
	s_add_i32 m0, s47, 0xc000
	ds_read_b128 v[178:181], v149
	ds_read_b128 v[182:185], v149 offset:1024
	ds_read_b128 v[186:189], v149 offset:2048
	ds_read_b128 v[190:193], v149 offset:3072
	ds_read_b128 v[194:197], v149 offset:4096
	ds_read_b128 v[198:201], v149 offset:5120
	ds_read_b128 v[202:205], v149 offset:6144
	ds_read_b128 v[206:209], v149 offset:7168
	global_load_lds_dwordx4 v[210:211], off
	v_lshl_add_u64 v[210:211], s[36:37], 0, v[138:139]
	s_add_i32 m0, s47, 0xe000
	s_nop 0
	global_load_lds_dwordx4 v[210:211], off
	s_waitcnt vmcnt(8)
	s_waitcnt lgkmcnt(0)
	s_setprio 1
	s_barrier
	v_mfma_f32_16x16x32_bf16 v[124:127], v[142:145], v[178:181], v[124:127]
	v_mfma_f32_16x16x32_bf16 v[120:123], v[154:157], v[178:181], v[120:123]
	v_mfma_f32_16x16x32_bf16 v[108:111], v[142:145], v[186:189], v[108:111]
	v_mfma_f32_16x16x32_bf16 v[104:107], v[154:157], v[186:189], v[104:107]
	v_mfma_f32_16x16x32_bf16 v[92:95], v[142:145], v[194:197], v[92:95]
	v_mfma_f32_16x16x32_bf16 v[88:91], v[154:157], v[194:197], v[88:91]
	v_mfma_f32_16x16x32_bf16 v[76:79], v[142:145], v[202:205], v[76:79]
	v_mfma_f32_16x16x32_bf16 v[72:75], v[154:157], v[202:205], v[72:75]
	v_mfma_f32_16x16x32_bf16 v[124:127], v[150:153], v[182:185], v[124:127]
	v_mfma_f32_16x16x32_bf16 v[120:123], v[158:161], v[182:185], v[120:123]
	v_mfma_f32_16x16x32_bf16 v[108:111], v[150:153], v[190:193], v[108:111]
	v_mfma_f32_16x16x32_bf16 v[104:107], v[158:161], v[190:193], v[104:107]
	v_mfma_f32_16x16x32_bf16 v[92:95], v[150:153], v[198:201], v[92:95]
	v_mfma_f32_16x16x32_bf16 v[88:91], v[158:161], v[198:201], v[88:91]
	v_mfma_f32_16x16x32_bf16 v[76:79], v[150:153], v[206:209], v[76:79]
	v_mfma_f32_16x16x32_bf16 v[72:75], v[158:161], v[206:209], v[72:75]
	s_setprio 0
	s_setprio 1
	v_mfma_f32_16x16x32_bf16 v[116:119], v[162:165], v[178:181], v[116:119]
	v_mfma_f32_16x16x32_bf16 v[112:115], v[170:173], v[178:181], v[112:115]
	v_mfma_f32_16x16x32_bf16 v[100:103], v[162:165], v[186:189], v[100:103]
	v_mfma_f32_16x16x32_bf16 v[96:99], v[170:173], v[186:189], v[96:99]
	v_mfma_f32_16x16x32_bf16 v[84:87], v[162:165], v[194:197], v[84:87]
	v_mfma_f32_16x16x32_bf16 v[80:83], v[170:173], v[194:197], v[80:83]
	v_mfma_f32_16x16x32_bf16 v[68:71], v[162:165], v[202:205], v[68:71]
	v_mfma_f32_16x16x32_bf16 v[64:67], v[170:173], v[202:205], v[64:67]
	v_mfma_f32_16x16x32_bf16 v[116:119], v[166:169], v[182:185], v[116:119]
	v_mfma_f32_16x16x32_bf16 v[112:115], v[174:177], v[182:185], v[112:115]
	v_mfma_f32_16x16x32_bf16 v[100:103], v[166:169], v[190:193], v[100:103]
	v_mfma_f32_16x16x32_bf16 v[96:99], v[174:177], v[190:193], v[96:99]
	v_mfma_f32_16x16x32_bf16 v[84:87], v[166:169], v[198:201], v[84:87]
	v_mfma_f32_16x16x32_bf16 v[80:83], v[174:177], v[198:201], v[80:83]
	v_mfma_f32_16x16x32_bf16 v[68:71], v[166:169], v[206:209], v[68:71]
	v_mfma_f32_16x16x32_bf16 v[64:67], v[174:177], v[206:209], v[64:67]
	s_setprio 0
	s_barrier
	s_add_i32 s73, s64, s46
	v_lshl_add_u64 v[210:211], s[40:41], 0, v[130:131]
	s_mov_b32 m0, s73
	ds_read_b128 v[178:181], v149 offset:16384
	ds_read_b128 v[182:185], v149 offset:17408
	ds_read_b128 v[186:189], v149 offset:18432
	ds_read_b128 v[190:193], v149 offset:19456
	ds_read_b128 v[194:197], v149 offset:20480
	ds_read_b128 v[198:201], v149 offset:21504
	ds_read_b128 v[202:205], v149 offset:22528
	ds_read_b128 v[206:209], v149 offset:23552
	global_load_lds_dwordx4 v[210:211], off
	s_add_i32 m0, s73, 0x2000
	s_add_u32 s76, s40, 0x160000
	v_lshl_add_u64 v[212:213], s[40:41], 0, v[134:135]
	s_addc_u32 s77, s41, 0
	s_add_i32 s73, s65, s46
	global_load_lds_dwordx4 v[212:213], off
	v_lshl_add_u64 v[214:215], s[76:77], 0, v[130:131]
	s_mov_b32 m0, s73
	v_lshl_add_u64 v[216:217], s[42:43], 0, v[132:133]
	global_load_lds_dwordx4 v[214:215], off
	v_lshl_add_u64 v[214:215], s[76:77], 0, v[134:135]
	s_add_i32 m0, s73, 0x2000
	s_nop 0
	global_load_lds_dwordx4 v[214:215], off
	v_lshl_add_u64 v[214:215], s[42:43], 0, v[128:129]
	s_mov_b32 m0, s47
	s_nop 0
	global_load_lds_dwordx4 v[214:215], off
	s_mov_b32 m0, s50
	s_nop 0
	global_load_lds_dwordx4 v[216:217], off
	s_waitcnt vmcnt(8)
	s_waitcnt lgkmcnt(0)
	s_setprio 1
	s_barrier
; #define PG8_STAGE(bufoff, gbase, voff) do { _Pragma("unroll") for (int _i = 0; _i < 2; ++_i) \
;         __builtin_amdgcn_global_load_lds((const unsigned*)((const char*)(gbase) + (BYTE_ELEMS ? _i * r##voff + (v##voff)[0] : (v##voff)[_i])), (PG8_LAS unsigned*)(lds + (bufoff) + ldsw + _i * 8192), 16, 0, 0); } while (0)
; #define PG8_LDA(dst, b, h) do { _Pragma("unroll") for (int m = 0; m < 4; ++m) _Pragma("unroll") for (int k = 0; k < 2; ++k) dst[m][k] = *(const PG8_LAS bf16x8*)(lds + PG8_SA(b, h) + aoff + m * 2048 + k * 1024); } while (0)
; #define PG8_LDB(dst, b, h) do { _Pragma("unroll") for (int n = 0; n < 2; ++n) _Pragma("unroll") for (int k = 0; k < 2; ++k) dst[n][k] = *(const PG8_LAS bf16x8*)(lds + PG8_SB(b, h) + boff + n * 2048 + k * 1024); } while (0)
; #define PG8_WAIT_V(n) asm volatile("s_waitcnt vmcnt(" #n ")" ::: "memory")
; #define PG8_WAIT_L(n) asm volatile("s_waitcnt lgkmcnt(" #n ")" ::: "memory")
; #define PG8_BAR __builtin_amdgcn_s_barrier()
; #define PG8_SCHED __builtin_amdgcn_sched_barrier(0)
;     ...
;             PG8_WAIT_V(8); PG8_WAIT_L(0); PG8_BAR; PG8_MMA(1, 0, At, B0); PG8_MMA(1, 1, At, B1); PG8_BAR; PG8_SCHED;
;             PG8_LDB(B0, 1, 0); PG8_LDB(B1, 1, 1); PG8_SCHED; PG8_LDA(At, 1, 0); PG8_STAGE(PG8_SA(0, 1), a2 + hstepA, offA);
;             PG8_WAIT_V(8); PG8_WAIT_L(0); PG8_BAR; PG8_MMA(0, 0, At, B0); PG8_MMA(0, 1, At, B1); PG8_BAR; PG8_SCHED;
	v_mfma_f32_16x16x32_bf16 v[60:63], v[142:145], v[178:181], v[60:63]
	v_mfma_f32_16x16x32_bf16 v[56:59], v[154:157], v[178:181], v[56:59]
	v_mfma_f32_16x16x32_bf16 v[44:47], v[142:145], v[186:189], v[44:47]
	v_mfma_f32_16x16x32_bf16 v[40:43], v[154:157], v[186:189], v[40:43]
	v_mfma_f32_16x16x32_bf16 v[28:31], v[142:145], v[194:197], v[28:31]
	v_mfma_f32_16x16x32_bf16 v[24:27], v[154:157], v[194:197], v[24:27]
	v_mfma_f32_16x16x32_bf16 v[12:15], v[142:145], v[202:205], v[12:15]
	v_mfma_f32_16x16x32_bf16 v[8:11], v[154:157], v[202:205], v[8:11]
	v_mfma_f32_16x16x32_bf16 v[60:63], v[150:153], v[182:185], v[60:63]
	v_mfma_f32_16x16x32_bf16 v[56:59], v[158:161], v[182:185], v[56:59]
	v_mfma_f32_16x16x32_bf16 v[44:47], v[150:153], v[190:193], v[44:47]
	v_mfma_f32_16x16x32_bf16 v[40:43], v[158:161], v[190:193], v[40:43]
	v_mfma_f32_16x16x32_bf16 v[28:31], v[150:153], v[198:201], v[28:31]
	v_mfma_f32_16x16x32_bf16 v[24:27], v[158:161], v[198:201], v[24:27]
	v_mfma_f32_16x16x32_bf16 v[12:15], v[150:153], v[206:209], v[12:15]
	v_mfma_f32_16x16x32_bf16 v[8:11], v[158:161], v[206:209], v[8:11]
	s_setprio 0
	s_setprio 1
	v_mfma_f32_16x16x32_bf16 v[52:55], v[162:165], v[178:181], v[52:55]
	v_mfma_f32_16x16x32_bf16 v[48:51], v[170:173], v[178:181], v[48:51]
	v_mfma_f32_16x16x32_bf16 v[36:39], v[162:165], v[186:189], v[36:39]
	v_mfma_f32_16x16x32_bf16 v[32:35], v[170:173], v[186:189], v[32:35]
	v_mfma_f32_16x16x32_bf16 v[20:23], v[162:165], v[194:197], v[20:23]
	v_mfma_f32_16x16x32_bf16 v[16:19], v[170:173], v[194:197], v[16:19]
	v_mfma_f32_16x16x32_bf16 v[4:7], v[162:165], v[202:205], v[4:7]
	v_mfma_f32_16x16x32_bf16 v[0:3], v[170:173], v[202:205], v[0:3]
	v_mfma_f32_16x16x32_bf16 v[52:55], v[166:169], v[182:185], v[52:55]
	v_mfma_f32_16x16x32_bf16 v[48:51], v[174:177], v[182:185], v[48:51]
	v_mfma_f32_16x16x32_bf16 v[36:39], v[166:169], v[190:193], v[36:39]
	v_mfma_f32_16x16x32_bf16 v[32:35], v[174:177], v[190:193], v[32:35]
	v_mfma_f32_16x16x32_bf16 v[20:23], v[166:169], v[198:201], v[20:23]
	v_mfma_f32_16x16x32_bf16 v[16:19], v[174:177], v[198:201], v[16:19]
	v_mfma_f32_16x16x32_bf16 v[4:7], v[166:169], v[206:209], v[4:7]
	v_mfma_f32_16x16x32_bf16 v[0:3], v[174:177], v[206:209], v[0:3]
	s_setprio 0
	s_barrier
	s_add_i32 s73, 0, 0x18000
	s_add_i32 s76, 0, 0x1c000
	v_add_u32_e32 v158, s73, v146
	v_add_u32_e32 v174, s76, v146
	ds_read_b128 v[142:145], v158
	ds_read_b128 v[150:153], v158 offset:1024
	ds_read_b128 v[154:157], v158 offset:2048
	ds_read_b128 v[158:161], v158 offset:3072
	ds_read_b128 v[162:165], v174
	ds_read_b128 v[166:169], v174 offset:1024
	ds_read_b128 v[170:173], v174 offset:2048
	ds_read_b128 v[174:177], v174 offset:3072
	s_add_u32 s42, s42, 0x160000
	s_addc_u32 s43, s43, 0
	s_mov_b32 m0, s51
	v_lshl_add_u64 v[218:219], s[42:43], 0, v[128:129]
	ds_read_b128 v[178:181], v149 offset:32768
	ds_read_b128 v[182:185], v149 offset:33792
	ds_read_b128 v[186:189], v149 offset:34816
	ds_read_b128 v[190:193], v149 offset:35840
	ds_read_b128 v[194:197], v149 offset:36864
	ds_read_b128 v[198:201], v149 offset:37888
	ds_read_b128 v[202:205], v149 offset:38912
	ds_read_b128 v[206:209], v149 offset:39936
	global_load_lds_dwordx4 v[218:219], off
	v_lshl_add_u64 v[218:219], s[42:43], 0, v[132:133]
	s_mov_b32 m0, s56
	s_nop 0
	global_load_lds_dwordx4 v[218:219], off
	s_waitcnt vmcnt(8)
	s_waitcnt lgkmcnt(0)
	s_setprio 1
	s_barrier
	v_mfma_f32_16x16x32_bf16 v[124:127], v[142:145], v[178:181], v[124:127]
	v_mfma_f32_16x16x32_bf16 v[120:123], v[154:157], v[178:181], v[120:123]
	v_mfma_f32_16x16x32_bf16 v[108:111], v[142:145], v[186:189], v[108:111]
	v_mfma_f32_16x16x32_bf16 v[104:107], v[154:157], v[186:189], v[104:107]
	v_mfma_f32_16x16x32_bf16 v[92:95], v[142:145], v[194:197], v[92:95]
	v_mfma_f32_16x16x32_bf16 v[88:91], v[154:157], v[194:197], v[88:91]
	v_mfma_f32_16x16x32_bf16 v[76:79], v[142:145], v[202:205], v[76:79]
	v_mfma_f32_16x16x32_bf16 v[72:75], v[154:157], v[202:205], v[72:75]
	v_mfma_f32_16x16x32_bf16 v[124:127], v[150:153], v[182:185], v[124:127]
	v_mfma_f32_16x16x32_bf16 v[120:123], v[158:161], v[182:185], v[120:123]
	v_mfma_f32_16x16x32_bf16 v[108:111], v[150:153], v[190:193], v[108:111]
	v_mfma_f32_16x16x32_bf16 v[104:107], v[158:161], v[190:193], v[104:107]
	v_mfma_f32_16x16x32_bf16 v[92:95], v[150:153], v[198:201], v[92:95]
	v_mfma_f32_16x16x32_bf16 v[88:91], v[158:161], v[198:201], v[88:91]
	v_mfma_f32_16x16x32_bf16 v[76:79], v[150:153], v[206:209], v[76:79]
	v_mfma_f32_16x16x32_bf16 v[72:75], v[158:161], v[206:209], v[72:75]
	s_setprio 0
	s_setprio 1
	v_mfma_f32_16x16x32_bf16 v[116:119], v[162:165], v[178:181], v[116:119]
	v_mfma_f32_16x16x32_bf16 v[112:115], v[170:173], v[178:181], v[112:115]
	v_mfma_f32_16x16x32_bf16 v[100:103], v[162:165], v[186:189], v[100:103]
	v_mfma_f32_16x16x32_bf16 v[96:99], v[170:173], v[186:189], v[96:99]
	v_mfma_f32_16x16x32_bf16 v[84:87], v[162:165], v[194:197], v[84:87]
	v_mfma_f32_16x16x32_bf16 v[80:83], v[170:173], v[194:197], v[80:83]
	v_mfma_f32_16x16x32_bf16 v[68:71], v[162:165], v[202:205], v[68:71]
	v_mfma_f32_16x16x32_bf16 v[64:67], v[170:173], v[202:205], v[64:67]
	v_mfma_f32_16x16x32_bf16 v[116:119], v[166:169], v[182:185], v[116:119]
	v_mfma_f32_16x16x32_bf16 v[112:115], v[174:177], v[182:185], v[112:115]
	v_mfma_f32_16x16x32_bf16 v[100:103], v[166:169], v[190:193], v[100:103]
	v_mfma_f32_16x16x32_bf16 v[96:99], v[174:177], v[190:193], v[96:99]
	v_mfma_f32_16x16x32_bf16 v[84:87], v[166:169], v[198:201], v[84:87]
	v_mfma_f32_16x16x32_bf16 v[80:83], v[174:177], v[198:201], v[80:83]
	v_mfma_f32_16x16x32_bf16 v[68:71], v[166:169], v[206:209], v[68:71]
	v_mfma_f32_16x16x32_bf16 v[64:67], v[174:177], v[206:209], v[64:67]
	s_setprio 0
	s_barrier
; #define PG8_STAGE(bufoff, gbase, voff) do { _Pragma("unroll") for (int _i = 0; _i < 2; ++_i) \
;         __builtin_amdgcn_global_load_lds((const unsigned*)((const char*)(gbase) + (BYTE_ELEMS ? _i * r##voff + (v##voff)[0] : (v##voff)[_i])), (PG8_LAS unsigned*)(lds + (bufoff) + ldsw + _i * 8192), 16, 0, 0); } while (0)
; #define PG8_LDA(dst, b, h) do { _Pragma("unroll") for (int m = 0; m < 4; ++m) _Pragma("unroll") for (int k = 0; k < 2; ++k) dst[m][k] = *(const PG8_LAS bf16x8*)(lds + PG8_SA(b, h) + aoff + m * 2048 + k * 1024); } while (0)
; #define PG8_WAIT_V(n) asm volatile("s_waitcnt vmcnt(" #n ")" ::: "memory")
; #define PG8_WAIT_L(n) asm volatile("s_waitcnt lgkmcnt(" #n ")" ::: "memory")
; #define PG8_BAR __builtin_amdgcn_s_barrier()
; #define PG8_SCHED __builtin_amdgcn_sched_barrier(0)
;     ...
;             PG8_LDA(At, 1, 1); PG8_STAGE(PG8_SB(1, 0), b3, offB); PG8_STAGE(PG8_SB(1, 1), b3 + hstepB, offB); PG8_STAGE(PG8_SA(1, 0), a3, offA);
;             PG8_WAIT_V(8); PG8_WAIT_L(0); PG8_BAR; PG8_MMA(1, 0, At, B0); PG8_MMA(1, 1, At, B1); PG8_BAR; PG8_SCHED;
	s_add_i32 s42, s73, s46
	v_lshl_add_u64 v[210:211], v[210:211], 0, s[4:5]
	s_mov_b32 m0, s42
	ds_read_b128 v[178:181], v149 offset:49152
	ds_read_b128 v[182:185], v149 offset:50176
	ds_read_b128 v[186:189], v149 offset:51200
	ds_read_b128 v[190:193], v149 offset:52224
	ds_read_b128 v[194:197], v149 offset:53248
	ds_read_b128 v[198:201], v149 offset:54272
	ds_read_b128 v[202:205], v149 offset:55296
	ds_read_b128 v[206:209], v149 offset:56320
	global_load_lds_dwordx4 v[210:211], off
	s_add_i32 m0, s42, 0x2000
	s_add_u32 s40, s40, 0x160080
	v_lshl_add_u64 v[210:211], v[212:213], 0, s[4:5]
	s_addc_u32 s41, s41, 0
	s_add_i32 s42, s76, s46
	global_load_lds_dwordx4 v[210:211], off
	v_lshl_add_u64 v[210:211], s[40:41], 0, v[130:131]
	s_mov_b32 m0, s42
	s_nop 0
	global_load_lds_dwordx4 v[210:211], off
	v_lshl_add_u64 v[210:211], s[40:41], 0, v[134:135]
	s_add_i32 m0, s42, 0x2000
	s_nop 0
	global_load_lds_dwordx4 v[210:211], off
	v_lshl_add_u64 v[210:211], v[214:215], 0, s[4:5]
	s_mov_b32 m0, s60
	s_nop 0
	global_load_lds_dwordx4 v[210:211], off
	v_lshl_add_u64 v[210:211], v[216:217], 0, s[4:5]
	s_mov_b32 m0, s61
	s_nop 0
	global_load_lds_dwordx4 v[210:211], off
	s_waitcnt vmcnt(8)
	s_waitcnt lgkmcnt(0)
	s_setprio 1
	s_barrier
	v_mfma_f32_16x16x32_bf16 v[60:63], v[142:145], v[178:181], v[60:63]
	v_mfma_f32_16x16x32_bf16 v[56:59], v[154:157], v[178:181], v[56:59]
	v_mfma_f32_16x16x32_bf16 v[44:47], v[142:145], v[186:189], v[44:47]
	v_mfma_f32_16x16x32_bf16 v[40:43], v[154:157], v[186:189], v[40:43]
	v_mfma_f32_16x16x32_bf16 v[28:31], v[142:145], v[194:197], v[28:31]
	v_mfma_f32_16x16x32_bf16 v[24:27], v[154:157], v[194:197], v[24:27]
	v_mfma_f32_16x16x32_bf16 v[12:15], v[142:145], v[202:205], v[12:15]
	v_mfma_f32_16x16x32_bf16 v[8:11], v[154:157], v[202:205], v[8:11]
	v_mfma_f32_16x16x32_bf16 v[60:63], v[150:153], v[182:185], v[60:63]
	v_mfma_f32_16x16x32_bf16 v[56:59], v[158:161], v[182:185], v[56:59]
	v_mfma_f32_16x16x32_bf16 v[44:47], v[150:153], v[190:193], v[44:47]
	v_mfma_f32_16x16x32_bf16 v[40:43], v[158:161], v[190:193], v[40:43]
	v_mfma_f32_16x16x32_bf16 v[28:31], v[150:153], v[198:201], v[28:31]
	v_mfma_f32_16x16x32_bf16 v[24:27], v[158:161], v[198:201], v[24:27]
	v_mfma_f32_16x16x32_bf16 v[12:15], v[150:153], v[206:209], v[12:15]
	v_mfma_f32_16x16x32_bf16 v[8:11], v[158:161], v[206:209], v[8:11]
	s_setprio 0
	s_setprio 1
	v_mfma_f32_16x16x32_bf16 v[52:55], v[162:165], v[178:181], v[52:55]
	v_mfma_f32_16x16x32_bf16 v[48:51], v[170:173], v[178:181], v[48:51]
	v_mfma_f32_16x16x32_bf16 v[36:39], v[162:165], v[186:189], v[36:39]
	v_mfma_f32_16x16x32_bf16 v[32:35], v[170:173], v[186:189], v[32:35]
	v_mfma_f32_16x16x32_bf16 v[20:23], v[162:165], v[194:197], v[20:23]
	v_mfma_f32_16x16x32_bf16 v[16:19], v[170:173], v[194:197], v[16:19]
	v_mfma_f32_16x16x32_bf16 v[4:7], v[162:165], v[202:205], v[4:7]
	v_mfma_f32_16x16x32_bf16 v[0:3], v[170:173], v[202:205], v[0:3]
	v_mfma_f32_16x16x32_bf16 v[52:55], v[166:169], v[182:185], v[52:55]
	v_mfma_f32_16x16x32_bf16 v[48:51], v[174:177], v[182:185], v[48:51]
	v_mfma_f32_16x16x32_bf16 v[36:39], v[166:169], v[190:193], v[36:39]
	v_mfma_f32_16x16x32_bf16 v[32:35], v[174:177], v[190:193], v[32:35]
	v_mfma_f32_16x16x32_bf16 v[20:23], v[166:169], v[198:201], v[20:23]
	v_mfma_f32_16x16x32_bf16 v[16:19], v[174:177], v[198:201], v[16:19]
	v_mfma_f32_16x16x32_bf16 v[4:7], v[166:169], v[206:209], v[4:7]
	v_mfma_f32_16x16x32_bf16 v[0:3], v[174:177], v[206:209], v[0:3]
	s_setprio 0
	s_barrier
	s_add_i32 s72, s72, 2
	s_add_u32 s36, s36, 0x100
	s_addc_u32 s37, s37, 0
	s_add_u32 s70, s70, 0x100
	s_addc_u32 s71, s71, 0
	s_cmpk_gt_u32 s72, 0x55
	s_cbranch_scc0 .LBB0_350
	s_and_b64 vcc, exec, s[6:7]
	s_cbranch_vccz .LBB0_353
	s_barrier

; #define PG8_STAGE(bufoff, gbase, voff) do { _Pragma("unroll") for (int _i = 0; _i < 2; ++_i) \
;         __builtin_amdgcn_global_load_lds((const unsigned*)((const char*)(gbase) + (BYTE_ELEMS ? _i * r##voff + (v##voff)[0] : (v##voff)[_i])), (PG8_LAS unsigned*)(lds + (bufoff) + ldsw + _i * 8192), 16, 0, 0); } while (0)
; #define PG8_LDA(dst, b, h) do { _Pragma("unroll") for (int m = 0; m < 4; ++m) _Pragma("unroll") for (int k = 0; k < 2; ++k) dst[m][k] = *(const PG8_LAS bf16x8*)(lds + PG8_SA(b, h) + aoff + m * 2048 + k * 1024); } while (0)
; #define PG8_LDB(dst, b, h) do { _Pragma("unroll") for (int n = 0; n < 2; ++n) _Pragma("unroll") for (int k = 0; k < 2; ++k) dst[n][k] = *(const PG8_LAS bf16x8*)(lds + PG8_SB(b, h) + boff + n * 2048 + k * 1024); } while (0)
; #define PG8_WAIT_V(n) asm volatile("s_waitcnt vmcnt(" #n ")" ::: "memory")
; #define PG8_WAIT_L(n) asm volatile("s_waitcnt lgkmcnt(" #n ")" ::: "memory")
; #define PG8_BAR __builtin_amdgcn_s_barrier()
; #define PG8_SCHED __builtin_amdgcn_sched_barrier(0)
;     ...
;             PG8_LDB(B0, 0, 0); PG8_LDB(B1, 0, 1); PG8_SCHED; PG8_LDA(At, 0, 0); PG8_STAGE(PG8_SA(1, 1), a1 + hstepA, offA);
;             PG8_WAIT_V(8); PG8_WAIT_L(0); PG8_BAR; PG8_MMA(0, 0, At, B0); PG8_MMA(0, 1, At, B1); PG8_BAR; PG8_SCHED;
;             PG8_LDA(At, 0, 1); PG8_STAGE(PG8_SB(0, 0), b2, offB); PG8_STAGE(PG8_SB(0, 1), b2 + hstepB, offB); PG8_STAGE(PG8_SA(0, 0), a2, offA);
;             PG8_WAIT_V(8); PG8_WAIT_L(0); PG8_BAR; PG8_MMA(1, 0, At, B0); PG8_MMA(1, 1, At, B1); PG8_BAR; PG8_SCHED;
.LBB0_389:
	ds_read_b128 v[142:145], v147
	ds_read_b128 v[150:153], v147 offset:1024
	ds_read_b128 v[154:157], v147 offset:2048
	ds_read_b128 v[158:161], v147 offset:3072
	ds_read_b128 v[162:165], v148
	ds_read_b128 v[166:169], v148 offset:1024
	ds_read_b128 v[170:173], v148 offset:2048
	ds_read_b128 v[174:177], v148 offset:3072
	s_add_u32 s46, s42, 0xffea0080
	s_addc_u32 s47, s43, -1
	s_cmpk_eq_i32 s78, 0x54
	s_cselect_b32 s51, s37, s47
	s_cselect_b32 s50, s36, s46
	s_cselect_b32 s47, s41, s77
	s_cselect_b32 s46, s40, s76
	v_lshl_add_u64 v[210:211], s[42:43], 0, v[136:137]
	s_add_i32 m0, s57, 0xc000
	ds_read_b128 v[178:181], v149
	ds_read_b128 v[182:185], v149 offset:1024
	ds_read_b128 v[186:189], v149 offset:2048
	ds_read_b128 v[190:193], v149 offset:3072
	ds_read_b128 v[194:197], v149 offset:4096
	ds_read_b128 v[198:201], v149 offset:5120
	ds_read_b128 v[202:205], v149 offset:6144
	ds_read_b128 v[206:209], v149 offset:7168
	global_load_lds_dwordx4 v[210:211], off
	v_lshl_add_u64 v[210:211], s[42:43], 0, v[138:139]
	s_add_i32 m0, s57, 0xe000
	s_nop 0
	global_load_lds_dwordx4 v[210:211], off
	s_waitcnt vmcnt(8)
	s_waitcnt lgkmcnt(0)
	s_setprio 1
	s_barrier
	v_mfma_f32_16x16x32_bf16 v[124:127], v[142:145], v[178:181], v[124:127]
	v_mfma_f32_16x16x32_bf16 v[120:123], v[154:157], v[178:181], v[120:123]
	v_mfma_f32_16x16x32_bf16 v[108:111], v[142:145], v[186:189], v[108:111]
	v_mfma_f32_16x16x32_bf16 v[104:107], v[154:157], v[186:189], v[104:107]
	v_mfma_f32_16x16x32_bf16 v[92:95], v[142:145], v[194:197], v[92:95]
	v_mfma_f32_16x16x32_bf16 v[88:91], v[154:157], v[194:197], v[88:91]
	v_mfma_f32_16x16x32_bf16 v[76:79], v[142:145], v[202:205], v[76:79]
	v_mfma_f32_16x16x32_bf16 v[72:75], v[154:157], v[202:205], v[72:75]
	v_mfma_f32_16x16x32_bf16 v[124:127], v[150:153], v[182:185], v[124:127]
	v_mfma_f32_16x16x32_bf16 v[120:123], v[158:161], v[182:185], v[120:123]
	v_mfma_f32_16x16x32_bf16 v[108:111], v[150:153], v[190:193], v[108:111]
	v_mfma_f32_16x16x32_bf16 v[104:107], v[158:161], v[190:193], v[104:107]
	v_mfma_f32_16x16x32_bf16 v[92:95], v[150:153], v[198:201], v[92:95]
	v_mfma_f32_16x16x32_bf16 v[88:91], v[158:161], v[198:201], v[88:91]
	v_mfma_f32_16x16x32_bf16 v[76:79], v[150:153], v[206:209], v[76:79]
	v_mfma_f32_16x16x32_bf16 v[72:75], v[158:161], v[206:209], v[72:75]
	s_setprio 0
	s_setprio 1
	v_mfma_f32_16x16x32_bf16 v[116:119], v[162:165], v[178:181], v[116:119]
	v_mfma_f32_16x16x32_bf16 v[112:115], v[170:173], v[178:181], v[112:115]
	v_mfma_f32_16x16x32_bf16 v[100:103], v[162:165], v[186:189], v[100:103]
	v_mfma_f32_16x16x32_bf16 v[96:99], v[170:173], v[186:189], v[96:99]
	v_mfma_f32_16x16x32_bf16 v[84:87], v[162:165], v[194:197], v[84:87]
	v_mfma_f32_16x16x32_bf16 v[80:83], v[170:173], v[194:197], v[80:83]
	v_mfma_f32_16x16x32_bf16 v[68:71], v[162:165], v[202:205], v[68:71]
	v_mfma_f32_16x16x32_bf16 v[64:67], v[170:173], v[202:205], v[64:67]
	v_mfma_f32_16x16x32_bf16 v[116:119], v[166:169], v[182:185], v[116:119]
	v_mfma_f32_16x16x32_bf16 v[112:115], v[174:177], v[182:185], v[112:115]
	v_mfma_f32_16x16x32_bf16 v[100:103], v[166:169], v[190:193], v[100:103]
	v_mfma_f32_16x16x32_bf16 v[96:99], v[174:177], v[190:193], v[96:99]
	v_mfma_f32_16x16x32_bf16 v[84:87], v[166:169], v[198:201], v[84:87]
	v_mfma_f32_16x16x32_bf16 v[80:83], v[174:177], v[198:201], v[80:83]
	v_mfma_f32_16x16x32_bf16 v[68:71], v[166:169], v[206:209], v[68:71]
	v_mfma_f32_16x16x32_bf16 v[64:67], v[174:177], v[206:209], v[64:67]
	s_setprio 0
	s_barrier
	s_add_i32 s79, s68, s56
	v_lshl_add_u64 v[210:211], s[46:47], 0, v[130:131]
	s_mov_b32 m0, s79
	ds_read_b128 v[178:181], v149 offset:16384
	ds_read_b128 v[182:185], v149 offset:17408
	ds_read_b128 v[186:189], v149 offset:18432
	ds_read_b128 v[190:193], v149 offset:19456
	ds_read_b128 v[194:197], v149 offset:20480
	ds_read_b128 v[198:201], v149 offset:21504
	ds_read_b128 v[202:205], v149 offset:22528
	ds_read_b128 v[206:209], v149 offset:23552
	global_load_lds_dwordx4 v[210:211], off
	s_add_i32 m0, s79, 0x2000
	s_add_u32 s80, s46, 0x160000
	v_lshl_add_u64 v[212:213], s[46:47], 0, v[134:135]
	s_addc_u32 s81, s47, 0
	s_add_i32 s79, s69, s56
	global_load_lds_dwordx4 v[212:213], off
	v_lshl_add_u64 v[214:215], s[80:81], 0, v[130:131]
	s_mov_b32 m0, s79
	v_lshl_add_u64 v[216:217], s[50:51], 0, v[132:133]
	global_load_lds_dwordx4 v[214:215], off
	v_lshl_add_u64 v[214:215], s[80:81], 0, v[134:135]
	s_add_i32 m0, s79, 0x2000
	s_nop 0
	global_load_lds_dwordx4 v[214:215], off
	v_lshl_add_u64 v[214:215], s[50:51], 0, v[128:129]
	s_mov_b32 m0, s57
	s_nop 0
	global_load_lds_dwordx4 v[214:215], off
	s_mov_b32 m0, s58
	s_nop 0
	global_load_lds_dwordx4 v[216:217], off
	s_waitcnt vmcnt(8)
	s_waitcnt lgkmcnt(0)
	s_setprio 1
	s_barrier
; #define PG8_STAGE(bufoff, gbase, voff) do { _Pragma("unroll") for (int _i = 0; _i < 2; ++_i) \
;         __builtin_amdgcn_global_load_lds((const unsigned*)((const char*)(gbase) + (BYTE_ELEMS ? _i * r##voff + (v##voff)[0] : (v##voff)[_i])), (PG8_LAS unsigned*)(lds + (bufoff) + ldsw + _i * 8192), 16, 0, 0); } while (0)
; #define PG8_LDA(dst, b, h) do { _Pragma("unroll") for (int m = 0; m < 4; ++m) _Pragma("unroll") for (int k = 0; k < 2; ++k) dst[m][k] = *(const PG8_LAS bf16x8*)(lds + PG8_SA(b, h) + aoff + m * 2048 + k * 1024); } while (0)
; #define PG8_LDB(dst, b, h) do { _Pragma("unroll") for (int n = 0; n < 2; ++n) _Pragma("unroll") for (int k = 0; k < 2; ++k) dst[n][k] = *(const PG8_LAS bf16x8*)(lds + PG8_SB(b, h) + boff + n * 2048 + k * 1024); } while (0)
; #define PG8_WAIT_V(n) asm volatile("s_waitcnt vmcnt(" #n ")" ::: "memory")
; #define PG8_WAIT_L(n) asm volatile("s_waitcnt lgkmcnt(" #n ")" ::: "memory")
; #define PG8_BAR __builtin_amdgcn_s_barrier()
; #define PG8_SCHED __builtin_amdgcn_sched_barrier(0)
;     ...
;             PG8_WAIT_V(8); PG8_WAIT_L(0); PG8_BAR; PG8_MMA(1, 0, At, B0); PG8_MMA(1, 1, At, B1); PG8_BAR; PG8_SCHED;
;             PG8_LDB(B0, 1, 0); PG8_LDB(B1, 1, 1); PG8_SCHED; PG8_LDA(At, 1, 0); PG8_STAGE(PG8_SA(0, 1), a2 + hstepA, offA);
;             PG8_WAIT_V(8); PG8_WAIT_L(0); PG8_BAR; PG8_MMA(0, 0, At, B0); PG8_MMA(0, 1, At, B1); PG8_BAR; PG8_SCHED;
	v_mfma_f32_16x16x32_bf16 v[60:63], v[142:145], v[178:181], v[60:63]
	v_mfma_f32_16x16x32_bf16 v[56:59], v[154:157], v[178:181], v[56:59]
	v_mfma_f32_16x16x32_bf16 v[44:47], v[142:145], v[186:189], v[44:47]
	v_mfma_f32_16x16x32_bf16 v[40:43], v[154:157], v[186:189], v[40:43]
	v_mfma_f32_16x16x32_bf16 v[28:31], v[142:145], v[194:197], v[28:31]
	v_mfma_f32_16x16x32_bf16 v[24:27], v[154:157], v[194:197], v[24:27]
	v_mfma_f32_16x16x32_bf16 v[12:15], v[142:145], v[202:205], v[12:15]
	v_mfma_f32_16x16x32_bf16 v[8:11], v[154:157], v[202:205], v[8:11]
	v_mfma_f32_16x16x32_bf16 v[60:63], v[150:153], v[182:185], v[60:63]
	v_mfma_f32_16x16x32_bf16 v[56:59], v[158:161], v[182:185], v[56:59]
	v_mfma_f32_16x16x32_bf16 v[44:47], v[150:153], v[190:193], v[44:47]
	v_mfma_f32_16x16x32_bf16 v[40:43], v[158:161], v[190:193], v[40:43]
	v_mfma_f32_16x16x32_bf16 v[28:31], v[150:153], v[198:201], v[28:31]
	v_mfma_f32_16x16x32_bf16 v[24:27], v[158:161], v[198:201], v[24:27]
	v_mfma_f32_16x16x32_bf16 v[12:15], v[150:153], v[206:209], v[12:15]
	v_mfma_f32_16x16x32_bf16 v[8:11], v[158:161], v[206:209], v[8:11]
	s_setprio 0
	s_setprio 1
	v_mfma_f32_16x16x32_bf16 v[52:55], v[162:165], v[178:181], v[52:55]
	v_mfma_f32_16x16x32_bf16 v[48:51], v[170:173], v[178:181], v[48:51]
	v_mfma_f32_16x16x32_bf16 v[36:39], v[162:165], v[186:189], v[36:39]
	v_mfma_f32_16x16x32_bf16 v[32:35], v[170:173], v[186:189], v[32:35]
	v_mfma_f32_16x16x32_bf16 v[20:23], v[162:165], v[194:197], v[20:23]
	v_mfma_f32_16x16x32_bf16 v[16:19], v[170:173], v[194:197], v[16:19]
	v_mfma_f32_16x16x32_bf16 v[4:7], v[162:165], v[202:205], v[4:7]
	v_mfma_f32_16x16x32_bf16 v[0:3], v[170:173], v[202:205], v[0:3]
	v_mfma_f32_16x16x32_bf16 v[52:55], v[166:169], v[182:185], v[52:55]
	v_mfma_f32_16x16x32_bf16 v[48:51], v[174:177], v[182:185], v[48:51]
	v_mfma_f32_16x16x32_bf16 v[36:39], v[166:169], v[190:193], v[36:39]
	v_mfma_f32_16x16x32_bf16 v[32:35], v[174:177], v[190:193], v[32:35]
	v_mfma_f32_16x16x32_bf16 v[20:23], v[166:169], v[198:201], v[20:23]
	v_mfma_f32_16x16x32_bf16 v[16:19], v[174:177], v[198:201], v[16:19]
	v_mfma_f32_16x16x32_bf16 v[4:7], v[166:169], v[206:209], v[4:7]
	v_mfma_f32_16x16x32_bf16 v[0:3], v[174:177], v[206:209], v[0:3]
	s_setprio 0
	s_barrier
	s_add_i32 s79, 0, 0x18000
	s_add_i32 s80, 0, 0x1c000
	v_add_u32_e32 v158, s79, v146
	v_add_u32_e32 v174, s80, v146
	ds_read_b128 v[142:145], v158
	ds_read_b128 v[150:153], v158 offset:1024
	ds_read_b128 v[154:157], v158 offset:2048
	ds_read_b128 v[158:161], v158 offset:3072
	ds_read_b128 v[162:165], v174
	ds_read_b128 v[166:169], v174 offset:1024
	ds_read_b128 v[170:173], v174 offset:2048
	ds_read_b128 v[174:177], v174 offset:3072
	s_add_u32 s50, s50, 0x160000
	s_addc_u32 s51, s51, 0
	s_mov_b32 m0, s59
	v_lshl_add_u64 v[218:219], s[50:51], 0, v[128:129]
	ds_read_b128 v[178:181], v149 offset:32768
	ds_read_b128 v[182:185], v149 offset:33792
	ds_read_b128 v[186:189], v149 offset:34816
	ds_read_b128 v[190:193], v149 offset:35840
	ds_read_b128 v[194:197], v149 offset:36864
	ds_read_b128 v[198:201], v149 offset:37888
	ds_read_b128 v[202:205], v149 offset:38912
	ds_read_b128 v[206:209], v149 offset:39936
	global_load_lds_dwordx4 v[218:219], off
	v_lshl_add_u64 v[218:219], s[50:51], 0, v[132:133]
	s_mov_b32 m0, s60
	s_nop 0
	global_load_lds_dwordx4 v[218:219], off
	s_waitcnt vmcnt(8)
	s_waitcnt lgkmcnt(0)
	s_setprio 1
	s_barrier
	v_mfma_f32_16x16x32_bf16 v[124:127], v[142:145], v[178:181], v[124:127]
	v_mfma_f32_16x16x32_bf16 v[120:123], v[154:157], v[178:181], v[120:123]
	v_mfma_f32_16x16x32_bf16 v[108:111], v[142:145], v[186:189], v[108:111]
	v_mfma_f32_16x16x32_bf16 v[104:107], v[154:157], v[186:189], v[104:107]
	v_mfma_f32_16x16x32_bf16 v[92:95], v[142:145], v[194:197], v[92:95]
	v_mfma_f32_16x16x32_bf16 v[88:91], v[154:157], v[194:197], v[88:91]
	v_mfma_f32_16x16x32_bf16 v[76:79], v[142:145], v[202:205], v[76:79]
	v_mfma_f32_16x16x32_bf16 v[72:75], v[154:157], v[202:205], v[72:75]
	v_mfma_f32_16x16x32_bf16 v[124:127], v[150:153], v[182:185], v[124:127]
	v_mfma_f32_16x16x32_bf16 v[120:123], v[158:161], v[182:185], v[120:123]
	v_mfma_f32_16x16x32_bf16 v[108:111], v[150:153], v[190:193], v[108:111]
	v_mfma_f32_16x16x32_bf16 v[104:107], v[158:161], v[190:193], v[104:107]
	v_mfma_f32_16x16x32_bf16 v[92:95], v[150:153], v[198:201], v[92:95]
	v_mfma_f32_16x16x32_bf16 v[88:91], v[158:161], v[198:201], v[88:91]
	v_mfma_f32_16x16x32_bf16 v[76:79], v[150:153], v[206:209], v[76:79]
	v_mfma_f32_16x16x32_bf16 v[72:75], v[158:161], v[206:209], v[72:75]
	s_setprio 0
	s_setprio 1
	v_mfma_f32_16x16x32_bf16 v[116:119], v[162:165], v[178:181], v[116:119]
	v_mfma_f32_16x16x32_bf16 v[112:115], v[170:173], v[178:181], v[112:115]
	v_mfma_f32_16x16x32_bf16 v[100:103], v[162:165], v[186:189], v[100:103]
	v_mfma_f32_16x16x32_bf16 v[96:99], v[170:173], v[186:189], v[96:99]
	v_mfma_f32_16x16x32_bf16 v[84:87], v[162:165], v[194:197], v[84:87]
	v_mfma_f32_16x16x32_bf16 v[80:83], v[170:173], v[194:197], v[80:83]
	v_mfma_f32_16x16x32_bf16 v[68:71], v[162:165], v[202:205], v[68:71]
	v_mfma_f32_16x16x32_bf16 v[64:67], v[170:173], v[202:205], v[64:67]
	v_mfma_f32_16x16x32_bf16 v[116:119], v[166:169], v[182:185], v[116:119]
	v_mfma_f32_16x16x32_bf16 v[112:115], v[174:177], v[182:185], v[112:115]
	v_mfma_f32_16x16x32_bf16 v[100:103], v[166:169], v[190:193], v[100:103]
	v_mfma_f32_16x16x32_bf16 v[96:99], v[174:177], v[190:193], v[96:99]
	v_mfma_f32_16x16x32_bf16 v[84:87], v[166:169], v[198:201], v[84:87]
	v_mfma_f32_16x16x32_bf16 v[80:83], v[174:177], v[198:201], v[80:83]
	v_mfma_f32_16x16x32_bf16 v[68:71], v[166:169], v[206:209], v[68:71]
	v_mfma_f32_16x16x32_bf16 v[64:67], v[174:177], v[206:209], v[64:67]
	s_setprio 0
	s_barrier
; #define PG8_STAGE(bufoff, gbase, voff) do { _Pragma("unroll") for (int _i = 0; _i < 2; ++_i) \
;         __builtin_amdgcn_global_load_lds((const unsigned*)((const char*)(gbase) + (BYTE_ELEMS ? _i * r##voff + (v##voff)[0] : (v##voff)[_i])), (PG8_LAS unsigned*)(lds + (bufoff) + ldsw + _i * 8192), 16, 0, 0); } while (0)
; #define PG8_LDA(dst, b, h) do { _Pragma("unroll") for (int m = 0; m < 4; ++m) _Pragma("unroll") for (int k = 0; k < 2; ++k) dst[m][k] = *(const PG8_LAS bf16x8*)(lds + PG8_SA(b, h) + aoff + m * 2048 + k * 1024); } while (0)
; #define PG8_WAIT_V(n) asm volatile("s_waitcnt vmcnt(" #n ")" ::: "memory")
; #define PG8_WAIT_L(n) asm volatile("s_waitcnt lgkmcnt(" #n ")" ::: "memory")
; #define PG8_BAR __builtin_amdgcn_s_barrier()
; #define PG8_SCHED __builtin_amdgcn_sched_barrier(0)
;     ...
;             PG8_LDA(At, 1, 1); PG8_STAGE(PG8_SB(1, 0), b3, offB); PG8_STAGE(PG8_SB(1, 1), b3 + hstepB, offB); PG8_STAGE(PG8_SA(1, 0), a3, offA);
;             PG8_WAIT_V(8); PG8_WAIT_L(0); PG8_BAR; PG8_MMA(1, 0, At, B0); PG8_MMA(1, 1, At, B1); PG8_BAR; PG8_SCHED;
	s_add_i32 s50, s79, s56
	v_lshl_add_u64 v[210:211], v[210:211], 0, s[20:21]
	s_mov_b32 m0, s50
	ds_read_b128 v[178:181], v149 offset:49152
	ds_read_b128 v[182:185], v149 offset:50176
	ds_read_b128 v[186:189], v149 offset:51200
	ds_read_b128 v[190:193], v149 offset:52224
	ds_read_b128 v[194:197], v149 offset:53248
	ds_read_b128 v[198:201], v149 offset:54272
	ds_read_b128 v[202:205], v149 offset:55296
	ds_read_b128 v[206:209], v149 offset:56320
	global_load_lds_dwordx4 v[210:211], off
	s_add_i32 m0, s50, 0x2000
	s_add_u32 s46, s46, 0x160080
	v_lshl_add_u64 v[210:211], v[212:213], 0, s[20:21]
	s_addc_u32 s47, s47, 0
	s_add_i32 s50, s80, s56
	global_load_lds_dwordx4 v[210:211], off
	v_lshl_add_u64 v[210:211], s[46:47], 0, v[130:131]
	s_mov_b32 m0, s50
	s_nop 0
	global_load_lds_dwordx4 v[210:211], off
	v_lshl_add_u64 v[210:211], s[46:47], 0, v[134:135]
	s_add_i32 m0, s50, 0x2000
	s_nop 0
	global_load_lds_dwordx4 v[210:211], off
	v_lshl_add_u64 v[210:211], v[214:215], 0, s[20:21]
	s_mov_b32 m0, s64
	s_nop 0
	global_load_lds_dwordx4 v[210:211], off
	v_lshl_add_u64 v[210:211], v[216:217], 0, s[20:21]
	s_mov_b32 m0, s65
	s_nop 0
	global_load_lds_dwordx4 v[210:211], off
	s_waitcnt vmcnt(8)
	s_waitcnt lgkmcnt(0)
	s_setprio 1
	s_barrier
	v_mfma_f32_16x16x32_bf16 v[60:63], v[142:145], v[178:181], v[60:63]
	v_mfma_f32_16x16x32_bf16 v[56:59], v[154:157], v[178:181], v[56:59]
	v_mfma_f32_16x16x32_bf16 v[44:47], v[142:145], v[186:189], v[44:47]
	v_mfma_f32_16x16x32_bf16 v[40:43], v[154:157], v[186:189], v[40:43]
	v_mfma_f32_16x16x32_bf16 v[28:31], v[142:145], v[194:197], v[28:31]
	v_mfma_f32_16x16x32_bf16 v[24:27], v[154:157], v[194:197], v[24:27]
	v_mfma_f32_16x16x32_bf16 v[12:15], v[142:145], v[202:205], v[12:15]
	v_mfma_f32_16x16x32_bf16 v[8:11], v[154:157], v[202:205], v[8:11]
	v_mfma_f32_16x16x32_bf16 v[60:63], v[150:153], v[182:185], v[60:63]
	v_mfma_f32_16x16x32_bf16 v[56:59], v[158:161], v[182:185], v[56:59]
	v_mfma_f32_16x16x32_bf16 v[44:47], v[150:153], v[190:193], v[44:47]
	v_mfma_f32_16x16x32_bf16 v[40:43], v[158:161], v[190:193], v[40:43]
	v_mfma_f32_16x16x32_bf16 v[28:31], v[150:153], v[198:201], v[28:31]
	v_mfma_f32_16x16x32_bf16 v[24:27], v[158:161], v[198:201], v[24:27]
	v_mfma_f32_16x16x32_bf16 v[12:15], v[150:153], v[206:209], v[12:15]
	v_mfma_f32_16x16x32_bf16 v[8:11], v[158:161], v[206:209], v[8:11]
	s_setprio 0
	s_setprio 1
	v_mfma_f32_16x16x32_bf16 v[52:55], v[162:165], v[178:181], v[52:55]
	v_mfma_f32_16x16x32_bf16 v[48:51], v[170:173], v[178:181], v[48:51]
	v_mfma_f32_16x16x32_bf16 v[36:39], v[162:165], v[186:189], v[36:39]
	v_mfma_f32_16x16x32_bf16 v[32:35], v[170:173], v[186:189], v[32:35]
	v_mfma_f32_16x16x32_bf16 v[20:23], v[162:165], v[194:197], v[20:23]
	v_mfma_f32_16x16x32_bf16 v[16:19], v[170:173], v[194:197], v[16:19]
	v_mfma_f32_16x16x32_bf16 v[4:7], v[162:165], v[202:205], v[4:7]
	v_mfma_f32_16x16x32_bf16 v[0:3], v[170:173], v[202:205], v[0:3]
	v_mfma_f32_16x16x32_bf16 v[52:55], v[166:169], v[182:185], v[52:55]
	v_mfma_f32_16x16x32_bf16 v[48:51], v[174:177], v[182:185], v[48:51]
	v_mfma_f32_16x16x32_bf16 v[36:39], v[166:169], v[190:193], v[36:39]
	v_mfma_f32_16x16x32_bf16 v[32:35], v[174:177], v[190:193], v[32:35]
	v_mfma_f32_16x16x32_bf16 v[20:23], v[166:169], v[198:201], v[20:23]
	v_mfma_f32_16x16x32_bf16 v[16:19], v[174:177], v[198:201], v[16:19]
	v_mfma_f32_16x16x32_bf16 v[4:7], v[166:169], v[206:209], v[4:7]
	v_mfma_f32_16x16x32_bf16 v[0:3], v[174:177], v[206:209], v[0:3]
	s_setprio 0
	s_barrier
	s_add_i32 s78, s78, 2
	s_add_u32 s42, s42, 0x100
	s_addc_u32 s43, s43, 0
	s_add_u32 s76, s76, 0x100
	s_addc_u32 s77, s77, 0
	s_cmpk_gt_u32 s78, 0x55
	s_cbranch_scc0 .LBB0_389
	s_and_b64 vcc, exec, s[22:23]
	s_cbranch_vccz .LBB0_392
	s_barrier

; #define PG8_STAGE(bufoff, gbase, voff) do { _Pragma("unroll") for (int _i = 0; _i < 2; ++_i) \
;         __builtin_amdgcn_global_load_lds((const unsigned*)((const char*)(gbase) + (BYTE_ELEMS ? _i * r##voff + (v##voff)[0] : (v##voff)[_i])), (PG8_LAS unsigned*)(lds + (bufoff) + ldsw + _i * 8192), 16, 0, 0); } while (0)
; #define PG8_LDA(dst, b, h) do { _Pragma("unroll") for (int m = 0; m < 4; ++m) _Pragma("unroll") for (int k = 0; k < 2; ++k) dst[m][k] = *(const PG8_LAS bf16x8*)(lds + PG8_SA(b, h) + aoff + m * 2048 + k * 1024); } while (0)
; #define PG8_LDB(dst, b, h) do { _Pragma("unroll") for (int n = 0; n < 2; ++n) _Pragma("unroll") for (int k = 0; k < 2; ++k) dst[n][k] = *(const PG8_LAS bf16x8*)(lds + PG8_SB(b, h) + boff + n * 2048 + k * 1024); } while (0)
; #define PG8_WAIT_V(n) asm volatile("s_waitcnt vmcnt(" #n ")" ::: "memory")
; #define PG8_WAIT_L(n) asm volatile("s_waitcnt lgkmcnt(" #n ")" ::: "memory")
; #define PG8_BAR __builtin_amdgcn_s_barrier()
; #define PG8_SCHED __builtin_amdgcn_sched_barrier(0)
;     ...
;             PG8_LDB(B0, 0, 0); PG8_LDB(B1, 0, 1); PG8_SCHED; PG8_LDA(At, 0, 0); PG8_STAGE(PG8_SA(1, 1), a1 + hstepA, offA);
;             PG8_WAIT_V(8); PG8_WAIT_L(0); PG8_BAR; PG8_MMA(0, 0, At, B0); PG8_MMA(0, 1, At, B1); PG8_BAR; PG8_SCHED;
;             PG8_LDA(At, 0, 1); PG8_STAGE(PG8_SB(0, 0), b2, offB); PG8_STAGE(PG8_SB(0, 1), b2 + hstepB, offB); PG8_STAGE(PG8_SA(0, 0), a2, offA);
;             PG8_WAIT_V(8); PG8_WAIT_L(0); PG8_BAR; PG8_MMA(1, 0, At, B0); PG8_MMA(1, 1, At, B1); PG8_BAR; PG8_SCHED;
.LBB0_476:
	ds_read_b128 v[144:147], v163
	ds_read_b128 v[148:151], v163 offset:1024
	ds_read_b128 v[152:155], v163 offset:2048
	ds_read_b128 v[156:159], v163 offset:3072
	ds_read_b128 v[168:171], v164
	ds_read_b128 v[172:175], v164 offset:1024
	ds_read_b128 v[176:179], v164 offset:2048
	ds_read_b128 v[180:183], v164 offset:3072
	s_add_u32 s4, s2, 0xfff80080
	s_addc_u32 s5, s3, -1
	s_cmp_eq_u32 s94, 28
	s_cselect_b32 s67, s1, s5
	s_cselect_b32 s66, s7, s4
	s_cselect_b32 s5, s57, s69
	s_cselect_b32 s4, s59, s68
	v_lshl_add_u64 v[160:161], s[2:3], 0, v[138:139]
	s_add_i32 m0, s71, 0xc000
	ds_read_b128 v[184:187], v165
	ds_read_b128 v[188:191], v165 offset:1024
	ds_read_b128 v[192:195], v165 offset:2048
	ds_read_b128 v[196:199], v165 offset:3072
	ds_read_b128 v[200:203], v165 offset:4096
	ds_read_b128 v[204:207], v165 offset:5120
	ds_read_b128 v[208:211], v165 offset:6144
	ds_read_b128 v[212:215], v165 offset:7168
	global_load_lds_dwordx4 v[160:161], off
	v_lshl_add_u64 v[160:161], s[2:3], 0, v[140:141]
	s_add_i32 m0, s71, 0xe000
	s_nop 0
	global_load_lds_dwordx4 v[160:161], off
	s_waitcnt vmcnt(8)
	s_waitcnt lgkmcnt(0)
	s_setprio 1
	s_barrier
	v_mfma_f32_16x16x32_bf16 v[124:127], v[144:147], v[184:187], v[124:127]
	v_mfma_f32_16x16x32_bf16 v[120:123], v[152:155], v[184:187], v[120:123]
	v_mfma_f32_16x16x32_bf16 v[108:111], v[144:147], v[192:195], v[108:111]
	v_mfma_f32_16x16x32_bf16 v[104:107], v[152:155], v[192:195], v[104:107]
	v_mfma_f32_16x16x32_bf16 v[92:95], v[144:147], v[200:203], v[92:95]
	v_mfma_f32_16x16x32_bf16 v[88:91], v[152:155], v[200:203], v[88:91]
	v_mfma_f32_16x16x32_bf16 v[76:79], v[144:147], v[208:211], v[76:79]
	v_mfma_f32_16x16x32_bf16 v[72:75], v[152:155], v[208:211], v[72:75]
	v_mfma_f32_16x16x32_bf16 v[124:127], v[148:151], v[188:191], v[124:127]
	v_mfma_f32_16x16x32_bf16 v[120:123], v[156:159], v[188:191], v[120:123]
	v_mfma_f32_16x16x32_bf16 v[108:111], v[148:151], v[196:199], v[108:111]
	v_mfma_f32_16x16x32_bf16 v[104:107], v[156:159], v[196:199], v[104:107]
	v_mfma_f32_16x16x32_bf16 v[92:95], v[148:151], v[204:207], v[92:95]
	v_mfma_f32_16x16x32_bf16 v[88:91], v[156:159], v[204:207], v[88:91]
	v_mfma_f32_16x16x32_bf16 v[76:79], v[148:151], v[212:215], v[76:79]
	v_mfma_f32_16x16x32_bf16 v[72:75], v[156:159], v[212:215], v[72:75]
	s_setprio 0
	s_setprio 1
	v_mfma_f32_16x16x32_bf16 v[116:119], v[168:171], v[184:187], v[116:119]
	v_mfma_f32_16x16x32_bf16 v[112:115], v[176:179], v[184:187], v[112:115]
	v_mfma_f32_16x16x32_bf16 v[100:103], v[168:171], v[192:195], v[100:103]
	v_mfma_f32_16x16x32_bf16 v[96:99], v[176:179], v[192:195], v[96:99]
	v_mfma_f32_16x16x32_bf16 v[84:87], v[168:171], v[200:203], v[84:87]
	v_mfma_f32_16x16x32_bf16 v[80:83], v[176:179], v[200:203], v[80:83]
	v_mfma_f32_16x16x32_bf16 v[68:71], v[168:171], v[208:211], v[68:71]
	v_mfma_f32_16x16x32_bf16 v[64:67], v[176:179], v[208:211], v[64:67]
	v_mfma_f32_16x16x32_bf16 v[116:119], v[172:175], v[188:191], v[116:119]
	v_mfma_f32_16x16x32_bf16 v[112:115], v[180:183], v[188:191], v[112:115]
	v_mfma_f32_16x16x32_bf16 v[100:103], v[172:175], v[196:199], v[100:103]
	v_mfma_f32_16x16x32_bf16 v[96:99], v[180:183], v[196:199], v[96:99]
	v_mfma_f32_16x16x32_bf16 v[84:87], v[172:175], v[204:207], v[84:87]
	v_mfma_f32_16x16x32_bf16 v[80:83], v[180:183], v[204:207], v[80:83]
	v_mfma_f32_16x16x32_bf16 v[68:71], v[172:175], v[212:215], v[68:71]
	v_mfma_f32_16x16x32_bf16 v[64:67], v[180:183], v[212:215], v[64:67]
	s_setprio 0
	s_barrier
	s_add_i32 s95, s87, s70
	v_lshl_add_u64 v[160:161], s[4:5], 0, v[130:131]
	s_mov_b32 m0, s95
	ds_read_b128 v[184:187], v165 offset:16384
	ds_read_b128 v[188:191], v165 offset:17408
	ds_read_b128 v[192:195], v165 offset:18432
	ds_read_b128 v[196:199], v165 offset:19456
	ds_read_b128 v[200:203], v165 offset:20480
	ds_read_b128 v[204:207], v165 offset:21504
	ds_read_b128 v[208:211], v165 offset:22528
	ds_read_b128 v[212:215], v165 offset:23552
	global_load_lds_dwordx4 v[160:161], off
	s_add_i32 m0, s95, 0x2000
	s_add_u32 s96, s4, 0x80000
	v_lshl_add_u64 v[216:217], s[4:5], 0, v[134:135]
	s_addc_u32 s97, s5, 0
	s_add_i32 s95, s88, s70
	global_load_lds_dwordx4 v[216:217], off
	v_lshl_add_u64 v[218:219], s[96:97], 0, v[130:131]
	s_mov_b32 m0, s95
	v_lshl_add_u64 v[220:221], s[66:67], 0, v[132:133]
	global_load_lds_dwordx4 v[218:219], off
	v_lshl_add_u64 v[218:219], s[96:97], 0, v[134:135]
	s_add_i32 m0, s95, 0x2000
	s_nop 0
	global_load_lds_dwordx4 v[218:219], off
	v_lshl_add_u64 v[218:219], s[66:67], 0, v[128:129]
	s_mov_b32 m0, s71
	s_nop 0
	global_load_lds_dwordx4 v[218:219], off
	s_mov_b32 m0, s72
	s_nop 0
	global_load_lds_dwordx4 v[220:221], off
	s_waitcnt vmcnt(8)
	s_waitcnt lgkmcnt(0)
	s_setprio 1
	s_barrier
; #define PG8_STAGE(bufoff, gbase, voff) do { _Pragma("unroll") for (int _i = 0; _i < 2; ++_i) \
;         __builtin_amdgcn_global_load_lds((const unsigned*)((const char*)(gbase) + (BYTE_ELEMS ? _i * r##voff + (v##voff)[0] : (v##voff)[_i])), (PG8_LAS unsigned*)(lds + (bufoff) + ldsw + _i * 8192), 16, 0, 0); } while (0)
; #define PG8_LDA(dst, b, h) do { _Pragma("unroll") for (int m = 0; m < 4; ++m) _Pragma("unroll") for (int k = 0; k < 2; ++k) dst[m][k] = *(const PG8_LAS bf16x8*)(lds + PG8_SA(b, h) + aoff + m * 2048 + k * 1024); } while (0)
; #define PG8_LDB(dst, b, h) do { _Pragma("unroll") for (int n = 0; n < 2; ++n) _Pragma("unroll") for (int k = 0; k < 2; ++k) dst[n][k] = *(const PG8_LAS bf16x8*)(lds + PG8_SB(b, h) + boff + n * 2048 + k * 1024); } while (0)
; #define PG8_WAIT_V(n) asm volatile("s_waitcnt vmcnt(" #n ")" ::: "memory")
; #define PG8_WAIT_L(n) asm volatile("s_waitcnt lgkmcnt(" #n ")" ::: "memory")
; #define PG8_BAR __builtin_amdgcn_s_barrier()
; #define PG8_SCHED __builtin_amdgcn_sched_barrier(0)
;     ...
;             PG8_LDB(B0, 0, 0); PG8_LDB(B1, 0, 1); PG8_SCHED; PG8_LDA(At, 0, 0); PG8_STAGE(PG8_SA(1, 1), a1 + hstepA, offA);
;             PG8_WAIT_V(8); PG8_WAIT_L(0); PG8_BAR; PG8_MMA(0, 0, At, B0); PG8_MMA(0, 1, At, B1); PG8_BAR; PG8_SCHED;
;             PG8_LDA(At, 0, 1); PG8_STAGE(PG8_SB(0, 0), b2, offB); PG8_STAGE(PG8_SB(0, 1), b2 + hstepB, offB); PG8_STAGE(PG8_SA(0, 0), a2, offA);
;             PG8_WAIT_V(8); PG8_WAIT_L(0); PG8_BAR; PG8_MMA(1, 0, At, B0); PG8_MMA(1, 1, At, B1); PG8_BAR; PG8_SCHED;
;             PG8_LDB(B0, 1, 0); PG8_LDB(B1, 1, 1); PG8_SCHED; PG8_LDA(At, 1, 0); PG8_STAGE(PG8_SA(0, 1), a2 + hstepA, offA);
;             PG8_WAIT_V(8); PG8_WAIT_L(0); PG8_BAR; PG8_MMA(0, 0, At, B0); PG8_MMA(0, 1, At, B1); PG8_BAR; PG8_SCHED;
;             PG8_LDA(At, 1, 1); PG8_STAGE(PG8_SB(1, 0), b3, offB); PG8_STAGE(PG8_SB(1, 1), b3 + hstepB, offB); PG8_STAGE(PG8_SA(1, 0), a3, offA);
;             PG8_WAIT_V(8); PG8_WAIT_L(0); PG8_BAR; PG8_MMA(1, 0, At, B0); PG8_MMA(1, 1, At, B1); PG8_BAR; PG8_SCHED;
	v_mfma_f32_16x16x32_bf16 v[60:63], v[144:147], v[184:187], v[60:63]
	v_mfma_f32_16x16x32_bf16 v[56:59], v[152:155], v[184:187], v[56:59]
	v_mfma_f32_16x16x32_bf16 v[44:47], v[144:147], v[192:195], v[44:47]
	v_mfma_f32_16x16x32_bf16 v[40:43], v[152:155], v[192:195], v[40:43]
	v_mfma_f32_16x16x32_bf16 v[28:31], v[144:147], v[200:203], v[28:31]
	v_mfma_f32_16x16x32_bf16 v[24:27], v[152:155], v[200:203], v[24:27]
	v_mfma_f32_16x16x32_bf16 v[12:15], v[144:147], v[208:211], v[12:15]
	v_mfma_f32_16x16x32_bf16 v[8:11], v[152:155], v[208:211], v[8:11]
	v_mfma_f32_16x16x32_bf16 v[60:63], v[148:151], v[188:191], v[60:63]
	v_mfma_f32_16x16x32_bf16 v[56:59], v[156:159], v[188:191], v[56:59]
	v_mfma_f32_16x16x32_bf16 v[44:47], v[148:151], v[196:199], v[44:47]
	v_mfma_f32_16x16x32_bf16 v[40:43], v[156:159], v[196:199], v[40:43]
	v_mfma_f32_16x16x32_bf16 v[28:31], v[148:151], v[204:207], v[28:31]
	v_mfma_f32_16x16x32_bf16 v[24:27], v[156:159], v[204:207], v[24:27]
	v_mfma_f32_16x16x32_bf16 v[12:15], v[148:151], v[212:215], v[12:15]
	v_mfma_f32_16x16x32_bf16 v[8:11], v[156:159], v[212:215], v[8:11]
	s_setprio 0
	s_setprio 1
	v_mfma_f32_16x16x32_bf16 v[52:55], v[168:171], v[184:187], v[52:55]
	v_mfma_f32_16x16x32_bf16 v[48:51], v[176:179], v[184:187], v[48:51]
	v_mfma_f32_16x16x32_bf16 v[36:39], v[168:171], v[192:195], v[36:39]
	v_mfma_f32_16x16x32_bf16 v[32:35], v[176:179], v[192:195], v[32:35]
	v_mfma_f32_16x16x32_bf16 v[20:23], v[168:171], v[200:203], v[20:23]
	v_mfma_f32_16x16x32_bf16 v[16:19], v[176:179], v[200:203], v[16:19]
	v_mfma_f32_16x16x32_bf16 v[4:7], v[168:171], v[208:211], v[4:7]
	v_mfma_f32_16x16x32_bf16 v[0:3], v[176:179], v[208:211], v[0:3]
	v_mfma_f32_16x16x32_bf16 v[52:55], v[172:175], v[188:191], v[52:55]
	v_mfma_f32_16x16x32_bf16 v[48:51], v[180:183], v[188:191], v[48:51]
	v_mfma_f32_16x16x32_bf16 v[36:39], v[172:175], v[196:199], v[36:39]
	v_mfma_f32_16x16x32_bf16 v[32:35], v[180:183], v[196:199], v[32:35]
	v_mfma_f32_16x16x32_bf16 v[20:23], v[172:175], v[204:207], v[20:23]
	v_mfma_f32_16x16x32_bf16 v[16:19], v[180:183], v[204:207], v[16:19]
	v_mfma_f32_16x16x32_bf16 v[4:7], v[172:175], v[212:215], v[4:7]
	v_mfma_f32_16x16x32_bf16 v[0:3], v[180:183], v[212:215], v[0:3]
	s_setprio 0
	s_barrier
	s_add_i32 s95, 0, 0x18000
	v_add_u32_e32 v136, s95, v162
	s_add_i32 s96, 0, 0x1c000
	ds_read_b128 v[144:147], v136
	ds_read_b128 v[148:151], v136 offset:1024
	ds_read_b128 v[152:155], v136 offset:2048
	ds_read_b128 v[156:159], v136 offset:3072
	v_add_u32_e32 v136, s96, v162
	ds_read_b128 v[168:171], v136
	ds_read_b128 v[172:175], v136 offset:1024
	ds_read_b128 v[176:179], v136 offset:2048
	ds_read_b128 v[180:183], v136 offset:3072
	s_add_u32 s66, s66, 0x80000
	s_addc_u32 s67, s67, 0
	s_mov_b32 m0, s73
	v_lshl_add_u64 v[222:223], s[66:67], 0, v[128:129]
	ds_read_b128 v[184:187], v165 offset:32768
	ds_read_b128 v[188:191], v165 offset:33792
	ds_read_b128 v[192:195], v165 offset:34816
	ds_read_b128 v[196:199], v165 offset:35840
	ds_read_b128 v[200:203], v165 offset:36864
	ds_read_b128 v[204:207], v165 offset:37888
	ds_read_b128 v[208:211], v165 offset:38912
	ds_read_b128 v[212:215], v165 offset:39936
	global_load_lds_dwordx4 v[222:223], off
	v_lshl_add_u64 v[222:223], s[66:67], 0, v[132:133]
	s_mov_b32 m0, s76
	s_nop 0
	global_load_lds_dwordx4 v[222:223], off
	s_waitcnt vmcnt(8)
	s_waitcnt lgkmcnt(0)
	s_setprio 1
	s_barrier
	v_mfma_f32_16x16x32_bf16 v[124:127], v[144:147], v[184:187], v[124:127]
	v_mfma_f32_16x16x32_bf16 v[120:123], v[152:155], v[184:187], v[120:123]
	v_mfma_f32_16x16x32_bf16 v[108:111], v[144:147], v[192:195], v[108:111]
	v_mfma_f32_16x16x32_bf16 v[104:107], v[152:155], v[192:195], v[104:107]
	v_mfma_f32_16x16x32_bf16 v[92:95], v[144:147], v[200:203], v[92:95]
	v_mfma_f32_16x16x32_bf16 v[88:91], v[152:155], v[200:203], v[88:91]
	v_mfma_f32_16x16x32_bf16 v[76:79], v[144:147], v[208:211], v[76:79]
	v_mfma_f32_16x16x32_bf16 v[72:75], v[152:155], v[208:211], v[72:75]
	v_mfma_f32_16x16x32_bf16 v[124:127], v[148:151], v[188:191], v[124:127]
	v_mfma_f32_16x16x32_bf16 v[120:123], v[156:159], v[188:191], v[120:123]
	v_mfma_f32_16x16x32_bf16 v[108:111], v[148:151], v[196:199], v[108:111]
	v_mfma_f32_16x16x32_bf16 v[104:107], v[156:159], v[196:199], v[104:107]
	v_mfma_f32_16x16x32_bf16 v[92:95], v[148:151], v[204:207], v[92:95]
	v_mfma_f32_16x16x32_bf16 v[88:91], v[156:159], v[204:207], v[88:91]
	v_mfma_f32_16x16x32_bf16 v[76:79], v[148:151], v[212:215], v[76:79]
	v_mfma_f32_16x16x32_bf16 v[72:75], v[156:159], v[212:215], v[72:75]
	s_setprio 0
	s_setprio 1
	v_mfma_f32_16x16x32_bf16 v[116:119], v[168:171], v[184:187], v[116:119]
	v_mfma_f32_16x16x32_bf16 v[112:115], v[176:179], v[184:187], v[112:115]
	v_mfma_f32_16x16x32_bf16 v[100:103], v[168:171], v[192:195], v[100:103]
	v_mfma_f32_16x16x32_bf16 v[96:99], v[176:179], v[192:195], v[96:99]
	v_mfma_f32_16x16x32_bf16 v[84:87], v[168:171], v[200:203], v[84:87]
	v_mfma_f32_16x16x32_bf16 v[80:83], v[176:179], v[200:203], v[80:83]
	v_mfma_f32_16x16x32_bf16 v[68:71], v[168:171], v[208:211], v[68:71]
	v_mfma_f32_16x16x32_bf16 v[64:67], v[176:179], v[208:211], v[64:67]
	v_mfma_f32_16x16x32_bf16 v[116:119], v[172:175], v[188:191], v[116:119]
	v_mfma_f32_16x16x32_bf16 v[112:115], v[180:183], v[188:191], v[112:115]
	v_mfma_f32_16x16x32_bf16 v[100:103], v[172:175], v[196:199], v[100:103]
	v_mfma_f32_16x16x32_bf16 v[96:99], v[180:183], v[196:199], v[96:99]
	v_mfma_f32_16x16x32_bf16 v[84:87], v[172:175], v[204:207], v[84:87]
	v_mfma_f32_16x16x32_bf16 v[80:83], v[180:183], v[204:207], v[80:83]
	v_mfma_f32_16x16x32_bf16 v[68:71], v[172:175], v[212:215], v[68:71]
	v_mfma_f32_16x16x32_bf16 v[64:67], v[180:183], v[212:215], v[64:67]
	s_setprio 0
	s_barrier
; #define PG8_STAGE(bufoff, gbase, voff) do { _Pragma("unroll") for (int _i = 0; _i < 2; ++_i) \
;         __builtin_amdgcn_global_load_lds((const unsigned*)((const char*)(gbase) + (BYTE_ELEMS ? _i * r##voff + (v##voff)[0] : (v##voff)[_i])), (PG8_LAS unsigned*)(lds + (bufoff) + ldsw + _i * 8192), 16, 0, 0); } while (0)
; #define PG8_LDA(dst, b, h) do { _Pragma("unroll") for (int m = 0; m < 4; ++m) _Pragma("unroll") for (int k = 0; k < 2; ++k) dst[m][k] = *(const PG8_LAS bf16x8*)(lds + PG8_SA(b, h) + aoff + m * 2048 + k * 1024); } while (0)
; #define PG8_LDB(dst, b, h) do { _Pragma("unroll") for (int n = 0; n < 2; ++n) _Pragma("unroll") for (int k = 0; k < 2; ++k) dst[n][k] = *(const PG8_LAS bf16x8*)(lds + PG8_SB(b, h) + boff + n * 2048 + k * 1024); } while (0)
; #define PG8_WAIT_V(n) asm volatile("s_waitcnt vmcnt(" #n ")" ::: "memory")
; #define PG8_WAIT_L(n) asm volatile("s_waitcnt lgkmcnt(" #n ")" ::: "memory")
; #define PG8_BAR __builtin_amdgcn_s_barrier()
; #define PG8_SCHED __builtin_amdgcn_sched_barrier(0)
;     ...
;         for (int t = 0; t < nt; t += 2) {
;     ...
;             PG8_LDB(B0, 0, 0); PG8_LDB(B1, 0, 1); PG8_SCHED; PG8_LDA(At, 0, 0); PG8_STAGE(PG8_SA(1, 1), a1 + hstepA, offA);
;             PG8_WAIT_V(8); PG8_WAIT_L(0); PG8_BAR; PG8_MMA(0, 0, At, B0); PG8_MMA(0, 1, At, B1); PG8_BAR; PG8_SCHED;
;             PG8_LDA(At, 0, 1); PG8_STAGE(PG8_SB(0, 0), b2, offB); PG8_STAGE(PG8_SB(0, 1), b2 + hstepB, offB); PG8_STAGE(PG8_SA(0, 0), a2, offA);
;             PG8_WAIT_V(8); PG8_WAIT_L(0); PG8_BAR; PG8_MMA(1, 0, At, B0); PG8_MMA(1, 1, At, B1); PG8_BAR; PG8_SCHED;
;             PG8_LDB(B0, 1, 0); PG8_LDB(B1, 1, 1); PG8_SCHED; PG8_LDA(At, 1, 0); PG8_STAGE(PG8_SA(0, 1), a2 + hstepA, offA);
;             PG8_WAIT_V(8); PG8_WAIT_L(0); PG8_BAR; PG8_MMA(0, 0, At, B0); PG8_MMA(0, 1, At, B1); PG8_BAR; PG8_SCHED;
;             PG8_LDA(At, 1, 1); PG8_STAGE(PG8_SB(1, 0), b3, offB); PG8_STAGE(PG8_SB(1, 1), b3 + hstepB, offB); PG8_STAGE(PG8_SA(1, 0), a3, offA);
;             PG8_WAIT_V(8); PG8_WAIT_L(0); PG8_BAR; PG8_MMA(1, 0, At, B0); PG8_MMA(1, 1, At, B1); PG8_BAR; PG8_SCHED;
	s_add_i32 s66, s95, s70
	v_lshl_add_u64 v[160:161], v[160:161], 0, s[50:51]
	s_mov_b32 m0, s66
	ds_read_b128 v[184:187], v165 offset:49152
	ds_read_b128 v[188:191], v165 offset:50176
	ds_read_b128 v[192:195], v165 offset:51200
	ds_read_b128 v[196:199], v165 offset:52224
	ds_read_b128 v[200:203], v165 offset:53248
	ds_read_b128 v[204:207], v165 offset:54272
	ds_read_b128 v[208:211], v165 offset:55296
	ds_read_b128 v[212:215], v165 offset:56320
	global_load_lds_dwordx4 v[160:161], off
	s_add_i32 m0, s66, 0x2000
	s_add_u32 s4, s4, 0x80080
	v_lshl_add_u64 v[160:161], v[216:217], 0, s[50:51]
	s_addc_u32 s5, s5, 0
	s_add_i32 s66, s96, s70
	global_load_lds_dwordx4 v[160:161], off
	v_lshl_add_u64 v[160:161], s[4:5], 0, v[130:131]
	s_mov_b32 m0, s66
	s_nop 0
	global_load_lds_dwordx4 v[160:161], off
	v_lshl_add_u64 v[160:161], s[4:5], 0, v[134:135]
	s_add_i32 m0, s66, 0x2000
	s_nop 0
	global_load_lds_dwordx4 v[160:161], off
	v_lshl_add_u64 v[160:161], v[218:219], 0, s[50:51]
	s_mov_b32 m0, s82
	s_nop 0
	global_load_lds_dwordx4 v[160:161], off
	v_lshl_add_u64 v[160:161], v[220:221], 0, s[50:51]
	s_mov_b32 m0, s83
	s_nop 0
	global_load_lds_dwordx4 v[160:161], off
	s_waitcnt vmcnt(8)
	s_waitcnt lgkmcnt(0)
	s_setprio 1
	s_barrier
	v_mfma_f32_16x16x32_bf16 v[60:63], v[144:147], v[184:187], v[60:63]
	v_mfma_f32_16x16x32_bf16 v[56:59], v[152:155], v[184:187], v[56:59]
	v_mfma_f32_16x16x32_bf16 v[44:47], v[144:147], v[192:195], v[44:47]
	v_mfma_f32_16x16x32_bf16 v[40:43], v[152:155], v[192:195], v[40:43]
	v_mfma_f32_16x16x32_bf16 v[28:31], v[144:147], v[200:203], v[28:31]
	v_mfma_f32_16x16x32_bf16 v[24:27], v[152:155], v[200:203], v[24:27]
	v_mfma_f32_16x16x32_bf16 v[12:15], v[144:147], v[208:211], v[12:15]
	v_mfma_f32_16x16x32_bf16 v[8:11], v[152:155], v[208:211], v[8:11]
	v_mfma_f32_16x16x32_bf16 v[60:63], v[148:151], v[188:191], v[60:63]
	v_mfma_f32_16x16x32_bf16 v[56:59], v[156:159], v[188:191], v[56:59]
	v_mfma_f32_16x16x32_bf16 v[44:47], v[148:151], v[196:199], v[44:47]
	v_mfma_f32_16x16x32_bf16 v[40:43], v[156:159], v[196:199], v[40:43]
	v_mfma_f32_16x16x32_bf16 v[28:31], v[148:151], v[204:207], v[28:31]
	v_mfma_f32_16x16x32_bf16 v[24:27], v[156:159], v[204:207], v[24:27]
	v_mfma_f32_16x16x32_bf16 v[12:15], v[148:151], v[212:215], v[12:15]
	v_mfma_f32_16x16x32_bf16 v[8:11], v[156:159], v[212:215], v[8:11]
	s_setprio 0
	s_setprio 1
	v_mfma_f32_16x16x32_bf16 v[52:55], v[168:171], v[184:187], v[52:55]
	v_mfma_f32_16x16x32_bf16 v[48:51], v[176:179], v[184:187], v[48:51]
	v_mfma_f32_16x16x32_bf16 v[36:39], v[168:171], v[192:195], v[36:39]
	v_mfma_f32_16x16x32_bf16 v[32:35], v[176:179], v[192:195], v[32:35]
	v_mfma_f32_16x16x32_bf16 v[20:23], v[168:171], v[200:203], v[20:23]
	v_mfma_f32_16x16x32_bf16 v[16:19], v[176:179], v[200:203], v[16:19]
	v_mfma_f32_16x16x32_bf16 v[4:7], v[168:171], v[208:211], v[4:7]
	v_mfma_f32_16x16x32_bf16 v[0:3], v[176:179], v[208:211], v[0:3]
	v_mfma_f32_16x16x32_bf16 v[52:55], v[172:175], v[188:191], v[52:55]
	v_mfma_f32_16x16x32_bf16 v[48:51], v[180:183], v[188:191], v[48:51]
	v_mfma_f32_16x16x32_bf16 v[36:39], v[172:175], v[196:199], v[36:39]
	v_mfma_f32_16x16x32_bf16 v[32:35], v[180:183], v[196:199], v[32:35]
	v_mfma_f32_16x16x32_bf16 v[20:23], v[172:175], v[204:207], v[20:23]
	v_mfma_f32_16x16x32_bf16 v[16:19], v[180:183], v[204:207], v[16:19]
	v_mfma_f32_16x16x32_bf16 v[4:7], v[172:175], v[212:215], v[4:7]
	v_mfma_f32_16x16x32_bf16 v[0:3], v[180:183], v[212:215], v[0:3]
	s_setprio 0
	s_barrier
	s_add_i32 s94, s94, 2
	s_add_u32 s2, s2, 0x100
	s_addc_u32 s3, s3, 0
	s_add_u32 s68, s68, 0x100
	s_addc_u32 s69, s69, 0
	s_cmp_gt_u32 s94, 29
	s_cbranch_scc0 .LBB0_476
	s_and_b64 vcc, exec, s[52:53]
	s_cbranch_vccz .LBB0_479
	s_barrier

; __device__ __forceinline__ int tid_of(int wv) { int l; asm volatile("v_mbcnt_lo_u32_b32 %0, -1, 0\n\tv_mbcnt_hi_u32_b32 %0, -1, %0" : "=v"(l)); return wv * 64 + l; }
; #define PG8_STAGE(bufoff, gbase, voff) do { _Pragma("unroll") for (int _i = 0; _i < 2; ++_i) \
;         __builtin_amdgcn_global_load_lds((const unsigned*)((const char*)(gbase) + (BYTE_ELEMS ? _i * r##voff + (v##voff)[0] : (v##voff)[_i])), (PG8_LAS unsigned*)(lds + (bufoff) + ldsw + _i * 8192), 16, 0, 0); } while (0)
; #define PG8_WAIT_V(n) asm volatile("s_waitcnt vmcnt(" #n ")" ::: "memory")
;     ...
;         const bool has_next = S.next(ui + 1, nxt);
;         const char* nA = has_next ? (const char*)g.A + (size_t)nxt.pm * tstepA : cA; const char* nB = has_next ? (const char*)g.Bt + (size_t)nxt.pn * tstepB : cB;
;         for (int t = 0; t < nt; t += 2) {
;             const bool last = (t == nt - 2);
;             const char* a1 = cA + (size_t)(t + 1) * kstep;
;             const char* a2 = last ? nA : cA + (size_t)(t + 2) * kstep; const char* b2 = last ? nB : cB + (size_t)(t + 2) * kstep;
;             const char* a3 = a2 + kstep; const char* b3 = b2 + kstep;
;             if (last && has_next) S.a_ready(nxt);
;             if constexpr (MID) { if (t == nt / 2) { const int t3 = tid_of(wv); E.mid(acc, cur, wid >> 2, t3 & 15); } }
;             if constexpr (SP2) {
;             PG8_LDB(B0, 0, 0); PG8_LDB(B1, 0, 1); PG8_SCHED; PG8_LDA(At, 0, 0); PG8_STAGE(PG8_SA(1, 1), a1 + hstepA, offA);
;             PG8_WAIT_V(8); PG8_WAIT_L(0); PG8_BAR; PG8_MMA(0, 0, At, B0); PG8_MMA(0, 1, At, B1); PG8_BAR; PG8_SCHED;
;             PG8_LDA(At, 0, 1); PG8_STAGE(PG8_SB(0, 0), b2, offB); PG8_STAGE(PG8_SB(0, 1), b2 + hstepB, offB); PG8_STAGE(PG8_SA(0, 0), a2, offA);
;             PG8_WAIT_V(8); PG8_WAIT_L(0); PG8_BAR; PG8_MMA(1, 0, At, B0); PG8_MMA(1, 1, At, B1); PG8_BAR; PG8_SCHED;
;             PG8_LDB(B0, 1, 0); PG8_LDB(B1, 1, 1); PG8_SCHED; PG8_LDA(At, 1, 0); PG8_STAGE(PG8_SA(0, 1), a2 + hstepA, offA);
;             PG8_WAIT_V(8); PG8_WAIT_L(0); PG8_BAR; PG8_MMA(0, 0, At, B0); PG8_MMA(0, 1, At, B1); PG8_BAR; PG8_SCHED;
;             PG8_LDA(At, 1, 1); PG8_STAGE(PG8_SB(1, 0), b3, offB); PG8_STAGE(PG8_SB(1, 1), b3 + hstepB, offB); PG8_STAGE(PG8_SA(1, 0), a3, offA);
;             PG8_WAIT_V(8); PG8_WAIT_L(0); PG8_BAR; PG8_MMA(1, 0, At, B0); PG8_MMA(1, 1, At, B1); PG8_BAR; PG8_SCHED;
.LBB0_707:
	ds_read_b128 v[146:149], v140
	ds_read_b128 v[150:153], v140 offset:1024
	ds_read_b128 v[154:157], v140 offset:2048
	ds_read_b128 v[158:161], v140 offset:3072
	ds_read_b128 v[162:165], v141
	ds_read_b128 v[166:169], v141 offset:1024
	ds_read_b128 v[170:173], v141 offset:2048
	ds_read_b128 v[174:177], v141 offset:3072
	s_add_u32 s50, s6, s46
	s_addc_u32 s51, s7, s47
	s_add_u32 s50, s50, 0x100
	s_addc_u32 s51, s51, 0
	s_add_u32 s73, s60, s46
	s_addc_u32 s76, s61, s47
	s_cmpk_eq_i32 s46, 0xf00
	s_cselect_b32 s53, s7, s51
	s_cselect_b32 s52, s6, s50
	s_cselect_b32 s51, s5, s76
	s_cselect_b32 s50, s4, s73
	s_mov_b32 m0, s63
	v_lshl_add_u64 v[210:211], v[136:137], 0, s[46:47]
	ds_read_b128 v[178:181], v142
	ds_read_b128 v[182:185], v142 offset:1024
	ds_read_b128 v[186:189], v142 offset:2048
	ds_read_b128 v[190:193], v142 offset:3072
	ds_read_b128 v[194:197], v142 offset:4096
	ds_read_b128 v[198:201], v142 offset:5120
	ds_read_b128 v[202:205], v142 offset:6144
	ds_read_b128 v[206:209], v142 offset:7168
	global_load_lds_dwordx4 v[210:211], off
	v_lshl_add_u64 v[210:211], v[138:139], 0, s[46:47]
	s_mov_b32 m0, s64
	s_nop 0
	global_load_lds_dwordx4 v[210:211], off
	s_waitcnt vmcnt(8)
	s_waitcnt lgkmcnt(0)
	s_setprio 1
	s_barrier
	v_mfma_f32_16x16x32_bf16 v[124:127], v[146:149], v[178:181], v[124:127]
	v_mfma_f32_16x16x32_bf16 v[120:123], v[154:157], v[178:181], v[120:123]
	v_mfma_f32_16x16x32_bf16 v[108:111], v[146:149], v[186:189], v[108:111]
	v_mfma_f32_16x16x32_bf16 v[104:107], v[154:157], v[186:189], v[104:107]
	v_mfma_f32_16x16x32_bf16 v[92:95], v[146:149], v[194:197], v[92:95]
	v_mfma_f32_16x16x32_bf16 v[88:91], v[154:157], v[194:197], v[88:91]
	v_mfma_f32_16x16x32_bf16 v[76:79], v[146:149], v[202:205], v[76:79]
	v_mfma_f32_16x16x32_bf16 v[72:75], v[154:157], v[202:205], v[72:75]
	v_mfma_f32_16x16x32_bf16 v[124:127], v[150:153], v[182:185], v[124:127]
	v_mfma_f32_16x16x32_bf16 v[120:123], v[158:161], v[182:185], v[120:123]
	v_mfma_f32_16x16x32_bf16 v[108:111], v[150:153], v[190:193], v[108:111]
	v_mfma_f32_16x16x32_bf16 v[104:107], v[158:161], v[190:193], v[104:107]
	v_mfma_f32_16x16x32_bf16 v[92:95], v[150:153], v[198:201], v[92:95]
	v_mfma_f32_16x16x32_bf16 v[88:91], v[158:161], v[198:201], v[88:91]
	v_mfma_f32_16x16x32_bf16 v[76:79], v[150:153], v[206:209], v[76:79]
	v_mfma_f32_16x16x32_bf16 v[72:75], v[158:161], v[206:209], v[72:75]
	s_setprio 0
	s_setprio 1
	v_mfma_f32_16x16x32_bf16 v[116:119], v[162:165], v[178:181], v[116:119]
	v_mfma_f32_16x16x32_bf16 v[112:115], v[170:173], v[178:181], v[112:115]
	v_mfma_f32_16x16x32_bf16 v[100:103], v[162:165], v[186:189], v[100:103]
	v_mfma_f32_16x16x32_bf16 v[96:99], v[170:173], v[186:189], v[96:99]
	v_mfma_f32_16x16x32_bf16 v[84:87], v[162:165], v[194:197], v[84:87]
	v_mfma_f32_16x16x32_bf16 v[80:83], v[170:173], v[194:197], v[80:83]
	v_mfma_f32_16x16x32_bf16 v[68:71], v[162:165], v[202:205], v[68:71]
	v_mfma_f32_16x16x32_bf16 v[64:67], v[170:173], v[202:205], v[64:67]
	v_mfma_f32_16x16x32_bf16 v[116:119], v[166:169], v[182:185], v[116:119]
	v_mfma_f32_16x16x32_bf16 v[112:115], v[174:177], v[182:185], v[112:115]
	v_mfma_f32_16x16x32_bf16 v[100:103], v[166:169], v[190:193], v[100:103]
	v_mfma_f32_16x16x32_bf16 v[96:99], v[174:177], v[190:193], v[96:99]
	v_mfma_f32_16x16x32_bf16 v[84:87], v[166:169], v[198:201], v[84:87]
	v_mfma_f32_16x16x32_bf16 v[80:83], v[174:177], v[198:201], v[80:83]
	v_mfma_f32_16x16x32_bf16 v[68:71], v[166:169], v[206:209], v[68:71]
	v_mfma_f32_16x16x32_bf16 v[64:67], v[174:177], v[206:209], v[64:67]
	s_setprio 0
	s_barrier
	s_mov_b32 m0, s65
	v_lshl_add_u64 v[210:211], s[50:51], 0, v[130:131]
	s_add_u32 s76, s50, 0x80000
	ds_read_b128 v[178:181], v142 offset:16384
	ds_read_b128 v[182:185], v142 offset:17408
	ds_read_b128 v[186:189], v142 offset:18432
	ds_read_b128 v[190:193], v142 offset:19456
	ds_read_b128 v[194:197], v142 offset:20480
	ds_read_b128 v[198:201], v142 offset:21504
	ds_read_b128 v[202:205], v142 offset:22528
	ds_read_b128 v[206:209], v142 offset:23552
	global_load_lds_dwordx4 v[210:211], off
	v_lshl_add_u64 v[212:213], s[50:51], 0, v[134:135]
	s_mov_b32 m0, s66
	s_addc_u32 s77, s51, 0
	global_load_lds_dwordx4 v[212:213], off
	v_lshl_add_u64 v[214:215], s[76:77], 0, v[130:131]
	s_mov_b32 m0, s67
	v_lshl_add_u64 v[216:217], s[52:53], 0, v[132:133]
	global_load_lds_dwordx4 v[214:215], off
	v_lshl_add_u64 v[214:215], s[76:77], 0, v[134:135]
	s_mov_b32 m0, s68
	s_nop 0
	global_load_lds_dwordx4 v[214:215], off
	v_lshl_add_u64 v[214:215], s[52:53], 0, v[128:129]
	s_mov_b32 m0, s29
	s_nop 0
	global_load_lds_dwordx4 v[214:215], off
	s_mov_b32 m0, s31
	s_nop 0
	global_load_lds_dwordx4 v[216:217], off
	s_waitcnt vmcnt(8)
	s_waitcnt lgkmcnt(0)
	s_setprio 1
	s_barrier
; #define PG8_STAGE(bufoff, gbase, voff) do { _Pragma("unroll") for (int _i = 0; _i < 2; ++_i) \
;         __builtin_amdgcn_global_load_lds((const unsigned*)((const char*)(gbase) + (BYTE_ELEMS ? _i * r##voff + (v##voff)[0] : (v##voff)[_i])), (PG8_LAS unsigned*)(lds + (bufoff) + ldsw + _i * 8192), 16, 0, 0); } while (0)
; #define PG8_LDA(dst, b, h) do { _Pragma("unroll") for (int m = 0; m < 4; ++m) _Pragma("unroll") for (int k = 0; k < 2; ++k) dst[m][k] = *(const PG8_LAS bf16x8*)(lds + PG8_SA(b, h) + aoff + m * 2048 + k * 1024); } while (0)
; #define PG8_LDB(dst, b, h) do { _Pragma("unroll") for (int n = 0; n < 2; ++n) _Pragma("unroll") for (int k = 0; k < 2; ++k) dst[n][k] = *(const PG8_LAS bf16x8*)(lds + PG8_SB(b, h) + boff + n * 2048 + k * 1024); } while (0)
; #define PG8_WAIT_V(n) asm volatile("s_waitcnt vmcnt(" #n ")" ::: "memory")
; #define PG8_WAIT_L(n) asm volatile("s_waitcnt lgkmcnt(" #n ")" ::: "memory")
; #define PG8_BAR __builtin_amdgcn_s_barrier()
; #define PG8_SCHED __builtin_amdgcn_sched_barrier(0)
;     ...
;             PG8_LDB(B0, 0, 0); PG8_LDB(B1, 0, 1); PG8_SCHED; PG8_LDA(At, 0, 0); PG8_STAGE(PG8_SA(1, 1), a1 + hstepA, offA);
;             PG8_WAIT_V(8); PG8_WAIT_L(0); PG8_BAR; PG8_MMA(0, 0, At, B0); PG8_MMA(0, 1, At, B1); PG8_BAR; PG8_SCHED;
;             PG8_LDA(At, 0, 1); PG8_STAGE(PG8_SB(0, 0), b2, offB); PG8_STAGE(PG8_SB(0, 1), b2 + hstepB, offB); PG8_STAGE(PG8_SA(0, 0), a2, offA);
;             PG8_WAIT_V(8); PG8_WAIT_L(0); PG8_BAR; PG8_MMA(1, 0, At, B0); PG8_MMA(1, 1, At, B1); PG8_BAR; PG8_SCHED;
;             PG8_LDB(B0, 1, 0); PG8_LDB(B1, 1, 1); PG8_SCHED; PG8_LDA(At, 1, 0); PG8_STAGE(PG8_SA(0, 1), a2 + hstepA, offA);
;             PG8_WAIT_V(8); PG8_WAIT_L(0); PG8_BAR; PG8_MMA(0, 0, At, B0); PG8_MMA(0, 1, At, B1); PG8_BAR; PG8_SCHED;
;             PG8_LDA(At, 1, 1); PG8_STAGE(PG8_SB(1, 0), b3, offB); PG8_STAGE(PG8_SB(1, 1), b3 + hstepB, offB); PG8_STAGE(PG8_SA(1, 0), a3, offA);
;             PG8_WAIT_V(8); PG8_WAIT_L(0); PG8_BAR; PG8_MMA(1, 0, At, B0); PG8_MMA(1, 1, At, B1); PG8_BAR; PG8_SCHED;
	v_mfma_f32_16x16x32_bf16 v[60:63], v[146:149], v[178:181], v[60:63]
	v_mfma_f32_16x16x32_bf16 v[56:59], v[154:157], v[178:181], v[56:59]
	v_mfma_f32_16x16x32_bf16 v[44:47], v[146:149], v[186:189], v[44:47]
	v_mfma_f32_16x16x32_bf16 v[40:43], v[154:157], v[186:189], v[40:43]
	v_mfma_f32_16x16x32_bf16 v[28:31], v[146:149], v[194:197], v[28:31]
	v_mfma_f32_16x16x32_bf16 v[24:27], v[154:157], v[194:197], v[24:27]
	v_mfma_f32_16x16x32_bf16 v[12:15], v[146:149], v[202:205], v[12:15]
	v_mfma_f32_16x16x32_bf16 v[8:11], v[154:157], v[202:205], v[8:11]
	v_mfma_f32_16x16x32_bf16 v[60:63], v[150:153], v[182:185], v[60:63]
	v_mfma_f32_16x16x32_bf16 v[56:59], v[158:161], v[182:185], v[56:59]
	v_mfma_f32_16x16x32_bf16 v[44:47], v[150:153], v[190:193], v[44:47]
	v_mfma_f32_16x16x32_bf16 v[40:43], v[158:161], v[190:193], v[40:43]
	v_mfma_f32_16x16x32_bf16 v[28:31], v[150:153], v[198:201], v[28:31]
	v_mfma_f32_16x16x32_bf16 v[24:27], v[158:161], v[198:201], v[24:27]
	v_mfma_f32_16x16x32_bf16 v[12:15], v[150:153], v[206:209], v[12:15]
	v_mfma_f32_16x16x32_bf16 v[8:11], v[158:161], v[206:209], v[8:11]
	s_setprio 0
	s_setprio 1
	v_mfma_f32_16x16x32_bf16 v[52:55], v[162:165], v[178:181], v[52:55]
	v_mfma_f32_16x16x32_bf16 v[48:51], v[170:173], v[178:181], v[48:51]
	v_mfma_f32_16x16x32_bf16 v[36:39], v[162:165], v[186:189], v[36:39]
	v_mfma_f32_16x16x32_bf16 v[32:35], v[170:173], v[186:189], v[32:35]
	v_mfma_f32_16x16x32_bf16 v[20:23], v[162:165], v[194:197], v[20:23]
	v_mfma_f32_16x16x32_bf16 v[16:19], v[170:173], v[194:197], v[16:19]
	v_mfma_f32_16x16x32_bf16 v[4:7], v[162:165], v[202:205], v[4:7]
	v_mfma_f32_16x16x32_bf16 v[0:3], v[170:173], v[202:205], v[0:3]
	v_mfma_f32_16x16x32_bf16 v[52:55], v[166:169], v[182:185], v[52:55]
	v_mfma_f32_16x16x32_bf16 v[48:51], v[174:177], v[182:185], v[48:51]
	v_mfma_f32_16x16x32_bf16 v[36:39], v[166:169], v[190:193], v[36:39]
	v_mfma_f32_16x16x32_bf16 v[32:35], v[174:177], v[190:193], v[32:35]
	v_mfma_f32_16x16x32_bf16 v[20:23], v[166:169], v[198:201], v[20:23]
	v_mfma_f32_16x16x32_bf16 v[16:19], v[174:177], v[198:201], v[16:19]
	v_mfma_f32_16x16x32_bf16 v[4:7], v[166:169], v[206:209], v[4:7]
	v_mfma_f32_16x16x32_bf16 v[0:3], v[174:177], v[206:209], v[0:3]
	s_setprio 0
	s_barrier
	ds_read_b128 v[146:149], v143
	ds_read_b128 v[150:153], v143 offset:1024
	ds_read_b128 v[154:157], v143 offset:2048
	ds_read_b128 v[158:161], v143 offset:3072
	ds_read_b128 v[162:165], v144
	ds_read_b128 v[166:169], v144 offset:1024
	ds_read_b128 v[170:173], v144 offset:2048
	ds_read_b128 v[174:177], v144 offset:3072
	s_add_u32 s52, s52, 0x80000
	s_addc_u32 s53, s53, 0
	s_mov_b32 m0, s55
	v_lshl_add_u64 v[218:219], s[52:53], 0, v[128:129]
	ds_read_b128 v[178:181], v142 offset:32768
	ds_read_b128 v[182:185], v142 offset:33792
	ds_read_b128 v[186:189], v142 offset:34816
	ds_read_b128 v[190:193], v142 offset:35840
	ds_read_b128 v[194:197], v142 offset:36864
	ds_read_b128 v[198:201], v142 offset:37888
	ds_read_b128 v[202:205], v142 offset:38912
	ds_read_b128 v[206:209], v142 offset:39936
	global_load_lds_dwordx4 v[218:219], off
	v_lshl_add_u64 v[218:219], s[52:53], 0, v[132:133]
	s_mov_b32 m0, s56
	s_nop 0
	global_load_lds_dwordx4 v[218:219], off
	s_waitcnt vmcnt(8)
	s_waitcnt lgkmcnt(0)
	s_setprio 1
	s_barrier
	v_mfma_f32_16x16x32_bf16 v[124:127], v[146:149], v[178:181], v[124:127]
	v_mfma_f32_16x16x32_bf16 v[120:123], v[154:157], v[178:181], v[120:123]
	v_mfma_f32_16x16x32_bf16 v[108:111], v[146:149], v[186:189], v[108:111]
	v_mfma_f32_16x16x32_bf16 v[104:107], v[154:157], v[186:189], v[104:107]
	v_mfma_f32_16x16x32_bf16 v[92:95], v[146:149], v[194:197], v[92:95]
	v_mfma_f32_16x16x32_bf16 v[88:91], v[154:157], v[194:197], v[88:91]
	v_mfma_f32_16x16x32_bf16 v[76:79], v[146:149], v[202:205], v[76:79]
	v_mfma_f32_16x16x32_bf16 v[72:75], v[154:157], v[202:205], v[72:75]
	v_mfma_f32_16x16x32_bf16 v[124:127], v[150:153], v[182:185], v[124:127]
	v_mfma_f32_16x16x32_bf16 v[120:123], v[158:161], v[182:185], v[120:123]
	v_mfma_f32_16x16x32_bf16 v[108:111], v[150:153], v[190:193], v[108:111]
	v_mfma_f32_16x16x32_bf16 v[104:107], v[158:161], v[190:193], v[104:107]
	v_mfma_f32_16x16x32_bf16 v[92:95], v[150:153], v[198:201], v[92:95]
	v_mfma_f32_16x16x32_bf16 v[88:91], v[158:161], v[198:201], v[88:91]
	v_mfma_f32_16x16x32_bf16 v[76:79], v[150:153], v[206:209], v[76:79]
	v_mfma_f32_16x16x32_bf16 v[72:75], v[158:161], v[206:209], v[72:75]
	s_setprio 0
	s_setprio 1
	v_mfma_f32_16x16x32_bf16 v[116:119], v[162:165], v[178:181], v[116:119]
	v_mfma_f32_16x16x32_bf16 v[112:115], v[170:173], v[178:181], v[112:115]
	v_mfma_f32_16x16x32_bf16 v[100:103], v[162:165], v[186:189], v[100:103]
	v_mfma_f32_16x16x32_bf16 v[96:99], v[170:173], v[186:189], v[96:99]
	v_mfma_f32_16x16x32_bf16 v[84:87], v[162:165], v[194:197], v[84:87]
	v_mfma_f32_16x16x32_bf16 v[80:83], v[170:173], v[194:197], v[80:83]
	v_mfma_f32_16x16x32_bf16 v[68:71], v[162:165], v[202:205], v[68:71]
	v_mfma_f32_16x16x32_bf16 v[64:67], v[170:173], v[202:205], v[64:67]
	v_mfma_f32_16x16x32_bf16 v[116:119], v[166:169], v[182:185], v[116:119]
	v_mfma_f32_16x16x32_bf16 v[112:115], v[174:177], v[182:185], v[112:115]
	v_mfma_f32_16x16x32_bf16 v[100:103], v[166:169], v[190:193], v[100:103]
	v_mfma_f32_16x16x32_bf16 v[96:99], v[174:177], v[190:193], v[96:99]
	v_mfma_f32_16x16x32_bf16 v[84:87], v[166:169], v[198:201], v[84:87]
	v_mfma_f32_16x16x32_bf16 v[80:83], v[174:177], v[198:201], v[80:83]
	v_mfma_f32_16x16x32_bf16 v[68:71], v[166:169], v[206:209], v[68:71]
	v_mfma_f32_16x16x32_bf16 v[64:67], v[174:177], v[206:209], v[64:67]
	s_setprio 0
	s_barrier
; #define PG8_STAGE(bufoff, gbase, voff) do { _Pragma("unroll") for (int _i = 0; _i < 2; ++_i) \
;         __builtin_amdgcn_global_load_lds((const unsigned*)((const char*)(gbase) + (BYTE_ELEMS ? _i * r##voff + (v##voff)[0] : (v##voff)[_i])), (PG8_LAS unsigned*)(lds + (bufoff) + ldsw + _i * 8192), 16, 0, 0); } while (0)
; #define PG8_LDA(dst, b, h) do { _Pragma("unroll") for (int m = 0; m < 4; ++m) _Pragma("unroll") for (int k = 0; k < 2; ++k) dst[m][k] = *(const PG8_LAS bf16x8*)(lds + PG8_SA(b, h) + aoff + m * 2048 + k * 1024); } while (0)
; #define PG8_WAIT_V(n) asm volatile("s_waitcnt vmcnt(" #n ")" ::: "memory")
; #define PG8_WAIT_L(n) asm volatile("s_waitcnt lgkmcnt(" #n ")" ::: "memory")
; #define PG8_BAR __builtin_amdgcn_s_barrier()
; #define PG8_SCHED __builtin_amdgcn_sched_barrier(0)
;     ...
;         for (int t = 0; t < nt; t += 2) {
;     ...
;             PG8_LDA(At, 1, 1); PG8_STAGE(PG8_SB(1, 0), b3, offB); PG8_STAGE(PG8_SB(1, 1), b3 + hstepB, offB); PG8_STAGE(PG8_SA(1, 0), a3, offA);
;             PG8_WAIT_V(8); PG8_WAIT_L(0); PG8_BAR; PG8_MMA(1, 0, At, B0); PG8_MMA(1, 1, At, B1); PG8_BAR; PG8_SCHED;
	s_mov_b32 m0, s69
	v_lshl_add_u64 v[210:211], v[210:211], 0, s[42:43]
	s_add_u32 s50, s50, 0x80080
	ds_read_b128 v[178:181], v142 offset:49152
	ds_read_b128 v[182:185], v142 offset:50176
	ds_read_b128 v[186:189], v142 offset:51200
	ds_read_b128 v[190:193], v142 offset:52224
	ds_read_b128 v[194:197], v142 offset:53248
	ds_read_b128 v[198:201], v142 offset:54272
	ds_read_b128 v[202:205], v142 offset:55296
	ds_read_b128 v[206:209], v142 offset:56320
	global_load_lds_dwordx4 v[210:211], off
	v_lshl_add_u64 v[210:211], v[212:213], 0, s[42:43]
	s_mov_b32 m0, s70
	s_addc_u32 s51, s51, 0
	global_load_lds_dwordx4 v[210:211], off
	v_lshl_add_u64 v[210:211], s[50:51], 0, v[130:131]
	s_mov_b32 m0, s71
	s_nop 0
	global_load_lds_dwordx4 v[210:211], off
	v_lshl_add_u64 v[210:211], s[50:51], 0, v[134:135]
	s_mov_b32 m0, s72
	s_nop 0
	global_load_lds_dwordx4 v[210:211], off
	v_lshl_add_u64 v[210:211], v[214:215], 0, s[42:43]
	s_mov_b32 m0, s58
	s_nop 0
	global_load_lds_dwordx4 v[210:211], off
	v_lshl_add_u64 v[210:211], v[216:217], 0, s[42:43]
	s_mov_b32 m0, s59
	s_nop 0
	global_load_lds_dwordx4 v[210:211], off
	s_waitcnt vmcnt(8)
	s_waitcnt lgkmcnt(0)
	s_setprio 1
	s_barrier
	v_mfma_f32_16x16x32_bf16 v[60:63], v[146:149], v[178:181], v[60:63]
	v_mfma_f32_16x16x32_bf16 v[56:59], v[154:157], v[178:181], v[56:59]
	v_mfma_f32_16x16x32_bf16 v[44:47], v[146:149], v[186:189], v[44:47]
	v_mfma_f32_16x16x32_bf16 v[40:43], v[154:157], v[186:189], v[40:43]
	v_mfma_f32_16x16x32_bf16 v[28:31], v[146:149], v[194:197], v[28:31]
	v_mfma_f32_16x16x32_bf16 v[24:27], v[154:157], v[194:197], v[24:27]
	v_mfma_f32_16x16x32_bf16 v[12:15], v[146:149], v[202:205], v[12:15]
	v_mfma_f32_16x16x32_bf16 v[8:11], v[154:157], v[202:205], v[8:11]
	v_mfma_f32_16x16x32_bf16 v[60:63], v[150:153], v[182:185], v[60:63]
	v_mfma_f32_16x16x32_bf16 v[56:59], v[158:161], v[182:185], v[56:59]
	v_mfma_f32_16x16x32_bf16 v[44:47], v[150:153], v[190:193], v[44:47]
	v_mfma_f32_16x16x32_bf16 v[40:43], v[158:161], v[190:193], v[40:43]
	v_mfma_f32_16x16x32_bf16 v[28:31], v[150:153], v[198:201], v[28:31]
	v_mfma_f32_16x16x32_bf16 v[24:27], v[158:161], v[198:201], v[24:27]
	v_mfma_f32_16x16x32_bf16 v[12:15], v[150:153], v[206:209], v[12:15]
	v_mfma_f32_16x16x32_bf16 v[8:11], v[158:161], v[206:209], v[8:11]
	s_setprio 0
	s_setprio 1
	v_mfma_f32_16x16x32_bf16 v[52:55], v[162:165], v[178:181], v[52:55]
	v_mfma_f32_16x16x32_bf16 v[48:51], v[170:173], v[178:181], v[48:51]
	v_mfma_f32_16x16x32_bf16 v[36:39], v[162:165], v[186:189], v[36:39]
	v_mfma_f32_16x16x32_bf16 v[32:35], v[170:173], v[186:189], v[32:35]
	v_mfma_f32_16x16x32_bf16 v[20:23], v[162:165], v[194:197], v[20:23]
	v_mfma_f32_16x16x32_bf16 v[16:19], v[170:173], v[194:197], v[16:19]
	v_mfma_f32_16x16x32_bf16 v[4:7], v[162:165], v[202:205], v[4:7]
	v_mfma_f32_16x16x32_bf16 v[0:3], v[170:173], v[202:205], v[0:3]
	v_mfma_f32_16x16x32_bf16 v[52:55], v[166:169], v[182:185], v[52:55]
	v_mfma_f32_16x16x32_bf16 v[48:51], v[174:177], v[182:185], v[48:51]
	v_mfma_f32_16x16x32_bf16 v[36:39], v[166:169], v[190:193], v[36:39]
	v_mfma_f32_16x16x32_bf16 v[32:35], v[174:177], v[190:193], v[32:35]
	v_mfma_f32_16x16x32_bf16 v[20:23], v[166:169], v[198:201], v[20:23]
	v_mfma_f32_16x16x32_bf16 v[16:19], v[174:177], v[198:201], v[16:19]
	v_mfma_f32_16x16x32_bf16 v[4:7], v[166:169], v[206:209], v[4:7]
	v_mfma_f32_16x16x32_bf16 v[0:3], v[174:177], v[206:209], v[0:3]
	s_setprio 0
	s_barrier
	s_add_i32 s62, s62, 2
	s_add_u32 s46, s46, 0x100
	s_addc_u32 s47, s47, 0
	s_cmp_gt_u32 s62, 29
	s_cbranch_scc0 .LBB0_707
	s_cmpk_lt_u32 s3, 0x100
	s_cbranch_scc0 .LBB0_710
	s_barrier

; __device__ __forceinline__ int tid_of(int wv) { int l; asm volatile("v_mbcnt_lo_u32_b32 %0, -1, 0\n\tv_mbcnt_hi_u32_b32 %0, -1, %0" : "=v"(l)); return wv * 64 + l; }
; #define PG8_STAGE(bufoff, gbase, voff) do { _Pragma("unroll") for (int _i = 0; _i < 2; ++_i) \
;         __builtin_amdgcn_global_load_lds((const unsigned*)((const char*)(gbase) + (BYTE_ELEMS ? _i * r##voff + (v##voff)[0] : (v##voff)[_i])), (PG8_LAS unsigned*)(lds + (bufoff) + ldsw + _i * 8192), 16, 0, 0); } while (0)
; #define PG8_WAIT_V(n) asm volatile("s_waitcnt vmcnt(" #n ")" ::: "memory")
;     ...
;         const bool has_next = S.next(ui + 1, nxt);
;         const char* nA = has_next ? (const char*)g.A + (size_t)nxt.pm * tstepA : cA; const char* nB = has_next ? (const char*)g.Bt + (size_t)nxt.pn * tstepB : cB;
;         for (int t = 0; t < nt; t += 2) {
;             const bool last = (t == nt - 2);
;             const char* a1 = cA + (size_t)(t + 1) * kstep;
;             const char* a2 = last ? nA : cA + (size_t)(t + 2) * kstep; const char* b2 = last ? nB : cB + (size_t)(t + 2) * kstep;
;             const char* a3 = a2 + kstep; const char* b3 = b2 + kstep;
;             if (last && has_next) S.a_ready(nxt);
;             if constexpr (MID) { if (t == nt / 2) { const int t3 = tid_of(wv); E.mid(acc, cur, wid >> 2, t3 & 15); } }
;             if constexpr (SP2) {
;             PG8_LDB(B0, 0, 0); PG8_LDB(B1, 0, 1); PG8_SCHED; PG8_LDA(At, 0, 0); PG8_STAGE(PG8_SA(1, 1), a1 + hstepA, offA);
;             PG8_WAIT_V(8); PG8_WAIT_L(0); PG8_BAR; PG8_MMA(0, 0, At, B0); PG8_MMA(0, 1, At, B1); PG8_BAR; PG8_SCHED;
;             PG8_LDA(At, 0, 1); PG8_STAGE(PG8_SB(0, 0), b2, offB); PG8_STAGE(PG8_SB(0, 1), b2 + hstepB, offB); PG8_STAGE(PG8_SA(0, 0), a2, offA);
;             PG8_WAIT_V(8); PG8_WAIT_L(0); PG8_BAR; PG8_MMA(1, 0, At, B0); PG8_MMA(1, 1, At, B1); PG8_BAR; PG8_SCHED;
;             PG8_LDB(B0, 1, 0); PG8_LDB(B1, 1, 1); PG8_SCHED; PG8_LDA(At, 1, 0); PG8_STAGE(PG8_SA(0, 1), a2 + hstepA, offA);
;             PG8_WAIT_V(8); PG8_WAIT_L(0); PG8_BAR; PG8_MMA(0, 0, At, B0); PG8_MMA(0, 1, At, B1); PG8_BAR; PG8_SCHED;
;             PG8_LDA(At, 1, 1); PG8_STAGE(PG8_SB(1, 0), b3, offB); PG8_STAGE(PG8_SB(1, 1), b3 + hstepB, offB); PG8_STAGE(PG8_SA(1, 0), a3, offA);
;             PG8_WAIT_V(8); PG8_WAIT_L(0); PG8_BAR; PG8_MMA(1, 0, At, B0); PG8_MMA(1, 1, At, B1); PG8_BAR; PG8_SCHED;
.LBB0_886:
	ds_read_b128 v[144:147], v157
	ds_read_b128 v[148:151], v157 offset:1024
	ds_read_b128 v[152:155], v157 offset:2048
	ds_read_b128 v[162:165], v157 offset:3072
	ds_read_b128 v[166:169], v158
	ds_read_b128 v[170:173], v158 offset:1024
	ds_read_b128 v[174:177], v158 offset:2048
	ds_read_b128 v[178:181], v158 offset:3072
	s_add_u32 s54, s4, 0xfff30080
	s_addc_u32 s55, s5, -1
	s_cmp_eq_u32 s92, 4
	s_cselect_b32 s57, s51, s55
	s_cselect_b32 s56, s50, s54
	s_cselect_b32 s55, s3, s91
	s_cselect_b32 s54, s47, s90
	v_lshl_add_u64 v[214:215], s[4:5], 0, v[138:139]
	s_add_i32 m0, s59, 0xc000
	ds_read_b128 v[182:185], v159
	ds_read_b128 v[186:189], v159 offset:1024
	ds_read_b128 v[190:193], v159 offset:2048
	ds_read_b128 v[194:197], v159 offset:3072
	ds_read_b128 v[198:201], v159 offset:4096
	ds_read_b128 v[202:205], v159 offset:5120
	ds_read_b128 v[206:209], v159 offset:6144
	ds_read_b128 v[210:213], v159 offset:7168
	global_load_lds_dwordx4 v[214:215], off
	v_lshl_add_u64 v[214:215], s[4:5], 0, v[140:141]
	s_add_i32 m0, s59, 0xe000
	s_nop 0
	global_load_lds_dwordx4 v[214:215], off
	s_waitcnt vmcnt(8)
	s_waitcnt lgkmcnt(0)
	s_setprio 1
	s_barrier
	v_mfma_f32_16x16x32_bf16 v[124:127], v[144:147], v[182:185], v[124:127]
	v_mfma_f32_16x16x32_bf16 v[120:123], v[152:155], v[182:185], v[120:123]
	v_mfma_f32_16x16x32_bf16 v[108:111], v[144:147], v[190:193], v[108:111]
	v_mfma_f32_16x16x32_bf16 v[104:107], v[152:155], v[190:193], v[104:107]
	v_mfma_f32_16x16x32_bf16 v[92:95], v[144:147], v[198:201], v[92:95]
	v_mfma_f32_16x16x32_bf16 v[88:91], v[152:155], v[198:201], v[88:91]
	v_mfma_f32_16x16x32_bf16 v[76:79], v[144:147], v[206:209], v[76:79]
	v_mfma_f32_16x16x32_bf16 v[72:75], v[152:155], v[206:209], v[72:75]
	v_mfma_f32_16x16x32_bf16 v[124:127], v[148:151], v[186:189], v[124:127]
	v_mfma_f32_16x16x32_bf16 v[120:123], v[162:165], v[186:189], v[120:123]
	v_mfma_f32_16x16x32_bf16 v[108:111], v[148:151], v[194:197], v[108:111]
	v_mfma_f32_16x16x32_bf16 v[104:107], v[162:165], v[194:197], v[104:107]
	v_mfma_f32_16x16x32_bf16 v[92:95], v[148:151], v[202:205], v[92:95]
	v_mfma_f32_16x16x32_bf16 v[88:91], v[162:165], v[202:205], v[88:91]
	v_mfma_f32_16x16x32_bf16 v[76:79], v[148:151], v[210:213], v[76:79]
	v_mfma_f32_16x16x32_bf16 v[72:75], v[162:165], v[210:213], v[72:75]
	s_setprio 0
	s_setprio 1
	v_mfma_f32_16x16x32_bf16 v[116:119], v[166:169], v[182:185], v[116:119]
	v_mfma_f32_16x16x32_bf16 v[112:115], v[174:177], v[182:185], v[112:115]
	v_mfma_f32_16x16x32_bf16 v[100:103], v[166:169], v[190:193], v[100:103]
	v_mfma_f32_16x16x32_bf16 v[96:99], v[174:177], v[190:193], v[96:99]
	v_mfma_f32_16x16x32_bf16 v[84:87], v[166:169], v[198:201], v[84:87]
	v_mfma_f32_16x16x32_bf16 v[80:83], v[174:177], v[198:201], v[80:83]
	v_mfma_f32_16x16x32_bf16 v[68:71], v[166:169], v[206:209], v[68:71]
	v_mfma_f32_16x16x32_bf16 v[64:67], v[174:177], v[206:209], v[64:67]
	v_mfma_f32_16x16x32_bf16 v[116:119], v[170:173], v[186:189], v[116:119]
	v_mfma_f32_16x16x32_bf16 v[112:115], v[178:181], v[186:189], v[112:115]
	v_mfma_f32_16x16x32_bf16 v[100:103], v[170:173], v[194:197], v[100:103]
	v_mfma_f32_16x16x32_bf16 v[96:99], v[178:181], v[194:197], v[96:99]
	v_mfma_f32_16x16x32_bf16 v[84:87], v[170:173], v[202:205], v[84:87]
	v_mfma_f32_16x16x32_bf16 v[80:83], v[178:181], v[202:205], v[80:83]
	v_mfma_f32_16x16x32_bf16 v[68:71], v[170:173], v[210:213], v[68:71]
	v_mfma_f32_16x16x32_bf16 v[64:67], v[178:181], v[210:213], v[64:67]
	s_setprio 0
	s_barrier
	s_add_i32 s93, s76, s58
	v_lshl_add_u64 v[214:215], s[54:55], 0, v[130:131]
	s_mov_b32 m0, s93
	ds_read_b128 v[182:185], v159 offset:16384
	ds_read_b128 v[186:189], v159 offset:17408
	ds_read_b128 v[190:193], v159 offset:18432
	ds_read_b128 v[194:197], v159 offset:19456
	ds_read_b128 v[198:201], v159 offset:20480
	ds_read_b128 v[202:205], v159 offset:21504
	ds_read_b128 v[206:209], v159 offset:22528
	ds_read_b128 v[210:213], v159 offset:23552
	global_load_lds_dwordx4 v[214:215], off
	s_add_i32 m0, s93, 0x2000
	s_add_u32 s94, s54, 0x20000
	v_lshl_add_u64 v[216:217], s[54:55], 0, v[134:135]
	s_addc_u32 s95, s55, 0
	s_add_i32 s93, s77, s58
	global_load_lds_dwordx4 v[216:217], off
	v_lshl_add_u64 v[218:219], s[94:95], 0, v[130:131]
	s_mov_b32 m0, s93
	v_lshl_add_u64 v[220:221], s[56:57], 0, v[132:133]
	global_load_lds_dwordx4 v[218:219], off
	v_lshl_add_u64 v[218:219], s[94:95], 0, v[134:135]
	s_add_i32 m0, s93, 0x2000
	s_nop 0
	global_load_lds_dwordx4 v[218:219], off
	v_lshl_add_u64 v[218:219], s[56:57], 0, v[128:129]
	s_mov_b32 m0, s59
	s_nop 0
	global_load_lds_dwordx4 v[218:219], off
	s_mov_b32 m0, s60
	s_nop 0
	global_load_lds_dwordx4 v[220:221], off
	s_waitcnt vmcnt(8)
	s_waitcnt lgkmcnt(0)
	s_setprio 1
	s_barrier
; #define PG8_STAGE(bufoff, gbase, voff) do { _Pragma("unroll") for (int _i = 0; _i < 2; ++_i) \
;         __builtin_amdgcn_global_load_lds((const unsigned*)((const char*)(gbase) + (BYTE_ELEMS ? _i * r##voff + (v##voff)[0] : (v##voff)[_i])), (PG8_LAS unsigned*)(lds + (bufoff) + ldsw + _i * 8192), 16, 0, 0); } while (0)
; #define PG8_LDA(dst, b, h) do { _Pragma("unroll") for (int m = 0; m < 4; ++m) _Pragma("unroll") for (int k = 0; k < 2; ++k) dst[m][k] = *(const PG8_LAS bf16x8*)(lds + PG8_SA(b, h) + aoff + m * 2048 + k * 1024); } while (0)
; #define PG8_LDB(dst, b, h) do { _Pragma("unroll") for (int n = 0; n < 2; ++n) _Pragma("unroll") for (int k = 0; k < 2; ++k) dst[n][k] = *(const PG8_LAS bf16x8*)(lds + PG8_SB(b, h) + boff + n * 2048 + k * 1024); } while (0)
; #define PG8_WAIT_V(n) asm volatile("s_waitcnt vmcnt(" #n ")" ::: "memory")
; #define PG8_WAIT_L(n) asm volatile("s_waitcnt lgkmcnt(" #n ")" ::: "memory")
; #define PG8_BAR __builtin_amdgcn_s_barrier()
; #define PG8_SCHED __builtin_amdgcn_sched_barrier(0)
;     ...
;             PG8_LDB(B0, 0, 0); PG8_LDB(B1, 0, 1); PG8_SCHED; PG8_LDA(At, 0, 0); PG8_STAGE(PG8_SA(1, 1), a1 + hstepA, offA);
;             PG8_WAIT_V(8); PG8_WAIT_L(0); PG8_BAR; PG8_MMA(0, 0, At, B0); PG8_MMA(0, 1, At, B1); PG8_BAR; PG8_SCHED;
;             PG8_LDA(At, 0, 1); PG8_STAGE(PG8_SB(0, 0), b2, offB); PG8_STAGE(PG8_SB(0, 1), b2 + hstepB, offB); PG8_STAGE(PG8_SA(0, 0), a2, offA);
;             PG8_WAIT_V(8); PG8_WAIT_L(0); PG8_BAR; PG8_MMA(1, 0, At, B0); PG8_MMA(1, 1, At, B1); PG8_BAR; PG8_SCHED;
;             PG8_LDB(B0, 1, 0); PG8_LDB(B1, 1, 1); PG8_SCHED; PG8_LDA(At, 1, 0); PG8_STAGE(PG8_SA(0, 1), a2 + hstepA, offA);
;             PG8_WAIT_V(8); PG8_WAIT_L(0); PG8_BAR; PG8_MMA(0, 0, At, B0); PG8_MMA(0, 1, At, B1); PG8_BAR; PG8_SCHED;
;             PG8_LDA(At, 1, 1); PG8_STAGE(PG8_SB(1, 0), b3, offB); PG8_STAGE(PG8_SB(1, 1), b3 + hstepB, offB); PG8_STAGE(PG8_SA(1, 0), a3, offA);
;             PG8_WAIT_V(8); PG8_WAIT_L(0); PG8_BAR; PG8_MMA(1, 0, At, B0); PG8_MMA(1, 1, At, B1); PG8_BAR; PG8_SCHED;
	v_mfma_f32_16x16x32_bf16 v[60:63], v[144:147], v[182:185], v[60:63]
	v_mfma_f32_16x16x32_bf16 v[56:59], v[152:155], v[182:185], v[56:59]
	v_mfma_f32_16x16x32_bf16 v[44:47], v[144:147], v[190:193], v[44:47]
	v_mfma_f32_16x16x32_bf16 v[40:43], v[152:155], v[190:193], v[40:43]
	v_mfma_f32_16x16x32_bf16 v[28:31], v[144:147], v[198:201], v[28:31]
	v_mfma_f32_16x16x32_bf16 v[24:27], v[152:155], v[198:201], v[24:27]
	v_mfma_f32_16x16x32_bf16 v[12:15], v[144:147], v[206:209], v[12:15]
	v_mfma_f32_16x16x32_bf16 v[8:11], v[152:155], v[206:209], v[8:11]
	v_mfma_f32_16x16x32_bf16 v[60:63], v[148:151], v[186:189], v[60:63]
	v_mfma_f32_16x16x32_bf16 v[56:59], v[162:165], v[186:189], v[56:59]
	v_mfma_f32_16x16x32_bf16 v[44:47], v[148:151], v[194:197], v[44:47]
	v_mfma_f32_16x16x32_bf16 v[40:43], v[162:165], v[194:197], v[40:43]
	v_mfma_f32_16x16x32_bf16 v[28:31], v[148:151], v[202:205], v[28:31]
	v_mfma_f32_16x16x32_bf16 v[24:27], v[162:165], v[202:205], v[24:27]
	v_mfma_f32_16x16x32_bf16 v[12:15], v[148:151], v[210:213], v[12:15]
	v_mfma_f32_16x16x32_bf16 v[8:11], v[162:165], v[210:213], v[8:11]
	s_setprio 0
	s_setprio 1
	v_mfma_f32_16x16x32_bf16 v[52:55], v[166:169], v[182:185], v[52:55]
	v_mfma_f32_16x16x32_bf16 v[48:51], v[174:177], v[182:185], v[48:51]
	v_mfma_f32_16x16x32_bf16 v[36:39], v[166:169], v[190:193], v[36:39]
	v_mfma_f32_16x16x32_bf16 v[32:35], v[174:177], v[190:193], v[32:35]
	v_mfma_f32_16x16x32_bf16 v[20:23], v[166:169], v[198:201], v[20:23]
	v_mfma_f32_16x16x32_bf16 v[16:19], v[174:177], v[198:201], v[16:19]
	v_mfma_f32_16x16x32_bf16 v[4:7], v[166:169], v[206:209], v[4:7]
	v_mfma_f32_16x16x32_bf16 v[0:3], v[174:177], v[206:209], v[0:3]
	v_mfma_f32_16x16x32_bf16 v[52:55], v[170:173], v[186:189], v[52:55]
	v_mfma_f32_16x16x32_bf16 v[48:51], v[178:181], v[186:189], v[48:51]
	v_mfma_f32_16x16x32_bf16 v[36:39], v[170:173], v[194:197], v[36:39]
	v_mfma_f32_16x16x32_bf16 v[32:35], v[178:181], v[194:197], v[32:35]
	v_mfma_f32_16x16x32_bf16 v[20:23], v[170:173], v[202:205], v[20:23]
	v_mfma_f32_16x16x32_bf16 v[16:19], v[178:181], v[202:205], v[16:19]
	v_mfma_f32_16x16x32_bf16 v[4:7], v[170:173], v[210:213], v[4:7]
	v_mfma_f32_16x16x32_bf16 v[0:3], v[178:181], v[210:213], v[0:3]
	s_setprio 0
	s_barrier
	s_add_i32 s93, 0, 0x18000
	v_add_u32_e32 v136, s93, v156
	s_add_i32 s94, 0, 0x1c000
	ds_read_b128 v[144:147], v136
	ds_read_b128 v[148:151], v136 offset:1024
	ds_read_b128 v[152:155], v136 offset:2048
	ds_read_b128 v[162:165], v136 offset:3072
	v_add_u32_e32 v136, s94, v156
	ds_read_b128 v[166:169], v136
	ds_read_b128 v[170:173], v136 offset:1024
	ds_read_b128 v[174:177], v136 offset:2048
	ds_read_b128 v[178:181], v136 offset:3072
	s_add_u32 s56, s56, 0xd0000
	s_addc_u32 s57, s57, 0
	s_mov_b32 m0, s61
	v_lshl_add_u64 v[222:223], s[56:57], 0, v[128:129]
	ds_read_b128 v[182:185], v159 offset:32768
	ds_read_b128 v[186:189], v159 offset:33792
	ds_read_b128 v[190:193], v159 offset:34816
	ds_read_b128 v[194:197], v159 offset:35840
	ds_read_b128 v[198:201], v159 offset:36864
	ds_read_b128 v[202:205], v159 offset:37888
	ds_read_b128 v[206:209], v159 offset:38912
	ds_read_b128 v[210:213], v159 offset:39936
	global_load_lds_dwordx4 v[222:223], off
	v_lshl_add_u64 v[222:223], s[56:57], 0, v[132:133]
	s_mov_b32 m0, s62
	s_nop 0
	global_load_lds_dwordx4 v[222:223], off
	s_waitcnt vmcnt(8)
	s_waitcnt lgkmcnt(0)
	s_setprio 1
	s_barrier
	v_mfma_f32_16x16x32_bf16 v[124:127], v[144:147], v[182:185], v[124:127]
	v_mfma_f32_16x16x32_bf16 v[120:123], v[152:155], v[182:185], v[120:123]
	v_mfma_f32_16x16x32_bf16 v[108:111], v[144:147], v[190:193], v[108:111]
	v_mfma_f32_16x16x32_bf16 v[104:107], v[152:155], v[190:193], v[104:107]
	v_mfma_f32_16x16x32_bf16 v[92:95], v[144:147], v[198:201], v[92:95]
	v_mfma_f32_16x16x32_bf16 v[88:91], v[152:155], v[198:201], v[88:91]
	v_mfma_f32_16x16x32_bf16 v[76:79], v[144:147], v[206:209], v[76:79]
	v_mfma_f32_16x16x32_bf16 v[72:75], v[152:155], v[206:209], v[72:75]
	v_mfma_f32_16x16x32_bf16 v[124:127], v[148:151], v[186:189], v[124:127]
	v_mfma_f32_16x16x32_bf16 v[120:123], v[162:165], v[186:189], v[120:123]
	v_mfma_f32_16x16x32_bf16 v[108:111], v[148:151], v[194:197], v[108:111]
	v_mfma_f32_16x16x32_bf16 v[104:107], v[162:165], v[194:197], v[104:107]
	v_mfma_f32_16x16x32_bf16 v[92:95], v[148:151], v[202:205], v[92:95]
	v_mfma_f32_16x16x32_bf16 v[88:91], v[162:165], v[202:205], v[88:91]
	v_mfma_f32_16x16x32_bf16 v[76:79], v[148:151], v[210:213], v[76:79]
	v_mfma_f32_16x16x32_bf16 v[72:75], v[162:165], v[210:213], v[72:75]
	s_setprio 0
	s_setprio 1
	v_mfma_f32_16x16x32_bf16 v[116:119], v[166:169], v[182:185], v[116:119]
	v_mfma_f32_16x16x32_bf16 v[112:115], v[174:177], v[182:185], v[112:115]
	v_mfma_f32_16x16x32_bf16 v[100:103], v[166:169], v[190:193], v[100:103]
	v_mfma_f32_16x16x32_bf16 v[96:99], v[174:177], v[190:193], v[96:99]
	v_mfma_f32_16x16x32_bf16 v[84:87], v[166:169], v[198:201], v[84:87]
	v_mfma_f32_16x16x32_bf16 v[80:83], v[174:177], v[198:201], v[80:83]
	v_mfma_f32_16x16x32_bf16 v[68:71], v[166:169], v[206:209], v[68:71]
	v_mfma_f32_16x16x32_bf16 v[64:67], v[174:177], v[206:209], v[64:67]
	v_mfma_f32_16x16x32_bf16 v[116:119], v[170:173], v[186:189], v[116:119]
	v_mfma_f32_16x16x32_bf16 v[112:115], v[178:181], v[186:189], v[112:115]
	v_mfma_f32_16x16x32_bf16 v[100:103], v[170:173], v[194:197], v[100:103]
	v_mfma_f32_16x16x32_bf16 v[96:99], v[178:181], v[194:197], v[96:99]
	v_mfma_f32_16x16x32_bf16 v[84:87], v[170:173], v[202:205], v[84:87]
	v_mfma_f32_16x16x32_bf16 v[80:83], v[178:181], v[202:205], v[80:83]
	v_mfma_f32_16x16x32_bf16 v[68:71], v[170:173], v[210:213], v[68:71]
	v_mfma_f32_16x16x32_bf16 v[64:67], v[178:181], v[210:213], v[64:67]
	s_setprio 0
	s_barrier
; #define PG8_STAGE(bufoff, gbase, voff) do { _Pragma("unroll") for (int _i = 0; _i < 2; ++_i) \
;         __builtin_amdgcn_global_load_lds((const unsigned*)((const char*)(gbase) + (BYTE_ELEMS ? _i * r##voff + (v##voff)[0] : (v##voff)[_i])), (PG8_LAS unsigned*)(lds + (bufoff) + ldsw + _i * 8192), 16, 0, 0); } while (0)
; #define PG8_LDA(dst, b, h) do { _Pragma("unroll") for (int m = 0; m < 4; ++m) _Pragma("unroll") for (int k = 0; k < 2; ++k) dst[m][k] = *(const PG8_LAS bf16x8*)(lds + PG8_SA(b, h) + aoff + m * 2048 + k * 1024); } while (0)
; #define PG8_WAIT_V(n) asm volatile("s_waitcnt vmcnt(" #n ")" ::: "memory")
; #define PG8_WAIT_L(n) asm volatile("s_waitcnt lgkmcnt(" #n ")" ::: "memory")
; #define PG8_BAR __builtin_amdgcn_s_barrier()
; #define PG8_SCHED __builtin_amdgcn_sched_barrier(0)
;     ...
;         for (int t = 0; t < nt; t += 2) {
;     ...
;             PG8_LDA(At, 1, 1); PG8_STAGE(PG8_SB(1, 0), b3, offB); PG8_STAGE(PG8_SB(1, 1), b3 + hstepB, offB); PG8_STAGE(PG8_SA(1, 0), a3, offA);
;             PG8_WAIT_V(8); PG8_WAIT_L(0); PG8_BAR; PG8_MMA(1, 0, At, B0); PG8_MMA(1, 1, At, B1); PG8_BAR; PG8_SCHED;
	s_add_i32 s56, s93, s58
	v_lshl_add_u64 v[214:215], v[214:215], 0, s[40:41]
	s_mov_b32 m0, s56
	ds_read_b128 v[182:185], v159 offset:49152
	ds_read_b128 v[186:189], v159 offset:50176
	ds_read_b128 v[190:193], v159 offset:51200
	ds_read_b128 v[194:197], v159 offset:52224
	ds_read_b128 v[198:201], v159 offset:53248
	ds_read_b128 v[202:205], v159 offset:54272
	ds_read_b128 v[206:209], v159 offset:55296
	ds_read_b128 v[210:213], v159 offset:56320
	global_load_lds_dwordx4 v[214:215], off
	s_add_i32 m0, s56, 0x2000
	s_add_u32 s54, s54, 0x20080
	v_lshl_add_u64 v[214:215], v[216:217], 0, s[40:41]
	s_addc_u32 s55, s55, 0
	s_add_i32 s56, s94, s58
	global_load_lds_dwordx4 v[214:215], off
	v_lshl_add_u64 v[214:215], s[54:55], 0, v[130:131]
	s_mov_b32 m0, s56
	s_nop 0
	global_load_lds_dwordx4 v[214:215], off
	v_lshl_add_u64 v[214:215], s[54:55], 0, v[134:135]
	s_add_i32 m0, s56, 0x2000
	s_nop 0
	global_load_lds_dwordx4 v[214:215], off
	v_lshl_add_u64 v[214:215], v[218:219], 0, s[40:41]
	s_mov_b32 m0, s68
	s_nop 0
	global_load_lds_dwordx4 v[214:215], off
	v_lshl_add_u64 v[214:215], v[220:221], 0, s[40:41]
	s_mov_b32 m0, s69
	s_nop 0
	global_load_lds_dwordx4 v[214:215], off
	s_waitcnt vmcnt(8)
	s_waitcnt lgkmcnt(0)
	s_setprio 1
	s_barrier
	v_mfma_f32_16x16x32_bf16 v[60:63], v[144:147], v[182:185], v[60:63]
	v_mfma_f32_16x16x32_bf16 v[56:59], v[152:155], v[182:185], v[56:59]
	v_mfma_f32_16x16x32_bf16 v[44:47], v[144:147], v[190:193], v[44:47]
	v_mfma_f32_16x16x32_bf16 v[40:43], v[152:155], v[190:193], v[40:43]
	v_mfma_f32_16x16x32_bf16 v[28:31], v[144:147], v[198:201], v[28:31]
	v_mfma_f32_16x16x32_bf16 v[24:27], v[152:155], v[198:201], v[24:27]
	v_mfma_f32_16x16x32_bf16 v[12:15], v[144:147], v[206:209], v[12:15]
	v_mfma_f32_16x16x32_bf16 v[8:11], v[152:155], v[206:209], v[8:11]
	v_mfma_f32_16x16x32_bf16 v[60:63], v[148:151], v[186:189], v[60:63]
	v_mfma_f32_16x16x32_bf16 v[56:59], v[162:165], v[186:189], v[56:59]
	v_mfma_f32_16x16x32_bf16 v[44:47], v[148:151], v[194:197], v[44:47]
	v_mfma_f32_16x16x32_bf16 v[40:43], v[162:165], v[194:197], v[40:43]
	v_mfma_f32_16x16x32_bf16 v[28:31], v[148:151], v[202:205], v[28:31]
	v_mfma_f32_16x16x32_bf16 v[24:27], v[162:165], v[202:205], v[24:27]
	v_mfma_f32_16x16x32_bf16 v[12:15], v[148:151], v[210:213], v[12:15]
	v_mfma_f32_16x16x32_bf16 v[8:11], v[162:165], v[210:213], v[8:11]
	s_setprio 0
	s_setprio 1
	v_mfma_f32_16x16x32_bf16 v[52:55], v[166:169], v[182:185], v[52:55]
	v_mfma_f32_16x16x32_bf16 v[48:51], v[174:177], v[182:185], v[48:51]
	v_mfma_f32_16x16x32_bf16 v[36:39], v[166:169], v[190:193], v[36:39]
	v_mfma_f32_16x16x32_bf16 v[32:35], v[174:177], v[190:193], v[32:35]
	v_mfma_f32_16x16x32_bf16 v[20:23], v[166:169], v[198:201], v[20:23]
	v_mfma_f32_16x16x32_bf16 v[16:19], v[174:177], v[198:201], v[16:19]
	v_mfma_f32_16x16x32_bf16 v[4:7], v[166:169], v[206:209], v[4:7]
	v_mfma_f32_16x16x32_bf16 v[0:3], v[174:177], v[206:209], v[0:3]
	v_mfma_f32_16x16x32_bf16 v[52:55], v[170:173], v[186:189], v[52:55]
	v_mfma_f32_16x16x32_bf16 v[48:51], v[178:181], v[186:189], v[48:51]
	v_mfma_f32_16x16x32_bf16 v[36:39], v[170:173], v[194:197], v[36:39]
	v_mfma_f32_16x16x32_bf16 v[32:35], v[178:181], v[194:197], v[32:35]
	v_mfma_f32_16x16x32_bf16 v[20:23], v[170:173], v[202:205], v[20:23]
	v_mfma_f32_16x16x32_bf16 v[16:19], v[178:181], v[202:205], v[16:19]
	v_mfma_f32_16x16x32_bf16 v[4:7], v[170:173], v[210:213], v[4:7]
	v_mfma_f32_16x16x32_bf16 v[0:3], v[178:181], v[210:213], v[0:3]
	s_setprio 0
	s_barrier
	s_add_i32 s92, s92, 2
	s_add_u32 s4, s4, 0x100
	s_addc_u32 s5, s5, 0
	s_add_u32 s90, s90, 0x100
	s_addc_u32 s91, s91, 0
	s_cmp_gt_u32 s92, 5
	s_cbranch_scc0 .LBB0_886
	s_and_b64 vcc, exec, s[42:43]
	s_cbranch_vccz .LBB0_889
	s_barrier

; __device__ __forceinline__ int tid_of(int wv) { int l; asm volatile("v_mbcnt_lo_u32_b32 %0, -1, 0\n\tv_mbcnt_hi_u32_b32 %0, -1, %0" : "=v"(l)); return wv * 64 + l; }
; #define PG8_STAGE(bufoff, gbase, voff) do { _Pragma("unroll") for (int _i = 0; _i < 2; ++_i) \
;         __builtin_amdgcn_global_load_lds((const unsigned*)((const char*)(gbase) + (BYTE_ELEMS ? _i * r##voff + (v##voff)[0] : (v##voff)[_i])), (PG8_LAS unsigned*)(lds + (bufoff) + ldsw + _i * 8192), 16, 0, 0); } while (0)
; #define PG8_WAIT_V(n) asm volatile("s_waitcnt vmcnt(" #n ")" ::: "memory")
;     ...
;         const bool has_next = S.next(ui + 1, nxt);
;         const char* nA = has_next ? (const char*)g.A + (size_t)nxt.pm * tstepA : cA; const char* nB = has_next ? (const char*)g.Bt + (size_t)nxt.pn * tstepB : cB;
;         for (int t = 0; t < nt; t += 2) {
;             const bool last = (t == nt - 2);
;             const char* a1 = cA + (size_t)(t + 1) * kstep;
;             const char* a2 = last ? nA : cA + (size_t)(t + 2) * kstep; const char* b2 = last ? nB : cB + (size_t)(t + 2) * kstep;
;             const char* a3 = a2 + kstep; const char* b3 = b2 + kstep;
;             if (last && has_next) S.a_ready(nxt);
;             if constexpr (MID) { if (t == nt / 2) { const int t3 = tid_of(wv); E.mid(acc, cur, wid >> 2, t3 & 15); } }
;             if constexpr (SP2) {
;             PG8_LDB(B0, 0, 0); PG8_LDB(B1, 0, 1); PG8_SCHED; PG8_LDA(At, 0, 0); PG8_STAGE(PG8_SA(1, 1), a1 + hstepA, offA);
;             PG8_WAIT_V(8); PG8_WAIT_L(0); PG8_BAR; PG8_MMA(0, 0, At, B0); PG8_MMA(0, 1, At, B1); PG8_BAR; PG8_SCHED;
;             PG8_LDA(At, 0, 1); PG8_STAGE(PG8_SB(0, 0), b2, offB); PG8_STAGE(PG8_SB(0, 1), b2 + hstepB, offB); PG8_STAGE(PG8_SA(0, 0), a2, offA);
;             PG8_WAIT_V(8); PG8_WAIT_L(0); PG8_BAR; PG8_MMA(1, 0, At, B0); PG8_MMA(1, 1, At, B1); PG8_BAR; PG8_SCHED;
;             PG8_LDB(B0, 1, 0); PG8_LDB(B1, 1, 1); PG8_SCHED; PG8_LDA(At, 1, 0); PG8_STAGE(PG8_SA(0, 1), a2 + hstepA, offA);
;             PG8_WAIT_V(8); PG8_WAIT_L(0); PG8_BAR; PG8_MMA(0, 0, At, B0); PG8_MMA(0, 1, At, B1); PG8_BAR; PG8_SCHED;
;             PG8_LDA(At, 1, 1); PG8_STAGE(PG8_SB(1, 0), b3, offB); PG8_STAGE(PG8_SB(1, 1), b3 + hstepB, offB); PG8_STAGE(PG8_SA(1, 0), a3, offA);
;             PG8_WAIT_V(8); PG8_WAIT_L(0); PG8_BAR; PG8_MMA(1, 0, At, B0); PG8_MMA(1, 1, At, B1); PG8_BAR; PG8_SCHED;
.LBB0_939:
	ds_read_b128 v[144:147], v157
	ds_read_b128 v[148:151], v157 offset:1024
	ds_read_b128 v[152:155], v157 offset:2048
	ds_read_b128 v[162:165], v157 offset:3072
	ds_read_b128 v[166:169], v158
	ds_read_b128 v[170:173], v158 offset:1024
	ds_read_b128 v[174:177], v158 offset:2048
	ds_read_b128 v[178:181], v158 offset:3072
	s_add_u32 s4, s2, 0xfff30080
	s_addc_u32 s5, s3, -1
	s_cmp_eq_u32 s93, 4
	s_cselect_b32 s55, s51, s5
	s_cselect_b32 s54, s50, s4
	s_cselect_b32 s5, s47, s92
	s_cselect_b32 s4, s90, s91
	v_lshl_add_u64 v[214:215], s[2:3], 0, v[138:139]
	s_add_i32 m0, s60, 0xc000
	ds_read_b128 v[182:185], v159
	ds_read_b128 v[186:189], v159 offset:1024
	ds_read_b128 v[190:193], v159 offset:2048
	ds_read_b128 v[194:197], v159 offset:3072
	ds_read_b128 v[198:201], v159 offset:4096
	ds_read_b128 v[202:205], v159 offset:5120
	ds_read_b128 v[206:209], v159 offset:6144
	ds_read_b128 v[210:213], v159 offset:7168
	global_load_lds_dwordx4 v[214:215], off
	v_lshl_add_u64 v[214:215], s[2:3], 0, v[140:141]
	s_add_i32 m0, s60, 0xe000
	s_nop 0
	global_load_lds_dwordx4 v[214:215], off
	s_waitcnt vmcnt(8)
	s_waitcnt lgkmcnt(0)
	s_setprio 1
	s_barrier
	v_mfma_f32_16x16x32_bf16 v[124:127], v[144:147], v[182:185], v[124:127]
	v_mfma_f32_16x16x32_bf16 v[120:123], v[152:155], v[182:185], v[120:123]
	v_mfma_f32_16x16x32_bf16 v[108:111], v[144:147], v[190:193], v[108:111]
	v_mfma_f32_16x16x32_bf16 v[104:107], v[152:155], v[190:193], v[104:107]
	v_mfma_f32_16x16x32_bf16 v[92:95], v[144:147], v[198:201], v[92:95]
	v_mfma_f32_16x16x32_bf16 v[88:91], v[152:155], v[198:201], v[88:91]
	v_mfma_f32_16x16x32_bf16 v[76:79], v[144:147], v[206:209], v[76:79]
	v_mfma_f32_16x16x32_bf16 v[72:75], v[152:155], v[206:209], v[72:75]
	v_mfma_f32_16x16x32_bf16 v[124:127], v[148:151], v[186:189], v[124:127]
	v_mfma_f32_16x16x32_bf16 v[120:123], v[162:165], v[186:189], v[120:123]
	v_mfma_f32_16x16x32_bf16 v[108:111], v[148:151], v[194:197], v[108:111]
	v_mfma_f32_16x16x32_bf16 v[104:107], v[162:165], v[194:197], v[104:107]
	v_mfma_f32_16x16x32_bf16 v[92:95], v[148:151], v[202:205], v[92:95]
	v_mfma_f32_16x16x32_bf16 v[88:91], v[162:165], v[202:205], v[88:91]
	v_mfma_f32_16x16x32_bf16 v[76:79], v[148:151], v[210:213], v[76:79]
	v_mfma_f32_16x16x32_bf16 v[72:75], v[162:165], v[210:213], v[72:75]
	s_setprio 0
	s_setprio 1
	v_mfma_f32_16x16x32_bf16 v[116:119], v[166:169], v[182:185], v[116:119]
	v_mfma_f32_16x16x32_bf16 v[112:115], v[174:177], v[182:185], v[112:115]
	v_mfma_f32_16x16x32_bf16 v[100:103], v[166:169], v[190:193], v[100:103]
	v_mfma_f32_16x16x32_bf16 v[96:99], v[174:177], v[190:193], v[96:99]
	v_mfma_f32_16x16x32_bf16 v[84:87], v[166:169], v[198:201], v[84:87]
	v_mfma_f32_16x16x32_bf16 v[80:83], v[174:177], v[198:201], v[80:83]
	v_mfma_f32_16x16x32_bf16 v[68:71], v[166:169], v[206:209], v[68:71]
	v_mfma_f32_16x16x32_bf16 v[64:67], v[174:177], v[206:209], v[64:67]
	v_mfma_f32_16x16x32_bf16 v[116:119], v[170:173], v[186:189], v[116:119]
	v_mfma_f32_16x16x32_bf16 v[112:115], v[178:181], v[186:189], v[112:115]
	v_mfma_f32_16x16x32_bf16 v[100:103], v[170:173], v[194:197], v[100:103]
	v_mfma_f32_16x16x32_bf16 v[96:99], v[178:181], v[194:197], v[96:99]
	v_mfma_f32_16x16x32_bf16 v[84:87], v[170:173], v[202:205], v[84:87]
	v_mfma_f32_16x16x32_bf16 v[80:83], v[178:181], v[202:205], v[80:83]
	v_mfma_f32_16x16x32_bf16 v[68:71], v[170:173], v[210:213], v[68:71]
	v_mfma_f32_16x16x32_bf16 v[64:67], v[178:181], v[210:213], v[64:67]
	s_setprio 0
	s_barrier
	s_add_i32 s94, s73, s57
	v_lshl_add_u64 v[214:215], s[4:5], 0, v[130:131]
	s_mov_b32 m0, s94
	ds_read_b128 v[182:185], v159 offset:16384
	ds_read_b128 v[186:189], v159 offset:17408
	ds_read_b128 v[190:193], v159 offset:18432
	ds_read_b128 v[194:197], v159 offset:19456
	ds_read_b128 v[198:201], v159 offset:20480
	ds_read_b128 v[202:205], v159 offset:21504
	ds_read_b128 v[206:209], v159 offset:22528
	ds_read_b128 v[210:213], v159 offset:23552
	global_load_lds_dwordx4 v[214:215], off
	s_add_i32 m0, s94, 0x2000
	s_add_u32 s94, s4, 0x20000
	v_lshl_add_u64 v[216:217], s[4:5], 0, v[134:135]
	s_addc_u32 s95, s5, 0
	s_add_i32 s96, s76, s57
	global_load_lds_dwordx4 v[216:217], off
	v_lshl_add_u64 v[218:219], s[94:95], 0, v[130:131]
	s_mov_b32 m0, s96
	v_lshl_add_u64 v[220:221], s[54:55], 0, v[132:133]
	global_load_lds_dwordx4 v[218:219], off
	v_lshl_add_u64 v[218:219], s[94:95], 0, v[134:135]
	s_add_i32 m0, s96, 0x2000
	s_nop 0
	global_load_lds_dwordx4 v[218:219], off
	v_lshl_add_u64 v[218:219], s[54:55], 0, v[128:129]
	s_mov_b32 m0, s60
	s_nop 0
	global_load_lds_dwordx4 v[218:219], off
	s_mov_b32 m0, s61
	s_nop 0
	global_load_lds_dwordx4 v[220:221], off
	s_waitcnt vmcnt(8)
	s_waitcnt lgkmcnt(0)
	s_setprio 1
	s_barrier
; #define PG8_STAGE(bufoff, gbase, voff) do { _Pragma("unroll") for (int _i = 0; _i < 2; ++_i) \
;         __builtin_amdgcn_global_load_lds((const unsigned*)((const char*)(gbase) + (BYTE_ELEMS ? _i * r##voff + (v##voff)[0] : (v##voff)[_i])), (PG8_LAS unsigned*)(lds + (bufoff) + ldsw + _i * 8192), 16, 0, 0); } while (0)
; #define PG8_LDA(dst, b, h) do { _Pragma("unroll") for (int m = 0; m < 4; ++m) _Pragma("unroll") for (int k = 0; k < 2; ++k) dst[m][k] = *(const PG8_LAS bf16x8*)(lds + PG8_SA(b, h) + aoff + m * 2048 + k * 1024); } while (0)
; #define PG8_LDB(dst, b, h) do { _Pragma("unroll") for (int n = 0; n < 2; ++n) _Pragma("unroll") for (int k = 0; k < 2; ++k) dst[n][k] = *(const PG8_LAS bf16x8*)(lds + PG8_SB(b, h) + boff + n * 2048 + k * 1024); } while (0)
; #define PG8_WAIT_V(n) asm volatile("s_waitcnt vmcnt(" #n ")" ::: "memory")
; #define PG8_WAIT_L(n) asm volatile("s_waitcnt lgkmcnt(" #n ")" ::: "memory")
; #define PG8_BAR __builtin_amdgcn_s_barrier()
; #define PG8_SCHED __builtin_amdgcn_sched_barrier(0)
;     ...
;             PG8_LDB(B0, 0, 0); PG8_LDB(B1, 0, 1); PG8_SCHED; PG8_LDA(At, 0, 0); PG8_STAGE(PG8_SA(1, 1), a1 + hstepA, offA);
;             PG8_WAIT_V(8); PG8_WAIT_L(0); PG8_BAR; PG8_MMA(0, 0, At, B0); PG8_MMA(0, 1, At, B1); PG8_BAR; PG8_SCHED;
;             PG8_LDA(At, 0, 1); PG8_STAGE(PG8_SB(0, 0), b2, offB); PG8_STAGE(PG8_SB(0, 1), b2 + hstepB, offB); PG8_STAGE(PG8_SA(0, 0), a2, offA);
;             PG8_WAIT_V(8); PG8_WAIT_L(0); PG8_BAR; PG8_MMA(1, 0, At, B0); PG8_MMA(1, 1, At, B1); PG8_BAR; PG8_SCHED;
;             PG8_LDB(B0, 1, 0); PG8_LDB(B1, 1, 1); PG8_SCHED; PG8_LDA(At, 1, 0); PG8_STAGE(PG8_SA(0, 1), a2 + hstepA, offA);
;             PG8_WAIT_V(8); PG8_WAIT_L(0); PG8_BAR; PG8_MMA(0, 0, At, B0); PG8_MMA(0, 1, At, B1); PG8_BAR; PG8_SCHED;
;             PG8_LDA(At, 1, 1); PG8_STAGE(PG8_SB(1, 0), b3, offB); PG8_STAGE(PG8_SB(1, 1), b3 + hstepB, offB); PG8_STAGE(PG8_SA(1, 0), a3, offA);
;             PG8_WAIT_V(8); PG8_WAIT_L(0); PG8_BAR; PG8_MMA(1, 0, At, B0); PG8_MMA(1, 1, At, B1); PG8_BAR; PG8_SCHED;
	v_mfma_f32_16x16x32_bf16 v[60:63], v[144:147], v[182:185], v[60:63]
	v_mfma_f32_16x16x32_bf16 v[56:59], v[152:155], v[182:185], v[56:59]
	v_mfma_f32_16x16x32_bf16 v[44:47], v[144:147], v[190:193], v[44:47]
	v_mfma_f32_16x16x32_bf16 v[40:43], v[152:155], v[190:193], v[40:43]
	v_mfma_f32_16x16x32_bf16 v[28:31], v[144:147], v[198:201], v[28:31]
	v_mfma_f32_16x16x32_bf16 v[24:27], v[152:155], v[198:201], v[24:27]
	v_mfma_f32_16x16x32_bf16 v[12:15], v[144:147], v[206:209], v[12:15]
	v_mfma_f32_16x16x32_bf16 v[8:11], v[152:155], v[206:209], v[8:11]
	v_mfma_f32_16x16x32_bf16 v[60:63], v[148:151], v[186:189], v[60:63]
	v_mfma_f32_16x16x32_bf16 v[56:59], v[162:165], v[186:189], v[56:59]
	v_mfma_f32_16x16x32_bf16 v[44:47], v[148:151], v[194:197], v[44:47]
	v_mfma_f32_16x16x32_bf16 v[40:43], v[162:165], v[194:197], v[40:43]
	v_mfma_f32_16x16x32_bf16 v[28:31], v[148:151], v[202:205], v[28:31]
	v_mfma_f32_16x16x32_bf16 v[24:27], v[162:165], v[202:205], v[24:27]
	v_mfma_f32_16x16x32_bf16 v[12:15], v[148:151], v[210:213], v[12:15]
	v_mfma_f32_16x16x32_bf16 v[8:11], v[162:165], v[210:213], v[8:11]
	s_setprio 0
	s_setprio 1
	v_mfma_f32_16x16x32_bf16 v[52:55], v[166:169], v[182:185], v[52:55]
	v_mfma_f32_16x16x32_bf16 v[48:51], v[174:177], v[182:185], v[48:51]
	v_mfma_f32_16x16x32_bf16 v[36:39], v[166:169], v[190:193], v[36:39]
	v_mfma_f32_16x16x32_bf16 v[32:35], v[174:177], v[190:193], v[32:35]
	v_mfma_f32_16x16x32_bf16 v[20:23], v[166:169], v[198:201], v[20:23]
	v_mfma_f32_16x16x32_bf16 v[16:19], v[174:177], v[198:201], v[16:19]
	v_mfma_f32_16x16x32_bf16 v[4:7], v[166:169], v[206:209], v[4:7]
	v_mfma_f32_16x16x32_bf16 v[0:3], v[174:177], v[206:209], v[0:3]
	v_mfma_f32_16x16x32_bf16 v[52:55], v[170:173], v[186:189], v[52:55]
	v_mfma_f32_16x16x32_bf16 v[48:51], v[178:181], v[186:189], v[48:51]
	v_mfma_f32_16x16x32_bf16 v[36:39], v[170:173], v[194:197], v[36:39]
	v_mfma_f32_16x16x32_bf16 v[32:35], v[178:181], v[194:197], v[32:35]
	v_mfma_f32_16x16x32_bf16 v[20:23], v[170:173], v[202:205], v[20:23]
	v_mfma_f32_16x16x32_bf16 v[16:19], v[178:181], v[202:205], v[16:19]
	v_mfma_f32_16x16x32_bf16 v[4:7], v[170:173], v[210:213], v[4:7]
	v_mfma_f32_16x16x32_bf16 v[0:3], v[178:181], v[210:213], v[0:3]
	s_setprio 0
	s_barrier
	s_add_i32 s94, 0, 0x18000
	v_add_u32_e32 v136, s94, v156
	s_add_i32 s95, 0, 0x1c000
	ds_read_b128 v[144:147], v136
	ds_read_b128 v[148:151], v136 offset:1024
	ds_read_b128 v[152:155], v136 offset:2048
	ds_read_b128 v[162:165], v136 offset:3072
	v_add_u32_e32 v136, s95, v156
	ds_read_b128 v[166:169], v136
	ds_read_b128 v[170:173], v136 offset:1024
	ds_read_b128 v[174:177], v136 offset:2048
	ds_read_b128 v[178:181], v136 offset:3072
	s_add_u32 s54, s54, 0xd0000
	s_addc_u32 s55, s55, 0
	s_mov_b32 m0, s62
	v_lshl_add_u64 v[222:223], s[54:55], 0, v[128:129]
	ds_read_b128 v[182:185], v159 offset:32768
	ds_read_b128 v[186:189], v159 offset:33792
	ds_read_b128 v[190:193], v159 offset:34816
	ds_read_b128 v[194:197], v159 offset:35840
	ds_read_b128 v[198:201], v159 offset:36864
	ds_read_b128 v[202:205], v159 offset:37888
	ds_read_b128 v[206:209], v159 offset:38912
	ds_read_b128 v[210:213], v159 offset:39936
	global_load_lds_dwordx4 v[222:223], off
	v_lshl_add_u64 v[222:223], s[54:55], 0, v[132:133]
	s_mov_b32 m0, s63
	s_nop 0
	global_load_lds_dwordx4 v[222:223], off
	s_waitcnt vmcnt(8)
	s_waitcnt lgkmcnt(0)
	s_setprio 1
	s_barrier
	v_mfma_f32_16x16x32_bf16 v[124:127], v[144:147], v[182:185], v[124:127]
	v_mfma_f32_16x16x32_bf16 v[120:123], v[152:155], v[182:185], v[120:123]
	v_mfma_f32_16x16x32_bf16 v[108:111], v[144:147], v[190:193], v[108:111]
	v_mfma_f32_16x16x32_bf16 v[104:107], v[152:155], v[190:193], v[104:107]
	v_mfma_f32_16x16x32_bf16 v[92:95], v[144:147], v[198:201], v[92:95]
	v_mfma_f32_16x16x32_bf16 v[88:91], v[152:155], v[198:201], v[88:91]
	v_mfma_f32_16x16x32_bf16 v[76:79], v[144:147], v[206:209], v[76:79]
	v_mfma_f32_16x16x32_bf16 v[72:75], v[152:155], v[206:209], v[72:75]
	v_mfma_f32_16x16x32_bf16 v[124:127], v[148:151], v[186:189], v[124:127]
	v_mfma_f32_16x16x32_bf16 v[120:123], v[162:165], v[186:189], v[120:123]
	v_mfma_f32_16x16x32_bf16 v[108:111], v[148:151], v[194:197], v[108:111]
	v_mfma_f32_16x16x32_bf16 v[104:107], v[162:165], v[194:197], v[104:107]
	v_mfma_f32_16x16x32_bf16 v[92:95], v[148:151], v[202:205], v[92:95]
	v_mfma_f32_16x16x32_bf16 v[88:91], v[162:165], v[202:205], v[88:91]
	v_mfma_f32_16x16x32_bf16 v[76:79], v[148:151], v[210:213], v[76:79]
	v_mfma_f32_16x16x32_bf16 v[72:75], v[162:165], v[210:213], v[72:75]
	s_setprio 0
	s_setprio 1
	v_mfma_f32_16x16x32_bf16 v[116:119], v[166:169], v[182:185], v[116:119]
	v_mfma_f32_16x16x32_bf16 v[112:115], v[174:177], v[182:185], v[112:115]
	v_mfma_f32_16x16x32_bf16 v[100:103], v[166:169], v[190:193], v[100:103]
	v_mfma_f32_16x16x32_bf16 v[96:99], v[174:177], v[190:193], v[96:99]
	v_mfma_f32_16x16x32_bf16 v[84:87], v[166:169], v[198:201], v[84:87]
	v_mfma_f32_16x16x32_bf16 v[80:83], v[174:177], v[198:201], v[80:83]
	v_mfma_f32_16x16x32_bf16 v[68:71], v[166:169], v[206:209], v[68:71]
	v_mfma_f32_16x16x32_bf16 v[64:67], v[174:177], v[206:209], v[64:67]
	v_mfma_f32_16x16x32_bf16 v[116:119], v[170:173], v[186:189], v[116:119]
	v_mfma_f32_16x16x32_bf16 v[112:115], v[178:181], v[186:189], v[112:115]
	v_mfma_f32_16x16x32_bf16 v[100:103], v[170:173], v[194:197], v[100:103]
	v_mfma_f32_16x16x32_bf16 v[96:99], v[178:181], v[194:197], v[96:99]
	v_mfma_f32_16x16x32_bf16 v[84:87], v[170:173], v[202:205], v[84:87]
	v_mfma_f32_16x16x32_bf16 v[80:83], v[178:181], v[202:205], v[80:83]
	v_mfma_f32_16x16x32_bf16 v[68:71], v[170:173], v[210:213], v[68:71]
	v_mfma_f32_16x16x32_bf16 v[64:67], v[178:181], v[210:213], v[64:67]
	s_setprio 0
	s_barrier
; #define PG8_STAGE(bufoff, gbase, voff) do { _Pragma("unroll") for (int _i = 0; _i < 2; ++_i) \
;         __builtin_amdgcn_global_load_lds((const unsigned*)((const char*)(gbase) + (BYTE_ELEMS ? _i * r##voff + (v##voff)[0] : (v##voff)[_i])), (PG8_LAS unsigned*)(lds + (bufoff) + ldsw + _i * 8192), 16, 0, 0); } while (0)
; #define PG8_LDA(dst, b, h) do { _Pragma("unroll") for (int m = 0; m < 4; ++m) _Pragma("unroll") for (int k = 0; k < 2; ++k) dst[m][k] = *(const PG8_LAS bf16x8*)(lds + PG8_SA(b, h) + aoff + m * 2048 + k * 1024); } while (0)
; #define PG8_WAIT_V(n) asm volatile("s_waitcnt vmcnt(" #n ")" ::: "memory")
; #define PG8_WAIT_L(n) asm volatile("s_waitcnt lgkmcnt(" #n ")" ::: "memory")
; #define PG8_BAR __builtin_amdgcn_s_barrier()
; #define PG8_SCHED __builtin_amdgcn_sched_barrier(0)
;     ...
;         for (int t = 0; t < nt; t += 2) {
;     ...
;             PG8_LDA(At, 1, 1); PG8_STAGE(PG8_SB(1, 0), b3, offB); PG8_STAGE(PG8_SB(1, 1), b3 + hstepB, offB); PG8_STAGE(PG8_SA(1, 0), a3, offA);
;             PG8_WAIT_V(8); PG8_WAIT_L(0); PG8_BAR; PG8_MMA(1, 0, At, B0); PG8_MMA(1, 1, At, B1); PG8_BAR; PG8_SCHED;
	s_add_i32 s54, s94, s57
	v_lshl_add_u64 v[214:215], v[214:215], 0, s[40:41]
	s_mov_b32 m0, s54
	ds_read_b128 v[182:185], v159 offset:49152
	ds_read_b128 v[186:189], v159 offset:50176
	ds_read_b128 v[190:193], v159 offset:51200
	ds_read_b128 v[194:197], v159 offset:52224
	ds_read_b128 v[198:201], v159 offset:53248
	ds_read_b128 v[202:205], v159 offset:54272
	ds_read_b128 v[206:209], v159 offset:55296
	ds_read_b128 v[210:213], v159 offset:56320
	global_load_lds_dwordx4 v[214:215], off
	s_add_i32 m0, s54, 0x2000
	s_add_u32 s4, s4, 0x20080
	v_lshl_add_u64 v[214:215], v[216:217], 0, s[40:41]
	s_addc_u32 s5, s5, 0
	s_add_i32 s54, s95, s57
	global_load_lds_dwordx4 v[214:215], off
	v_lshl_add_u64 v[214:215], s[4:5], 0, v[130:131]
	s_mov_b32 m0, s54
	s_nop 0
	global_load_lds_dwordx4 v[214:215], off
	v_lshl_add_u64 v[214:215], s[4:5], 0, v[134:135]
	s_add_i32 m0, s54, 0x2000
	s_nop 0
	global_load_lds_dwordx4 v[214:215], off
	v_lshl_add_u64 v[214:215], v[218:219], 0, s[40:41]
	s_mov_b32 m0, s70
	s_nop 0
	global_load_lds_dwordx4 v[214:215], off
	v_lshl_add_u64 v[214:215], v[220:221], 0, s[40:41]
	s_mov_b32 m0, s71
	s_nop 0
	global_load_lds_dwordx4 v[214:215], off
	s_waitcnt vmcnt(8)
	s_waitcnt lgkmcnt(0)
	s_setprio 1
	s_barrier
	v_mfma_f32_16x16x32_bf16 v[60:63], v[144:147], v[182:185], v[60:63]
	v_mfma_f32_16x16x32_bf16 v[56:59], v[152:155], v[182:185], v[56:59]
	v_mfma_f32_16x16x32_bf16 v[44:47], v[144:147], v[190:193], v[44:47]
	v_mfma_f32_16x16x32_bf16 v[40:43], v[152:155], v[190:193], v[40:43]
	v_mfma_f32_16x16x32_bf16 v[28:31], v[144:147], v[198:201], v[28:31]
	v_mfma_f32_16x16x32_bf16 v[24:27], v[152:155], v[198:201], v[24:27]
	v_mfma_f32_16x16x32_bf16 v[12:15], v[144:147], v[206:209], v[12:15]
	v_mfma_f32_16x16x32_bf16 v[8:11], v[152:155], v[206:209], v[8:11]
	v_mfma_f32_16x16x32_bf16 v[60:63], v[148:151], v[186:189], v[60:63]
	v_mfma_f32_16x16x32_bf16 v[56:59], v[162:165], v[186:189], v[56:59]
	v_mfma_f32_16x16x32_bf16 v[44:47], v[148:151], v[194:197], v[44:47]
	v_mfma_f32_16x16x32_bf16 v[40:43], v[162:165], v[194:197], v[40:43]
	v_mfma_f32_16x16x32_bf16 v[28:31], v[148:151], v[202:205], v[28:31]
	v_mfma_f32_16x16x32_bf16 v[24:27], v[162:165], v[202:205], v[24:27]
	v_mfma_f32_16x16x32_bf16 v[12:15], v[148:151], v[210:213], v[12:15]
	v_mfma_f32_16x16x32_bf16 v[8:11], v[162:165], v[210:213], v[8:11]
	s_setprio 0
	s_setprio 1
	v_mfma_f32_16x16x32_bf16 v[52:55], v[166:169], v[182:185], v[52:55]
	v_mfma_f32_16x16x32_bf16 v[48:51], v[174:177], v[182:185], v[48:51]
	v_mfma_f32_16x16x32_bf16 v[36:39], v[166:169], v[190:193], v[36:39]
	v_mfma_f32_16x16x32_bf16 v[32:35], v[174:177], v[190:193], v[32:35]
	v_mfma_f32_16x16x32_bf16 v[20:23], v[166:169], v[198:201], v[20:23]
	v_mfma_f32_16x16x32_bf16 v[16:19], v[174:177], v[198:201], v[16:19]
	v_mfma_f32_16x16x32_bf16 v[4:7], v[166:169], v[206:209], v[4:7]
	v_mfma_f32_16x16x32_bf16 v[0:3], v[174:177], v[206:209], v[0:3]
	v_mfma_f32_16x16x32_bf16 v[52:55], v[170:173], v[186:189], v[52:55]
	v_mfma_f32_16x16x32_bf16 v[48:51], v[178:181], v[186:189], v[48:51]
	v_mfma_f32_16x16x32_bf16 v[36:39], v[170:173], v[194:197], v[36:39]
	v_mfma_f32_16x16x32_bf16 v[32:35], v[178:181], v[194:197], v[32:35]
	v_mfma_f32_16x16x32_bf16 v[20:23], v[170:173], v[202:205], v[20:23]
	v_mfma_f32_16x16x32_bf16 v[16:19], v[178:181], v[202:205], v[16:19]
	v_mfma_f32_16x16x32_bf16 v[4:7], v[170:173], v[210:213], v[4:7]
	v_mfma_f32_16x16x32_bf16 v[0:3], v[178:181], v[210:213], v[0:3]
	s_setprio 0
	s_barrier
	s_add_i32 s93, s93, 2
	s_add_u32 s2, s2, 0x100
	s_addc_u32 s3, s3, 0
	s_add_u32 s91, s91, 0x100
	s_addc_u32 s92, s92, 0
	s_cmp_gt_u32 s93, 5
	s_cbranch_scc0 .LBB0_939
	s_and_b64 vcc, exec, s[42:43]
	s_cbranch_vccz .LBB0_942
	s_barrier

; __device__ __forceinline__ int tid_of(int wv) { int l; asm volatile("v_mbcnt_lo_u32_b32 %0, -1, 0\n\tv_mbcnt_hi_u32_b32 %0, -1, %0" : "=v"(l)); return wv * 64 + l; }
; #define PG8_STAGE(bufoff, gbase, voff) do { _Pragma("unroll") for (int _i = 0; _i < 2; ++_i) \
;         __builtin_amdgcn_global_load_lds((const unsigned*)((const char*)(gbase) + (BYTE_ELEMS ? _i * r##voff + (v##voff)[0] : (v##voff)[_i])), (PG8_LAS unsigned*)(lds + (bufoff) + ldsw + _i * 8192), 16, 0, 0); } while (0)
; #define PG8_WAIT_V(n) asm volatile("s_waitcnt vmcnt(" #n ")" ::: "memory")
;     ...
;         const bool has_next = S.next(ui + 1, nxt);
;         const char* nA = has_next ? (const char*)g.A + (size_t)nxt.pm * tstepA : cA; const char* nB = has_next ? (const char*)g.Bt + (size_t)nxt.pn * tstepB : cB;
;         for (int t = 0; t < nt; t += 2) {
;             const bool last = (t == nt - 2);
;             const char* a1 = cA + (size_t)(t + 1) * kstep;
;             const char* a2 = last ? nA : cA + (size_t)(t + 2) * kstep; const char* b2 = last ? nB : cB + (size_t)(t + 2) * kstep;
;             const char* a3 = a2 + kstep; const char* b3 = b2 + kstep;
;             if (last && has_next) S.a_ready(nxt);
;             if constexpr (MID) { if (t == nt / 2) { const int t3 = tid_of(wv); E.mid(acc, cur, wid >> 2, t3 & 15); } }
;             if constexpr (SP2) {
;             PG8_LDB(B0, 0, 0); PG8_LDB(B1, 0, 1); PG8_SCHED; PG8_LDA(At, 0, 0); PG8_STAGE(PG8_SA(1, 1), a1 + hstepA, offA);
;             PG8_WAIT_V(8); PG8_WAIT_L(0); PG8_BAR; PG8_MMA(0, 0, At, B0); PG8_MMA(0, 1, At, B1); PG8_BAR; PG8_SCHED;
;             PG8_LDA(At, 0, 1); PG8_STAGE(PG8_SB(0, 0), b2, offB); PG8_STAGE(PG8_SB(0, 1), b2 + hstepB, offB); PG8_STAGE(PG8_SA(0, 0), a2, offA);
;             PG8_WAIT_V(8); PG8_WAIT_L(0); PG8_BAR; PG8_MMA(1, 0, At, B0); PG8_MMA(1, 1, At, B1); PG8_BAR; PG8_SCHED;
;             PG8_LDB(B0, 1, 0); PG8_LDB(B1, 1, 1); PG8_SCHED; PG8_LDA(At, 1, 0); PG8_STAGE(PG8_SA(0, 1), a2 + hstepA, offA);
;             PG8_WAIT_V(8); PG8_WAIT_L(0); PG8_BAR; PG8_MMA(0, 0, At, B0); PG8_MMA(0, 1, At, B1); PG8_BAR; PG8_SCHED;
;             PG8_LDA(At, 1, 1); PG8_STAGE(PG8_SB(1, 0), b3, offB); PG8_STAGE(PG8_SB(1, 1), b3 + hstepB, offB); PG8_STAGE(PG8_SA(1, 0), a3, offA);
;             PG8_WAIT_V(8); PG8_WAIT_L(0); PG8_BAR; PG8_MMA(1, 0, At, B0); PG8_MMA(1, 1, At, B1); PG8_BAR; PG8_SCHED;
.LBB0_993:
	ds_read_b128 v[142:145], v155
	ds_read_b128 v[146:149], v155 offset:1024
	ds_read_b128 v[150:153], v155 offset:2048
	ds_read_b128 v[160:163], v155 offset:3072
	ds_read_b128 v[164:167], v156
	ds_read_b128 v[168:171], v156 offset:1024
	ds_read_b128 v[172:175], v156 offset:2048
	ds_read_b128 v[176:179], v156 offset:3072
	s_add_u32 s54, s4, 0xfff30080
	s_addc_u32 s55, s5, -1
	s_cmp_eq_u32 s91, 4
	s_cselect_b32 s57, s51, s55
	s_cselect_b32 s56, s50, s54
	s_cselect_b32 s55, s3, s90
	s_cselect_b32 s54, s47, s89
	v_lshl_add_u64 v[212:213], s[4:5], 0, v[138:139]
	s_add_i32 m0, s60, 0xc000
	ds_read_b128 v[180:183], v157
	ds_read_b128 v[184:187], v157 offset:1024
	ds_read_b128 v[188:191], v157 offset:2048
	ds_read_b128 v[192:195], v157 offset:3072
	ds_read_b128 v[196:199], v157 offset:4096
	ds_read_b128 v[200:203], v157 offset:5120
	ds_read_b128 v[204:207], v157 offset:6144
	ds_read_b128 v[208:211], v157 offset:7168
	global_load_lds_dwordx4 v[212:213], off
	v_lshl_add_u64 v[212:213], s[4:5], 0, v[140:141]
	s_add_i32 m0, s60, 0xe000
	s_nop 0
	global_load_lds_dwordx4 v[212:213], off
	s_waitcnt vmcnt(8)
	s_waitcnt lgkmcnt(0)
	s_setprio 1
	s_barrier
	v_mfma_f32_16x16x32_bf16 v[124:127], v[142:145], v[180:183], v[124:127]
	v_mfma_f32_16x16x32_bf16 v[120:123], v[150:153], v[180:183], v[120:123]
	v_mfma_f32_16x16x32_bf16 v[108:111], v[142:145], v[188:191], v[108:111]
	v_mfma_f32_16x16x32_bf16 v[104:107], v[150:153], v[188:191], v[104:107]
	v_mfma_f32_16x16x32_bf16 v[92:95], v[142:145], v[196:199], v[92:95]
	v_mfma_f32_16x16x32_bf16 v[88:91], v[150:153], v[196:199], v[88:91]
	v_mfma_f32_16x16x32_bf16 v[76:79], v[142:145], v[204:207], v[76:79]
	v_mfma_f32_16x16x32_bf16 v[72:75], v[150:153], v[204:207], v[72:75]
	v_mfma_f32_16x16x32_bf16 v[124:127], v[146:149], v[184:187], v[124:127]
	v_mfma_f32_16x16x32_bf16 v[120:123], v[160:163], v[184:187], v[120:123]
	v_mfma_f32_16x16x32_bf16 v[108:111], v[146:149], v[192:195], v[108:111]
	v_mfma_f32_16x16x32_bf16 v[104:107], v[160:163], v[192:195], v[104:107]
	v_mfma_f32_16x16x32_bf16 v[92:95], v[146:149], v[200:203], v[92:95]
	v_mfma_f32_16x16x32_bf16 v[88:91], v[160:163], v[200:203], v[88:91]
	v_mfma_f32_16x16x32_bf16 v[76:79], v[146:149], v[208:211], v[76:79]
	v_mfma_f32_16x16x32_bf16 v[72:75], v[160:163], v[208:211], v[72:75]
	s_setprio 0
	s_setprio 1
	v_mfma_f32_16x16x32_bf16 v[116:119], v[164:167], v[180:183], v[116:119]
	v_mfma_f32_16x16x32_bf16 v[112:115], v[172:175], v[180:183], v[112:115]
	v_mfma_f32_16x16x32_bf16 v[100:103], v[164:167], v[188:191], v[100:103]
	v_mfma_f32_16x16x32_bf16 v[96:99], v[172:175], v[188:191], v[96:99]
	v_mfma_f32_16x16x32_bf16 v[84:87], v[164:167], v[196:199], v[84:87]
	v_mfma_f32_16x16x32_bf16 v[80:83], v[172:175], v[196:199], v[80:83]
	v_mfma_f32_16x16x32_bf16 v[68:71], v[164:167], v[204:207], v[68:71]
	v_mfma_f32_16x16x32_bf16 v[64:67], v[172:175], v[204:207], v[64:67]
	v_mfma_f32_16x16x32_bf16 v[116:119], v[168:171], v[184:187], v[116:119]
	v_mfma_f32_16x16x32_bf16 v[112:115], v[176:179], v[184:187], v[112:115]
	v_mfma_f32_16x16x32_bf16 v[100:103], v[168:171], v[192:195], v[100:103]
	v_mfma_f32_16x16x32_bf16 v[96:99], v[176:179], v[192:195], v[96:99]
	v_mfma_f32_16x16x32_bf16 v[84:87], v[168:171], v[200:203], v[84:87]
	v_mfma_f32_16x16x32_bf16 v[80:83], v[176:179], v[200:203], v[80:83]
	v_mfma_f32_16x16x32_bf16 v[68:71], v[168:171], v[208:211], v[68:71]
	v_mfma_f32_16x16x32_bf16 v[64:67], v[176:179], v[208:211], v[64:67]
	s_setprio 0
	s_barrier
	s_add_i32 s92, s72, s59
	v_lshl_add_u64 v[212:213], s[54:55], 0, v[130:131]
	s_mov_b32 m0, s92
	ds_read_b128 v[180:183], v157 offset:16384
	ds_read_b128 v[184:187], v157 offset:17408
	ds_read_b128 v[188:191], v157 offset:18432
	ds_read_b128 v[192:195], v157 offset:19456
	ds_read_b128 v[196:199], v157 offset:20480
	ds_read_b128 v[200:203], v157 offset:21504
	ds_read_b128 v[204:207], v157 offset:22528
	ds_read_b128 v[208:211], v157 offset:23552
	global_load_lds_dwordx4 v[212:213], off
	s_add_i32 m0, s92, 0x2000
	s_add_u32 s92, s54, 0x20000
	v_lshl_add_u64 v[214:215], s[54:55], 0, v[134:135]
	s_addc_u32 s93, s55, 0
	s_add_i32 s94, s73, s59
	global_load_lds_dwordx4 v[214:215], off
	v_lshl_add_u64 v[216:217], s[92:93], 0, v[130:131]
	s_mov_b32 m0, s94
	v_lshl_add_u64 v[218:219], s[56:57], 0, v[132:133]
	global_load_lds_dwordx4 v[216:217], off
	v_lshl_add_u64 v[216:217], s[92:93], 0, v[134:135]
	s_add_i32 m0, s94, 0x2000
	s_nop 0
	global_load_lds_dwordx4 v[216:217], off
	v_lshl_add_u64 v[216:217], s[56:57], 0, v[128:129]
	s_mov_b32 m0, s60
	s_nop 0
	global_load_lds_dwordx4 v[216:217], off
	s_mov_b32 m0, s61
	s_nop 0
	global_load_lds_dwordx4 v[218:219], off
	s_waitcnt vmcnt(8)
	s_waitcnt lgkmcnt(0)
	s_setprio 1
	s_barrier
; #define PG8_STAGE(bufoff, gbase, voff) do { _Pragma("unroll") for (int _i = 0; _i < 2; ++_i) \
;         __builtin_amdgcn_global_load_lds((const unsigned*)((const char*)(gbase) + (BYTE_ELEMS ? _i * r##voff + (v##voff)[0] : (v##voff)[_i])), (PG8_LAS unsigned*)(lds + (bufoff) + ldsw + _i * 8192), 16, 0, 0); } while (0)
; #define PG8_LDA(dst, b, h) do { _Pragma("unroll") for (int m = 0; m < 4; ++m) _Pragma("unroll") for (int k = 0; k < 2; ++k) dst[m][k] = *(const PG8_LAS bf16x8*)(lds + PG8_SA(b, h) + aoff + m * 2048 + k * 1024); } while (0)
; #define PG8_LDB(dst, b, h) do { _Pragma("unroll") for (int n = 0; n < 2; ++n) _Pragma("unroll") for (int k = 0; k < 2; ++k) dst[n][k] = *(const PG8_LAS bf16x8*)(lds + PG8_SB(b, h) + boff + n * 2048 + k * 1024); } while (0)
; #define PG8_WAIT_V(n) asm volatile("s_waitcnt vmcnt(" #n ")" ::: "memory")
; #define PG8_WAIT_L(n) asm volatile("s_waitcnt lgkmcnt(" #n ")" ::: "memory")
; #define PG8_BAR __builtin_amdgcn_s_barrier()
; #define PG8_SCHED __builtin_amdgcn_sched_barrier(0)
;     ...
;             PG8_LDB(B0, 0, 0); PG8_LDB(B1, 0, 1); PG8_SCHED; PG8_LDA(At, 0, 0); PG8_STAGE(PG8_SA(1, 1), a1 + hstepA, offA);
;             PG8_WAIT_V(8); PG8_WAIT_L(0); PG8_BAR; PG8_MMA(0, 0, At, B0); PG8_MMA(0, 1, At, B1); PG8_BAR; PG8_SCHED;
;             PG8_LDA(At, 0, 1); PG8_STAGE(PG8_SB(0, 0), b2, offB); PG8_STAGE(PG8_SB(0, 1), b2 + hstepB, offB); PG8_STAGE(PG8_SA(0, 0), a2, offA);
;             PG8_WAIT_V(8); PG8_WAIT_L(0); PG8_BAR; PG8_MMA(1, 0, At, B0); PG8_MMA(1, 1, At, B1); PG8_BAR; PG8_SCHED;
;             PG8_LDB(B0, 1, 0); PG8_LDB(B1, 1, 1); PG8_SCHED; PG8_LDA(At, 1, 0); PG8_STAGE(PG8_SA(0, 1), a2 + hstepA, offA);
;             PG8_WAIT_V(8); PG8_WAIT_L(0); PG8_BAR; PG8_MMA(0, 0, At, B0); PG8_MMA(0, 1, At, B1); PG8_BAR; PG8_SCHED;
;             PG8_LDA(At, 1, 1); PG8_STAGE(PG8_SB(1, 0), b3, offB); PG8_STAGE(PG8_SB(1, 1), b3 + hstepB, offB); PG8_STAGE(PG8_SA(1, 0), a3, offA);
;             PG8_WAIT_V(8); PG8_WAIT_L(0); PG8_BAR; PG8_MMA(1, 0, At, B0); PG8_MMA(1, 1, At, B1); PG8_BAR; PG8_SCHED;
	v_mfma_f32_16x16x32_bf16 v[60:63], v[142:145], v[180:183], v[60:63]
	v_mfma_f32_16x16x32_bf16 v[56:59], v[150:153], v[180:183], v[56:59]
	v_mfma_f32_16x16x32_bf16 v[44:47], v[142:145], v[188:191], v[44:47]
	v_mfma_f32_16x16x32_bf16 v[40:43], v[150:153], v[188:191], v[40:43]
	v_mfma_f32_16x16x32_bf16 v[28:31], v[142:145], v[196:199], v[28:31]
	v_mfma_f32_16x16x32_bf16 v[24:27], v[150:153], v[196:199], v[24:27]
	v_mfma_f32_16x16x32_bf16 v[12:15], v[142:145], v[204:207], v[12:15]
	v_mfma_f32_16x16x32_bf16 v[8:11], v[150:153], v[204:207], v[8:11]
	v_mfma_f32_16x16x32_bf16 v[60:63], v[146:149], v[184:187], v[60:63]
	v_mfma_f32_16x16x32_bf16 v[56:59], v[160:163], v[184:187], v[56:59]
	v_mfma_f32_16x16x32_bf16 v[44:47], v[146:149], v[192:195], v[44:47]
	v_mfma_f32_16x16x32_bf16 v[40:43], v[160:163], v[192:195], v[40:43]
	v_mfma_f32_16x16x32_bf16 v[28:31], v[146:149], v[200:203], v[28:31]
	v_mfma_f32_16x16x32_bf16 v[24:27], v[160:163], v[200:203], v[24:27]
	v_mfma_f32_16x16x32_bf16 v[12:15], v[146:149], v[208:211], v[12:15]
	v_mfma_f32_16x16x32_bf16 v[8:11], v[160:163], v[208:211], v[8:11]
	s_setprio 0
	s_setprio 1
	v_mfma_f32_16x16x32_bf16 v[52:55], v[164:167], v[180:183], v[52:55]
	v_mfma_f32_16x16x32_bf16 v[48:51], v[172:175], v[180:183], v[48:51]
	v_mfma_f32_16x16x32_bf16 v[36:39], v[164:167], v[188:191], v[36:39]
	v_mfma_f32_16x16x32_bf16 v[32:35], v[172:175], v[188:191], v[32:35]
	v_mfma_f32_16x16x32_bf16 v[20:23], v[164:167], v[196:199], v[20:23]
	v_mfma_f32_16x16x32_bf16 v[16:19], v[172:175], v[196:199], v[16:19]
	v_mfma_f32_16x16x32_bf16 v[4:7], v[164:167], v[204:207], v[4:7]
	v_mfma_f32_16x16x32_bf16 v[0:3], v[172:175], v[204:207], v[0:3]
	v_mfma_f32_16x16x32_bf16 v[52:55], v[168:171], v[184:187], v[52:55]
	v_mfma_f32_16x16x32_bf16 v[48:51], v[176:179], v[184:187], v[48:51]
	v_mfma_f32_16x16x32_bf16 v[36:39], v[168:171], v[192:195], v[36:39]
	v_mfma_f32_16x16x32_bf16 v[32:35], v[176:179], v[192:195], v[32:35]
	v_mfma_f32_16x16x32_bf16 v[20:23], v[168:171], v[200:203], v[20:23]
	v_mfma_f32_16x16x32_bf16 v[16:19], v[176:179], v[200:203], v[16:19]
	v_mfma_f32_16x16x32_bf16 v[4:7], v[168:171], v[208:211], v[4:7]
	v_mfma_f32_16x16x32_bf16 v[0:3], v[176:179], v[208:211], v[0:3]
	s_setprio 0
	s_barrier
	s_add_i32 s92, 0, 0x18000
	v_add_u32_e32 v136, s92, v154
	s_add_i32 s93, 0, 0x1c000
	ds_read_b128 v[142:145], v136
	ds_read_b128 v[146:149], v136 offset:1024
	ds_read_b128 v[150:153], v136 offset:2048
	ds_read_b128 v[160:163], v136 offset:3072
	v_add_u32_e32 v136, s93, v154
	ds_read_b128 v[164:167], v136
	ds_read_b128 v[168:171], v136 offset:1024
	ds_read_b128 v[172:175], v136 offset:2048
	ds_read_b128 v[176:179], v136 offset:3072
	s_add_u32 s56, s56, 0xd0000
	s_addc_u32 s57, s57, 0
	s_mov_b32 m0, s62
	v_lshl_add_u64 v[220:221], s[56:57], 0, v[128:129]
	ds_read_b128 v[180:183], v157 offset:32768
	ds_read_b128 v[184:187], v157 offset:33792
	ds_read_b128 v[188:191], v157 offset:34816
	ds_read_b128 v[192:195], v157 offset:35840
	ds_read_b128 v[196:199], v157 offset:36864
	ds_read_b128 v[200:203], v157 offset:37888
	ds_read_b128 v[204:207], v157 offset:38912
	ds_read_b128 v[208:211], v157 offset:39936
	global_load_lds_dwordx4 v[220:221], off
	v_lshl_add_u64 v[220:221], s[56:57], 0, v[132:133]
	s_mov_b32 m0, s63
	s_nop 0
	global_load_lds_dwordx4 v[220:221], off
	s_waitcnt vmcnt(8)
	s_waitcnt lgkmcnt(0)
	s_setprio 1
	s_barrier
	v_mfma_f32_16x16x32_bf16 v[124:127], v[142:145], v[180:183], v[124:127]
	v_mfma_f32_16x16x32_bf16 v[120:123], v[150:153], v[180:183], v[120:123]
	v_mfma_f32_16x16x32_bf16 v[108:111], v[142:145], v[188:191], v[108:111]
	v_mfma_f32_16x16x32_bf16 v[104:107], v[150:153], v[188:191], v[104:107]
	v_mfma_f32_16x16x32_bf16 v[92:95], v[142:145], v[196:199], v[92:95]
	v_mfma_f32_16x16x32_bf16 v[88:91], v[150:153], v[196:199], v[88:91]
	v_mfma_f32_16x16x32_bf16 v[76:79], v[142:145], v[204:207], v[76:79]
	v_mfma_f32_16x16x32_bf16 v[72:75], v[150:153], v[204:207], v[72:75]
	v_mfma_f32_16x16x32_bf16 v[124:127], v[146:149], v[184:187], v[124:127]
	v_mfma_f32_16x16x32_bf16 v[120:123], v[160:163], v[184:187], v[120:123]
	v_mfma_f32_16x16x32_bf16 v[108:111], v[146:149], v[192:195], v[108:111]
	v_mfma_f32_16x16x32_bf16 v[104:107], v[160:163], v[192:195], v[104:107]
	v_mfma_f32_16x16x32_bf16 v[92:95], v[146:149], v[200:203], v[92:95]
	v_mfma_f32_16x16x32_bf16 v[88:91], v[160:163], v[200:203], v[88:91]
	v_mfma_f32_16x16x32_bf16 v[76:79], v[146:149], v[208:211], v[76:79]
	v_mfma_f32_16x16x32_bf16 v[72:75], v[160:163], v[208:211], v[72:75]
	s_setprio 0
	s_setprio 1
	v_mfma_f32_16x16x32_bf16 v[116:119], v[164:167], v[180:183], v[116:119]
	v_mfma_f32_16x16x32_bf16 v[112:115], v[172:175], v[180:183], v[112:115]
	v_mfma_f32_16x16x32_bf16 v[100:103], v[164:167], v[188:191], v[100:103]
	v_mfma_f32_16x16x32_bf16 v[96:99], v[172:175], v[188:191], v[96:99]
	v_mfma_f32_16x16x32_bf16 v[84:87], v[164:167], v[196:199], v[84:87]
	v_mfma_f32_16x16x32_bf16 v[80:83], v[172:175], v[196:199], v[80:83]
	v_mfma_f32_16x16x32_bf16 v[68:71], v[164:167], v[204:207], v[68:71]
	v_mfma_f32_16x16x32_bf16 v[64:67], v[172:175], v[204:207], v[64:67]
	v_mfma_f32_16x16x32_bf16 v[116:119], v[168:171], v[184:187], v[116:119]
	v_mfma_f32_16x16x32_bf16 v[112:115], v[176:179], v[184:187], v[112:115]
	v_mfma_f32_16x16x32_bf16 v[100:103], v[168:171], v[192:195], v[100:103]
	v_mfma_f32_16x16x32_bf16 v[96:99], v[176:179], v[192:195], v[96:99]
	v_mfma_f32_16x16x32_bf16 v[84:87], v[168:171], v[200:203], v[84:87]
	v_mfma_f32_16x16x32_bf16 v[80:83], v[176:179], v[200:203], v[80:83]
	v_mfma_f32_16x16x32_bf16 v[68:71], v[168:171], v[208:211], v[68:71]
	v_mfma_f32_16x16x32_bf16 v[64:67], v[176:179], v[208:211], v[64:67]
	s_setprio 0
	s_barrier
; #define PG8_STAGE(bufoff, gbase, voff) do { _Pragma("unroll") for (int _i = 0; _i < 2; ++_i) \
;         __builtin_amdgcn_global_load_lds((const unsigned*)((const char*)(gbase) + (BYTE_ELEMS ? _i * r##voff + (v##voff)[0] : (v##voff)[_i])), (PG8_LAS unsigned*)(lds + (bufoff) + ldsw + _i * 8192), 16, 0, 0); } while (0)
; #define PG8_LDA(dst, b, h) do { _Pragma("unroll") for (int m = 0; m < 4; ++m) _Pragma("unroll") for (int k = 0; k < 2; ++k) dst[m][k] = *(const PG8_LAS bf16x8*)(lds + PG8_SA(b, h) + aoff + m * 2048 + k * 1024); } while (0)
; #define PG8_WAIT_V(n) asm volatile("s_waitcnt vmcnt(" #n ")" ::: "memory")
; #define PG8_WAIT_L(n) asm volatile("s_waitcnt lgkmcnt(" #n ")" ::: "memory")
; #define PG8_BAR __builtin_amdgcn_s_barrier()
; #define PG8_SCHED __builtin_amdgcn_sched_barrier(0)
;     ...
;         for (int t = 0; t < nt; t += 2) {
;     ...
;             PG8_LDA(At, 1, 1); PG8_STAGE(PG8_SB(1, 0), b3, offB); PG8_STAGE(PG8_SB(1, 1), b3 + hstepB, offB); PG8_STAGE(PG8_SA(1, 0), a3, offA);
;             PG8_WAIT_V(8); PG8_WAIT_L(0); PG8_BAR; PG8_MMA(1, 0, At, B0); PG8_MMA(1, 1, At, B1); PG8_BAR; PG8_SCHED;
	s_add_i32 s56, s92, s59
	v_lshl_add_u64 v[212:213], v[212:213], 0, s[40:41]
	s_mov_b32 m0, s56
	ds_read_b128 v[180:183], v157 offset:49152
	ds_read_b128 v[184:187], v157 offset:50176
	ds_read_b128 v[188:191], v157 offset:51200
	ds_read_b128 v[192:195], v157 offset:52224
	ds_read_b128 v[196:199], v157 offset:53248
	ds_read_b128 v[200:203], v157 offset:54272
	ds_read_b128 v[204:207], v157 offset:55296
	ds_read_b128 v[208:211], v157 offset:56320
	global_load_lds_dwordx4 v[212:213], off
	s_add_i32 m0, s56, 0x2000
	s_add_u32 s54, s54, 0x20080
	v_lshl_add_u64 v[212:213], v[214:215], 0, s[40:41]
	s_addc_u32 s55, s55, 0
	s_add_i32 s56, s93, s59
	global_load_lds_dwordx4 v[212:213], off
	v_lshl_add_u64 v[212:213], s[54:55], 0, v[130:131]
	s_mov_b32 m0, s56
	s_nop 0
	global_load_lds_dwordx4 v[212:213], off
	v_lshl_add_u64 v[212:213], s[54:55], 0, v[134:135]
	s_add_i32 m0, s56, 0x2000
	s_nop 0
	global_load_lds_dwordx4 v[212:213], off
	v_lshl_add_u64 v[212:213], v[216:217], 0, s[40:41]
	s_mov_b32 m0, s69
	s_nop 0
	global_load_lds_dwordx4 v[212:213], off
	v_lshl_add_u64 v[212:213], v[218:219], 0, s[40:41]
	s_mov_b32 m0, s70
	s_nop 0
	global_load_lds_dwordx4 v[212:213], off
	s_waitcnt vmcnt(8)
	s_waitcnt lgkmcnt(0)
	s_setprio 1
	s_barrier
	v_mfma_f32_16x16x32_bf16 v[60:63], v[142:145], v[180:183], v[60:63]
	v_mfma_f32_16x16x32_bf16 v[56:59], v[150:153], v[180:183], v[56:59]
	v_mfma_f32_16x16x32_bf16 v[44:47], v[142:145], v[188:191], v[44:47]
	v_mfma_f32_16x16x32_bf16 v[40:43], v[150:153], v[188:191], v[40:43]
	v_mfma_f32_16x16x32_bf16 v[28:31], v[142:145], v[196:199], v[28:31]
	v_mfma_f32_16x16x32_bf16 v[24:27], v[150:153], v[196:199], v[24:27]
	v_mfma_f32_16x16x32_bf16 v[12:15], v[142:145], v[204:207], v[12:15]
	v_mfma_f32_16x16x32_bf16 v[8:11], v[150:153], v[204:207], v[8:11]
	v_mfma_f32_16x16x32_bf16 v[60:63], v[146:149], v[184:187], v[60:63]
	v_mfma_f32_16x16x32_bf16 v[56:59], v[160:163], v[184:187], v[56:59]
	v_mfma_f32_16x16x32_bf16 v[44:47], v[146:149], v[192:195], v[44:47]
	v_mfma_f32_16x16x32_bf16 v[40:43], v[160:163], v[192:195], v[40:43]
	v_mfma_f32_16x16x32_bf16 v[28:31], v[146:149], v[200:203], v[28:31]
	v_mfma_f32_16x16x32_bf16 v[24:27], v[160:163], v[200:203], v[24:27]
	v_mfma_f32_16x16x32_bf16 v[12:15], v[146:149], v[208:211], v[12:15]
	v_mfma_f32_16x16x32_bf16 v[8:11], v[160:163], v[208:211], v[8:11]
	s_setprio 0
	s_setprio 1
	v_mfma_f32_16x16x32_bf16 v[52:55], v[164:167], v[180:183], v[52:55]
	v_mfma_f32_16x16x32_bf16 v[48:51], v[172:175], v[180:183], v[48:51]
	v_mfma_f32_16x16x32_bf16 v[36:39], v[164:167], v[188:191], v[36:39]
	v_mfma_f32_16x16x32_bf16 v[32:35], v[172:175], v[188:191], v[32:35]
	v_mfma_f32_16x16x32_bf16 v[20:23], v[164:167], v[196:199], v[20:23]
	v_mfma_f32_16x16x32_bf16 v[16:19], v[172:175], v[196:199], v[16:19]
	v_mfma_f32_16x16x32_bf16 v[4:7], v[164:167], v[204:207], v[4:7]
	v_mfma_f32_16x16x32_bf16 v[0:3], v[172:175], v[204:207], v[0:3]
	v_mfma_f32_16x16x32_bf16 v[52:55], v[168:171], v[184:187], v[52:55]
	v_mfma_f32_16x16x32_bf16 v[48:51], v[176:179], v[184:187], v[48:51]
	v_mfma_f32_16x16x32_bf16 v[36:39], v[168:171], v[192:195], v[36:39]
	v_mfma_f32_16x16x32_bf16 v[32:35], v[176:179], v[192:195], v[32:35]
	v_mfma_f32_16x16x32_bf16 v[20:23], v[168:171], v[200:203], v[20:23]
	v_mfma_f32_16x16x32_bf16 v[16:19], v[176:179], v[200:203], v[16:19]
	v_mfma_f32_16x16x32_bf16 v[4:7], v[168:171], v[208:211], v[4:7]
	v_mfma_f32_16x16x32_bf16 v[0:3], v[176:179], v[208:211], v[0:3]
	s_setprio 0
	s_barrier
	s_add_i32 s91, s91, 2
	s_add_u32 s4, s4, 0x100
	s_addc_u32 s5, s5, 0
	s_add_u32 s89, s89, 0x100
	s_addc_u32 s90, s90, 0
	s_cmp_gt_u32 s91, 5
	s_cbranch_scc0 .LBB0_993
	s_and_b64 vcc, exec, s[42:43]
	s_cbranch_vccz .LBB0_996
	s_barrier

; __device__ __forceinline__ int tid_of(int wv) { int l; asm volatile("v_mbcnt_lo_u32_b32 %0, -1, 0\n\tv_mbcnt_hi_u32_b32 %0, -1, %0" : "=v"(l)); return wv * 64 + l; }
; #define PG8_STAGE(bufoff, gbase, voff) do { _Pragma("unroll") for (int _i = 0; _i < 2; ++_i) \
;         __builtin_amdgcn_global_load_lds((const unsigned*)((const char*)(gbase) + (BYTE_ELEMS ? _i * r##voff + (v##voff)[0] : (v##voff)[_i])), (PG8_LAS unsigned*)(lds + (bufoff) + ldsw + _i * 8192), 16, 0, 0); } while (0)
; #define PG8_WAIT_V(n) asm volatile("s_waitcnt vmcnt(" #n ")" ::: "memory")
;     ...
;         const bool has_next = S.next(ui + 1, nxt);
;         const char* nA = has_next ? (const char*)g.A + (size_t)nxt.pm * tstepA : cA; const char* nB = has_next ? (const char*)g.Bt + (size_t)nxt.pn * tstepB : cB;
;         for (int t = 0; t < nt; t += 2) {
;             const bool last = (t == nt - 2);
;             const char* a1 = cA + (size_t)(t + 1) * kstep;
;             const char* a2 = last ? nA : cA + (size_t)(t + 2) * kstep; const char* b2 = last ? nB : cB + (size_t)(t + 2) * kstep;
;             const char* a3 = a2 + kstep; const char* b3 = b2 + kstep;
;             if (last && has_next) S.a_ready(nxt);
;             if constexpr (MID) { if (t == nt / 2) { const int t3 = tid_of(wv); E.mid(acc, cur, wid >> 2, t3 & 15); } }
;             if constexpr (SP2) {
;             PG8_LDB(B0, 0, 0); PG8_LDB(B1, 0, 1); PG8_SCHED; PG8_LDA(At, 0, 0); PG8_STAGE(PG8_SA(1, 1), a1 + hstepA, offA);
;             PG8_WAIT_V(8); PG8_WAIT_L(0); PG8_BAR; PG8_MMA(0, 0, At, B0); PG8_MMA(0, 1, At, B1); PG8_BAR; PG8_SCHED;
;             PG8_LDA(At, 0, 1); PG8_STAGE(PG8_SB(0, 0), b2, offB); PG8_STAGE(PG8_SB(0, 1), b2 + hstepB, offB); PG8_STAGE(PG8_SA(0, 0), a2, offA);
;             PG8_WAIT_V(8); PG8_WAIT_L(0); PG8_BAR; PG8_MMA(1, 0, At, B0); PG8_MMA(1, 1, At, B1); PG8_BAR; PG8_SCHED;
;             PG8_LDB(B0, 1, 0); PG8_LDB(B1, 1, 1); PG8_SCHED; PG8_LDA(At, 1, 0); PG8_STAGE(PG8_SA(0, 1), a2 + hstepA, offA);
;             PG8_WAIT_V(8); PG8_WAIT_L(0); PG8_BAR; PG8_MMA(0, 0, At, B0); PG8_MMA(0, 1, At, B1); PG8_BAR; PG8_SCHED;
;             PG8_LDA(At, 1, 1); PG8_STAGE(PG8_SB(1, 0), b3, offB); PG8_STAGE(PG8_SB(1, 1), b3 + hstepB, offB); PG8_STAGE(PG8_SA(1, 0), a3, offA);
;             PG8_WAIT_V(8); PG8_WAIT_L(0); PG8_BAR; PG8_MMA(1, 0, At, B0); PG8_MMA(1, 1, At, B1); PG8_BAR; PG8_SCHED;
.LBB0_1044:
	ds_read_b128 v[142:145], v149
	ds_read_b128 v[154:157], v149 offset:1024
	ds_read_b128 v[158:161], v149 offset:2048
	ds_read_b128 v[162:165], v149 offset:3072
	ds_read_b128 v[166:169], v150
	ds_read_b128 v[170:173], v150 offset:1024
	ds_read_b128 v[174:177], v150 offset:2048
	ds_read_b128 v[178:181], v150 offset:3072
	s_add_u32 s60, s58, 0xfff30080
	s_addc_u32 s61, s59, -1
	s_cmp_eq_u32 s93, 4
	s_cselect_b32 s63, s55, s61
	s_cselect_b32 s62, s54, s60
	s_cselect_b32 s61, s53, s92
	s_cselect_b32 s60, s90, s91
	v_lshl_add_u64 v[146:147], s[58:59], 0, v[136:137]
	s_add_i32 m0, s69, 0xc000
	ds_read_b128 v[182:185], v151
	ds_read_b128 v[186:189], v151 offset:1024
	ds_read_b128 v[190:193], v151 offset:2048
	ds_read_b128 v[194:197], v151 offset:3072
	ds_read_b128 v[198:201], v151 offset:4096
	ds_read_b128 v[202:205], v151 offset:5120
	ds_read_b128 v[206:209], v151 offset:6144
	ds_read_b128 v[210:213], v151 offset:7168
	global_load_lds_dwordx4 v[146:147], off
	v_lshl_add_u64 v[146:147], s[58:59], 0, v[138:139]
	s_add_i32 m0, s69, 0xe000
	s_nop 0
	global_load_lds_dwordx4 v[146:147], off
	s_waitcnt vmcnt(8)
	s_waitcnt lgkmcnt(0)
	s_setprio 1
	s_barrier
	v_mfma_f32_16x16x32_bf16 v[124:127], v[142:145], v[182:185], v[124:127]
	v_mfma_f32_16x16x32_bf16 v[120:123], v[158:161], v[182:185], v[120:123]
	v_mfma_f32_16x16x32_bf16 v[108:111], v[142:145], v[190:193], v[108:111]
	v_mfma_f32_16x16x32_bf16 v[104:107], v[158:161], v[190:193], v[104:107]
	v_mfma_f32_16x16x32_bf16 v[92:95], v[142:145], v[198:201], v[92:95]
	v_mfma_f32_16x16x32_bf16 v[88:91], v[158:161], v[198:201], v[88:91]
	v_mfma_f32_16x16x32_bf16 v[76:79], v[142:145], v[206:209], v[76:79]
	v_mfma_f32_16x16x32_bf16 v[72:75], v[158:161], v[206:209], v[72:75]
	v_mfma_f32_16x16x32_bf16 v[124:127], v[154:157], v[186:189], v[124:127]
	v_mfma_f32_16x16x32_bf16 v[120:123], v[162:165], v[186:189], v[120:123]
	v_mfma_f32_16x16x32_bf16 v[108:111], v[154:157], v[194:197], v[108:111]
	v_mfma_f32_16x16x32_bf16 v[104:107], v[162:165], v[194:197], v[104:107]
	v_mfma_f32_16x16x32_bf16 v[92:95], v[154:157], v[202:205], v[92:95]
	v_mfma_f32_16x16x32_bf16 v[88:91], v[162:165], v[202:205], v[88:91]
	v_mfma_f32_16x16x32_bf16 v[76:79], v[154:157], v[210:213], v[76:79]
	v_mfma_f32_16x16x32_bf16 v[72:75], v[162:165], v[210:213], v[72:75]
	s_setprio 0
	s_setprio 1
	v_mfma_f32_16x16x32_bf16 v[116:119], v[166:169], v[182:185], v[116:119]
	v_mfma_f32_16x16x32_bf16 v[112:115], v[174:177], v[182:185], v[112:115]
	v_mfma_f32_16x16x32_bf16 v[100:103], v[166:169], v[190:193], v[100:103]
	v_mfma_f32_16x16x32_bf16 v[96:99], v[174:177], v[190:193], v[96:99]
	v_mfma_f32_16x16x32_bf16 v[84:87], v[166:169], v[198:201], v[84:87]
	v_mfma_f32_16x16x32_bf16 v[80:83], v[174:177], v[198:201], v[80:83]
	v_mfma_f32_16x16x32_bf16 v[68:71], v[166:169], v[206:209], v[68:71]
	v_mfma_f32_16x16x32_bf16 v[64:67], v[174:177], v[206:209], v[64:67]
	v_mfma_f32_16x16x32_bf16 v[116:119], v[170:173], v[186:189], v[116:119]
	v_mfma_f32_16x16x32_bf16 v[112:115], v[178:181], v[186:189], v[112:115]
	v_mfma_f32_16x16x32_bf16 v[100:103], v[170:173], v[194:197], v[100:103]
	v_mfma_f32_16x16x32_bf16 v[96:99], v[178:181], v[194:197], v[96:99]
	v_mfma_f32_16x16x32_bf16 v[84:87], v[170:173], v[202:205], v[84:87]
	v_mfma_f32_16x16x32_bf16 v[80:83], v[178:181], v[202:205], v[80:83]
	v_mfma_f32_16x16x32_bf16 v[68:71], v[170:173], v[210:213], v[68:71]
	v_mfma_f32_16x16x32_bf16 v[64:67], v[178:181], v[210:213], v[64:67]
	s_setprio 0
	s_barrier
	s_add_i32 s94, s81, s66
	v_lshl_add_u64 v[146:147], s[60:61], 0, v[132:133]
	s_mov_b32 m0, s94
	ds_read_b128 v[182:185], v151 offset:16384
	ds_read_b128 v[186:189], v151 offset:17408
	ds_read_b128 v[190:193], v151 offset:18432
	ds_read_b128 v[194:197], v151 offset:19456
	ds_read_b128 v[198:201], v151 offset:20480
	ds_read_b128 v[202:205], v151 offset:21504
	ds_read_b128 v[206:209], v151 offset:22528
	ds_read_b128 v[210:213], v151 offset:23552
	global_load_lds_dwordx4 v[146:147], off
	s_add_i32 m0, s94, 0x2000
	s_add_u32 s94, s60, 0x20000
	v_lshl_add_u64 v[214:215], s[60:61], 0, v[128:129]
	s_addc_u32 s95, s61, 0
	s_add_i32 s96, s82, s66
	global_load_lds_dwordx4 v[214:215], off
	v_lshl_add_u64 v[216:217], s[94:95], 0, v[132:133]
	s_mov_b32 m0, s96
	v_lshl_add_u64 v[218:219], s[62:63], 0, v[130:131]
	global_load_lds_dwordx4 v[216:217], off
	v_lshl_add_u64 v[216:217], s[94:95], 0, v[128:129]
	s_add_i32 m0, s96, 0x2000
	s_nop 0
	global_load_lds_dwordx4 v[216:217], off
	v_lshl_add_u64 v[216:217], s[62:63], 0, v[134:135]
	s_mov_b32 m0, s69
	s_nop 0
	global_load_lds_dwordx4 v[216:217], off
	s_mov_b32 m0, s70
	s_nop 0
	global_load_lds_dwordx4 v[218:219], off
	s_waitcnt vmcnt(8)
	s_waitcnt lgkmcnt(0)
	s_setprio 1
	s_barrier
; #define PG8_STAGE(bufoff, gbase, voff) do { _Pragma("unroll") for (int _i = 0; _i < 2; ++_i) \
;         __builtin_amdgcn_global_load_lds((const unsigned*)((const char*)(gbase) + (BYTE_ELEMS ? _i * r##voff + (v##voff)[0] : (v##voff)[_i])), (PG8_LAS unsigned*)(lds + (bufoff) + ldsw + _i * 8192), 16, 0, 0); } while (0)
; #define PG8_LDA(dst, b, h) do { _Pragma("unroll") for (int m = 0; m < 4; ++m) _Pragma("unroll") for (int k = 0; k < 2; ++k) dst[m][k] = *(const PG8_LAS bf16x8*)(lds + PG8_SA(b, h) + aoff + m * 2048 + k * 1024); } while (0)
; #define PG8_LDB(dst, b, h) do { _Pragma("unroll") for (int n = 0; n < 2; ++n) _Pragma("unroll") for (int k = 0; k < 2; ++k) dst[n][k] = *(const PG8_LAS bf16x8*)(lds + PG8_SB(b, h) + boff + n * 2048 + k * 1024); } while (0)
; #define PG8_WAIT_V(n) asm volatile("s_waitcnt vmcnt(" #n ")" ::: "memory")
; #define PG8_WAIT_L(n) asm volatile("s_waitcnt lgkmcnt(" #n ")" ::: "memory")
; #define PG8_BAR __builtin_amdgcn_s_barrier()
; #define PG8_SCHED __builtin_amdgcn_sched_barrier(0)
;     ...
;             PG8_LDB(B0, 0, 0); PG8_LDB(B1, 0, 1); PG8_SCHED; PG8_LDA(At, 0, 0); PG8_STAGE(PG8_SA(1, 1), a1 + hstepA, offA);
;             PG8_WAIT_V(8); PG8_WAIT_L(0); PG8_BAR; PG8_MMA(0, 0, At, B0); PG8_MMA(0, 1, At, B1); PG8_BAR; PG8_SCHED;
;             PG8_LDA(At, 0, 1); PG8_STAGE(PG8_SB(0, 0), b2, offB); PG8_STAGE(PG8_SB(0, 1), b2 + hstepB, offB); PG8_STAGE(PG8_SA(0, 0), a2, offA);
;             PG8_WAIT_V(8); PG8_WAIT_L(0); PG8_BAR; PG8_MMA(1, 0, At, B0); PG8_MMA(1, 1, At, B1); PG8_BAR; PG8_SCHED;
;             PG8_LDB(B0, 1, 0); PG8_LDB(B1, 1, 1); PG8_SCHED; PG8_LDA(At, 1, 0); PG8_STAGE(PG8_SA(0, 1), a2 + hstepA, offA);
;             PG8_WAIT_V(8); PG8_WAIT_L(0); PG8_BAR; PG8_MMA(0, 0, At, B0); PG8_MMA(0, 1, At, B1); PG8_BAR; PG8_SCHED;
;             PG8_LDA(At, 1, 1); PG8_STAGE(PG8_SB(1, 0), b3, offB); PG8_STAGE(PG8_SB(1, 1), b3 + hstepB, offB); PG8_STAGE(PG8_SA(1, 0), a3, offA);
;             PG8_WAIT_V(8); PG8_WAIT_L(0); PG8_BAR; PG8_MMA(1, 0, At, B0); PG8_MMA(1, 1, At, B1); PG8_BAR; PG8_SCHED;
	v_mfma_f32_16x16x32_bf16 v[60:63], v[142:145], v[182:185], v[60:63]
	v_mfma_f32_16x16x32_bf16 v[56:59], v[158:161], v[182:185], v[56:59]
	v_mfma_f32_16x16x32_bf16 v[44:47], v[142:145], v[190:193], v[44:47]
	v_mfma_f32_16x16x32_bf16 v[40:43], v[158:161], v[190:193], v[40:43]
	v_mfma_f32_16x16x32_bf16 v[28:31], v[142:145], v[198:201], v[28:31]
	v_mfma_f32_16x16x32_bf16 v[24:27], v[158:161], v[198:201], v[24:27]
	v_mfma_f32_16x16x32_bf16 v[12:15], v[142:145], v[206:209], v[12:15]
	v_mfma_f32_16x16x32_bf16 v[8:11], v[158:161], v[206:209], v[8:11]
	v_mfma_f32_16x16x32_bf16 v[60:63], v[154:157], v[186:189], v[60:63]
	v_mfma_f32_16x16x32_bf16 v[56:59], v[162:165], v[186:189], v[56:59]
	v_mfma_f32_16x16x32_bf16 v[44:47], v[154:157], v[194:197], v[44:47]
	v_mfma_f32_16x16x32_bf16 v[40:43], v[162:165], v[194:197], v[40:43]
	v_mfma_f32_16x16x32_bf16 v[28:31], v[154:157], v[202:205], v[28:31]
	v_mfma_f32_16x16x32_bf16 v[24:27], v[162:165], v[202:205], v[24:27]
	v_mfma_f32_16x16x32_bf16 v[12:15], v[154:157], v[210:213], v[12:15]
	v_mfma_f32_16x16x32_bf16 v[8:11], v[162:165], v[210:213], v[8:11]
	s_setprio 0
	s_setprio 1
	v_mfma_f32_16x16x32_bf16 v[52:55], v[166:169], v[182:185], v[52:55]
	v_mfma_f32_16x16x32_bf16 v[48:51], v[174:177], v[182:185], v[48:51]
	v_mfma_f32_16x16x32_bf16 v[36:39], v[166:169], v[190:193], v[36:39]
	v_mfma_f32_16x16x32_bf16 v[32:35], v[174:177], v[190:193], v[32:35]
	v_mfma_f32_16x16x32_bf16 v[20:23], v[166:169], v[198:201], v[20:23]
	v_mfma_f32_16x16x32_bf16 v[16:19], v[174:177], v[198:201], v[16:19]
	v_mfma_f32_16x16x32_bf16 v[4:7], v[166:169], v[206:209], v[4:7]
	v_mfma_f32_16x16x32_bf16 v[0:3], v[174:177], v[206:209], v[0:3]
	v_mfma_f32_16x16x32_bf16 v[52:55], v[170:173], v[186:189], v[52:55]
	v_mfma_f32_16x16x32_bf16 v[48:51], v[178:181], v[186:189], v[48:51]
	v_mfma_f32_16x16x32_bf16 v[36:39], v[170:173], v[194:197], v[36:39]
	v_mfma_f32_16x16x32_bf16 v[32:35], v[178:181], v[194:197], v[32:35]
	v_mfma_f32_16x16x32_bf16 v[20:23], v[170:173], v[202:205], v[20:23]
	v_mfma_f32_16x16x32_bf16 v[16:19], v[178:181], v[202:205], v[16:19]
	v_mfma_f32_16x16x32_bf16 v[4:7], v[170:173], v[210:213], v[4:7]
	v_mfma_f32_16x16x32_bf16 v[0:3], v[178:181], v[210:213], v[0:3]
	s_setprio 0
	s_barrier
	s_add_i32 s94, 0, 0x18000
	v_add_u32_e32 v153, s94, v148
	s_add_i32 s95, 0, 0x1c000
	ds_read_b128 v[142:145], v153
	ds_read_b128 v[154:157], v153 offset:1024
	ds_read_b128 v[158:161], v153 offset:2048
	ds_read_b128 v[162:165], v153 offset:3072
	v_add_u32_e32 v153, s95, v148
	ds_read_b128 v[166:169], v153
	ds_read_b128 v[170:173], v153 offset:1024
	ds_read_b128 v[174:177], v153 offset:2048
	ds_read_b128 v[178:181], v153 offset:3072
	s_add_u32 s62, s62, 0xd0000
	s_addc_u32 s63, s63, 0
	s_mov_b32 m0, s71
	v_lshl_add_u64 v[220:221], s[62:63], 0, v[134:135]
	ds_read_b128 v[182:185], v151 offset:32768
	ds_read_b128 v[186:189], v151 offset:33792
	ds_read_b128 v[190:193], v151 offset:34816
	ds_read_b128 v[194:197], v151 offset:35840
	ds_read_b128 v[198:201], v151 offset:36864
	ds_read_b128 v[202:205], v151 offset:37888
	ds_read_b128 v[206:209], v151 offset:38912
	ds_read_b128 v[210:213], v151 offset:39936
	global_load_lds_dwordx4 v[220:221], off
	v_lshl_add_u64 v[220:221], s[62:63], 0, v[130:131]
	s_mov_b32 m0, s72
	s_nop 0
	global_load_lds_dwordx4 v[220:221], off
	s_waitcnt vmcnt(8)
	s_waitcnt lgkmcnt(0)
	s_setprio 1
	s_barrier
	v_mfma_f32_16x16x32_bf16 v[124:127], v[142:145], v[182:185], v[124:127]
	v_mfma_f32_16x16x32_bf16 v[120:123], v[158:161], v[182:185], v[120:123]
	v_mfma_f32_16x16x32_bf16 v[108:111], v[142:145], v[190:193], v[108:111]
	v_mfma_f32_16x16x32_bf16 v[104:107], v[158:161], v[190:193], v[104:107]
	v_mfma_f32_16x16x32_bf16 v[92:95], v[142:145], v[198:201], v[92:95]
	v_mfma_f32_16x16x32_bf16 v[88:91], v[158:161], v[198:201], v[88:91]
	v_mfma_f32_16x16x32_bf16 v[76:79], v[142:145], v[206:209], v[76:79]
	v_mfma_f32_16x16x32_bf16 v[72:75], v[158:161], v[206:209], v[72:75]
	v_mfma_f32_16x16x32_bf16 v[124:127], v[154:157], v[186:189], v[124:127]
	v_mfma_f32_16x16x32_bf16 v[120:123], v[162:165], v[186:189], v[120:123]
	v_mfma_f32_16x16x32_bf16 v[108:111], v[154:157], v[194:197], v[108:111]
	v_mfma_f32_16x16x32_bf16 v[104:107], v[162:165], v[194:197], v[104:107]
	v_mfma_f32_16x16x32_bf16 v[92:95], v[154:157], v[202:205], v[92:95]
	v_mfma_f32_16x16x32_bf16 v[88:91], v[162:165], v[202:205], v[88:91]
	v_mfma_f32_16x16x32_bf16 v[76:79], v[154:157], v[210:213], v[76:79]
	v_mfma_f32_16x16x32_bf16 v[72:75], v[162:165], v[210:213], v[72:75]
	s_setprio 0
	s_setprio 1
	v_mfma_f32_16x16x32_bf16 v[116:119], v[166:169], v[182:185], v[116:119]
	v_mfma_f32_16x16x32_bf16 v[112:115], v[174:177], v[182:185], v[112:115]
	v_mfma_f32_16x16x32_bf16 v[100:103], v[166:169], v[190:193], v[100:103]
	v_mfma_f32_16x16x32_bf16 v[96:99], v[174:177], v[190:193], v[96:99]
	v_mfma_f32_16x16x32_bf16 v[84:87], v[166:169], v[198:201], v[84:87]
	v_mfma_f32_16x16x32_bf16 v[80:83], v[174:177], v[198:201], v[80:83]
	v_mfma_f32_16x16x32_bf16 v[68:71], v[166:169], v[206:209], v[68:71]
	v_mfma_f32_16x16x32_bf16 v[64:67], v[174:177], v[206:209], v[64:67]
	v_mfma_f32_16x16x32_bf16 v[116:119], v[170:173], v[186:189], v[116:119]
	v_mfma_f32_16x16x32_bf16 v[112:115], v[178:181], v[186:189], v[112:115]
	v_mfma_f32_16x16x32_bf16 v[100:103], v[170:173], v[194:197], v[100:103]
	v_mfma_f32_16x16x32_bf16 v[96:99], v[178:181], v[194:197], v[96:99]
	v_mfma_f32_16x16x32_bf16 v[84:87], v[170:173], v[202:205], v[84:87]
	v_mfma_f32_16x16x32_bf16 v[80:83], v[178:181], v[202:205], v[80:83]
	v_mfma_f32_16x16x32_bf16 v[68:71], v[170:173], v[210:213], v[68:71]
	v_mfma_f32_16x16x32_bf16 v[64:67], v[178:181], v[210:213], v[64:67]
	s_setprio 0
	s_barrier
; #define PG8_STAGE(bufoff, gbase, voff) do { _Pragma("unroll") for (int _i = 0; _i < 2; ++_i) \
;         __builtin_amdgcn_global_load_lds((const unsigned*)((const char*)(gbase) + (BYTE_ELEMS ? _i * r##voff + (v##voff)[0] : (v##voff)[_i])), (PG8_LAS unsigned*)(lds + (bufoff) + ldsw + _i * 8192), 16, 0, 0); } while (0)
; #define PG8_LDA(dst, b, h) do { _Pragma("unroll") for (int m = 0; m < 4; ++m) _Pragma("unroll") for (int k = 0; k < 2; ++k) dst[m][k] = *(const PG8_LAS bf16x8*)(lds + PG8_SA(b, h) + aoff + m * 2048 + k * 1024); } while (0)
; #define PG8_WAIT_V(n) asm volatile("s_waitcnt vmcnt(" #n ")" ::: "memory")
; #define PG8_WAIT_L(n) asm volatile("s_waitcnt lgkmcnt(" #n ")" ::: "memory")
; #define PG8_BAR __builtin_amdgcn_s_barrier()
; #define PG8_SCHED __builtin_amdgcn_sched_barrier(0)
;     ...
;         for (int t = 0; t < nt; t += 2) {
;     ...
;             PG8_LDA(At, 1, 1); PG8_STAGE(PG8_SB(1, 0), b3, offB); PG8_STAGE(PG8_SB(1, 1), b3 + hstepB, offB); PG8_STAGE(PG8_SA(1, 0), a3, offA);
;             PG8_WAIT_V(8); PG8_WAIT_L(0); PG8_BAR; PG8_MMA(1, 0, At, B0); PG8_MMA(1, 1, At, B1); PG8_BAR; PG8_SCHED;
	s_add_i32 s62, s94, s66
	v_lshl_add_u64 v[146:147], v[146:147], 0, s[36:37]
	s_mov_b32 m0, s62
	ds_read_b128 v[182:185], v151 offset:49152
	ds_read_b128 v[186:189], v151 offset:50176
	ds_read_b128 v[190:193], v151 offset:51200
	ds_read_b128 v[194:197], v151 offset:52224
	ds_read_b128 v[198:201], v151 offset:53248
	ds_read_b128 v[202:205], v151 offset:54272
	ds_read_b128 v[206:209], v151 offset:55296
	ds_read_b128 v[210:213], v151 offset:56320
	global_load_lds_dwordx4 v[146:147], off
	s_add_i32 m0, s62, 0x2000
	s_add_u32 s60, s60, 0x20080
	v_lshl_add_u64 v[146:147], v[214:215], 0, s[36:37]
	s_addc_u32 s61, s61, 0
	s_add_i32 s62, s95, s66
	global_load_lds_dwordx4 v[146:147], off
	v_lshl_add_u64 v[146:147], s[60:61], 0, v[132:133]
	s_mov_b32 m0, s62
	s_nop 0
	global_load_lds_dwordx4 v[146:147], off
	v_lshl_add_u64 v[146:147], s[60:61], 0, v[128:129]
	s_add_i32 m0, s62, 0x2000
	s_nop 0
	global_load_lds_dwordx4 v[146:147], off
	v_lshl_add_u64 v[146:147], v[216:217], 0, s[36:37]
	s_mov_b32 m0, s78
	s_nop 0
	global_load_lds_dwordx4 v[146:147], off
	v_lshl_add_u64 v[146:147], v[218:219], 0, s[36:37]
	s_mov_b32 m0, s79
	s_nop 0
	global_load_lds_dwordx4 v[146:147], off
	s_waitcnt vmcnt(8)
	s_waitcnt lgkmcnt(0)
	s_setprio 1
	s_barrier
	v_mfma_f32_16x16x32_bf16 v[60:63], v[142:145], v[182:185], v[60:63]
	v_mfma_f32_16x16x32_bf16 v[56:59], v[158:161], v[182:185], v[56:59]
	v_mfma_f32_16x16x32_bf16 v[44:47], v[142:145], v[190:193], v[44:47]
	v_mfma_f32_16x16x32_bf16 v[40:43], v[158:161], v[190:193], v[40:43]
	v_mfma_f32_16x16x32_bf16 v[28:31], v[142:145], v[198:201], v[28:31]
	v_mfma_f32_16x16x32_bf16 v[24:27], v[158:161], v[198:201], v[24:27]
	v_mfma_f32_16x16x32_bf16 v[12:15], v[142:145], v[206:209], v[12:15]
	v_mfma_f32_16x16x32_bf16 v[8:11], v[158:161], v[206:209], v[8:11]
	v_mfma_f32_16x16x32_bf16 v[60:63], v[154:157], v[186:189], v[60:63]
	v_mfma_f32_16x16x32_bf16 v[56:59], v[162:165], v[186:189], v[56:59]
	v_mfma_f32_16x16x32_bf16 v[44:47], v[154:157], v[194:197], v[44:47]
	v_mfma_f32_16x16x32_bf16 v[40:43], v[162:165], v[194:197], v[40:43]
	v_mfma_f32_16x16x32_bf16 v[28:31], v[154:157], v[202:205], v[28:31]
	v_mfma_f32_16x16x32_bf16 v[24:27], v[162:165], v[202:205], v[24:27]
	v_mfma_f32_16x16x32_bf16 v[12:15], v[154:157], v[210:213], v[12:15]
	v_mfma_f32_16x16x32_bf16 v[8:11], v[162:165], v[210:213], v[8:11]
	s_setprio 0
	s_setprio 1
	v_mfma_f32_16x16x32_bf16 v[52:55], v[166:169], v[182:185], v[52:55]
	v_mfma_f32_16x16x32_bf16 v[48:51], v[174:177], v[182:185], v[48:51]
	v_mfma_f32_16x16x32_bf16 v[36:39], v[166:169], v[190:193], v[36:39]
	v_mfma_f32_16x16x32_bf16 v[32:35], v[174:177], v[190:193], v[32:35]
	v_mfma_f32_16x16x32_bf16 v[20:23], v[166:169], v[198:201], v[20:23]
	v_mfma_f32_16x16x32_bf16 v[16:19], v[174:177], v[198:201], v[16:19]
	v_mfma_f32_16x16x32_bf16 v[4:7], v[166:169], v[206:209], v[4:7]
	v_mfma_f32_16x16x32_bf16 v[0:3], v[174:177], v[206:209], v[0:3]
	v_mfma_f32_16x16x32_bf16 v[52:55], v[170:173], v[186:189], v[52:55]
	v_mfma_f32_16x16x32_bf16 v[48:51], v[178:181], v[186:189], v[48:51]
	v_mfma_f32_16x16x32_bf16 v[36:39], v[170:173], v[194:197], v[36:39]
	v_mfma_f32_16x16x32_bf16 v[32:35], v[178:181], v[194:197], v[32:35]
	v_mfma_f32_16x16x32_bf16 v[20:23], v[170:173], v[202:205], v[20:23]
	v_mfma_f32_16x16x32_bf16 v[16:19], v[178:181], v[202:205], v[16:19]
	v_mfma_f32_16x16x32_bf16 v[4:7], v[170:173], v[210:213], v[4:7]
	v_mfma_f32_16x16x32_bf16 v[0:3], v[178:181], v[210:213], v[0:3]
	s_setprio 0
	s_barrier
	s_add_i32 s93, s93, 2
	s_add_u32 s58, s58, 0x100
	s_addc_u32 s59, s59, 0
	s_add_u32 s91, s91, 0x100
	s_addc_u32 s92, s92, 0
	s_cmp_gt_u32 s93, 5
	s_cbranch_scc0 .LBB0_1044
	s_and_b64 vcc, exec, s[38:39]
	s_cbranch_vccz .LBB0_1047
	s_barrier

; __device__ __forceinline__ int tid_of(int wv) { int l; asm volatile("v_mbcnt_lo_u32_b32 %0, -1, 0\n\tv_mbcnt_hi_u32_b32 %0, -1, %0" : "=v"(l)); return wv * 64 + l; }
; #define PG8_STAGE(bufoff, gbase, voff) do { _Pragma("unroll") for (int _i = 0; _i < 2; ++_i) \
;         __builtin_amdgcn_global_load_lds((const unsigned*)((const char*)(gbase) + (BYTE_ELEMS ? _i * r##voff + (v##voff)[0] : (v##voff)[_i])), (PG8_LAS unsigned*)(lds + (bufoff) + ldsw + _i * 8192), 16, 0, 0); } while (0)
; #define PG8_LDA(dst, b, h) do { _Pragma("unroll") for (int m = 0; m < 4; ++m) _Pragma("unroll") for (int k = 0; k < 2; ++k) dst[m][k] = *(const PG8_LAS bf16x8*)(lds + PG8_SA(b, h) + aoff + m * 2048 + k * 1024); } while (0)
; #define PG8_LDB(dst, b, h) do { _Pragma("unroll") for (int n = 0; n < 2; ++n) _Pragma("unroll") for (int k = 0; k < 2; ++k) dst[n][k] = *(const PG8_LAS bf16x8*)(lds + PG8_SB(b, h) + boff + n * 2048 + k * 1024); } while (0)
; #define PG8_WAIT_V(n) asm volatile("s_waitcnt vmcnt(" #n ")" ::: "memory")
; #define PG8_WAIT_L(n) asm volatile("s_waitcnt lgkmcnt(" #n ")" ::: "memory")
; #define PG8_BAR __builtin_amdgcn_s_barrier()
; #define PG8_SCHED __builtin_amdgcn_sched_barrier(0)
;     ...
;             if constexpr (MID) { if (t == nt / 2) { const int t3 = tid_of(wv); E.mid(acc, cur, wid >> 2, t3 & 15); } }
;             if constexpr (SP2) {
;             PG8_LDB(B0, 0, 0); PG8_LDB(B1, 0, 1); PG8_SCHED; PG8_LDA(At, 0, 0); PG8_STAGE(PG8_SA(1, 1), a1 + hstepA, offA);
;             PG8_WAIT_V(8); PG8_WAIT_L(0); PG8_BAR; PG8_MMA(0, 0, At, B0); PG8_MMA(0, 1, At, B1); PG8_BAR; PG8_SCHED;
;             PG8_LDA(At, 0, 1); PG8_STAGE(PG8_SB(0, 0), b2, offB); PG8_STAGE(PG8_SB(0, 1), b2 + hstepB, offB); PG8_STAGE(PG8_SA(0, 0), a2, offA);
;             PG8_WAIT_V(8); PG8_WAIT_L(0); PG8_BAR; PG8_MMA(1, 0, At, B0); PG8_MMA(1, 1, At, B1); PG8_BAR; PG8_SCHED;
;             PG8_LDB(B0, 1, 0); PG8_LDB(B1, 1, 1); PG8_SCHED; PG8_LDA(At, 1, 0); PG8_STAGE(PG8_SA(0, 1), a2 + hstepA, offA);
;             PG8_WAIT_V(8); PG8_WAIT_L(0); PG8_BAR; PG8_MMA(0, 0, At, B0); PG8_MMA(0, 1, At, B1); PG8_BAR; PG8_SCHED;
;             PG8_LDA(At, 1, 1); PG8_STAGE(PG8_SB(1, 0), b3, offB); PG8_STAGE(PG8_SB(1, 1), b3 + hstepB, offB); PG8_STAGE(PG8_SA(1, 0), a3, offA);
;             PG8_WAIT_V(8); PG8_WAIT_L(0); PG8_BAR; PG8_MMA(1, 0, At, B0); PG8_MMA(1, 1, At, B1); PG8_BAR; PG8_SCHED;
.LBB0_1263:
	v_add_u32_e32 v1, s79, v172
	ds_read_b128 v[150:153], v1
	ds_read_b128 v[154:157], v1 offset:1024
	ds_read_b128 v[158:161], v1 offset:2048
	ds_read_b128 v[162:165], v1 offset:3072
	v_add_u32_e32 v1, s80, v172
	s_add_u32 s60, s56, s58
	ds_read_b128 v[166:169], v1
	ds_read_b128 v[176:179], v1 offset:1024
	ds_read_b128 v[180:183], v1 offset:2048
	ds_read_b128 v[184:187], v1 offset:3072
	s_addc_u32 s61, s57, s59
	s_add_u32 s60, s60, 0x100
	s_addc_u32 s61, s61, 0
	s_add_u32 s91, s88, s58
	s_addc_u32 s92, s89, s59
	s_cmpk_eq_i32 s58, 0xf00
	s_cselect_b32 s63, s49, s61
	s_cselect_b32 s62, s85, s60
	s_cselect_b32 s61, s86, s92
	s_cselect_b32 s60, s87, s91
	v_lshl_add_u64 v[2:3], v[146:147], 0, s[58:59]
	s_add_i32 m0, s67, 0xc000
	ds_read_b128 v[188:191], v174
	ds_read_b128 v[192:195], v174 offset:1024
	ds_read_b128 v[196:199], v174 offset:2048
	ds_read_b128 v[200:203], v174 offset:3072
	ds_read_b128 v[204:207], v174 offset:4096
	ds_read_b128 v[208:211], v174 offset:5120
	ds_read_b128 v[212:215], v174 offset:6144
	ds_read_b128 v[216:219], v174 offset:7168
	global_load_lds_dwordx4 v[2:3], off
	v_lshl_add_u64 v[2:3], v[148:149], 0, s[58:59]
	s_add_i32 m0, s67, 0xe000
	s_nop 0
	global_load_lds_dwordx4 v[2:3], off
	s_waitcnt vmcnt(8)
	s_waitcnt lgkmcnt(0)
	s_setprio 1
	s_barrier
	v_mfma_f32_16x16x32_bf16 v[128:131], v[150:153], v[188:191], v[128:131]
	v_mfma_f32_16x16x32_bf16 v[124:127], v[158:161], v[188:191], v[124:127]
	v_mfma_f32_16x16x32_bf16 v[112:115], v[150:153], v[196:199], v[112:115]
	v_mfma_f32_16x16x32_bf16 v[108:111], v[158:161], v[196:199], v[108:111]
	v_mfma_f32_16x16x32_bf16 v[96:99], v[150:153], v[204:207], v[96:99]
	v_mfma_f32_16x16x32_bf16 v[92:95], v[158:161], v[204:207], v[92:95]
	v_mfma_f32_16x16x32_bf16 v[80:83], v[150:153], v[212:215], v[80:83]
	v_mfma_f32_16x16x32_bf16 v[76:79], v[158:161], v[212:215], v[76:79]
	v_mfma_f32_16x16x32_bf16 v[128:131], v[154:157], v[192:195], v[128:131]
	v_mfma_f32_16x16x32_bf16 v[124:127], v[162:165], v[192:195], v[124:127]
	v_mfma_f32_16x16x32_bf16 v[112:115], v[154:157], v[200:203], v[112:115]
	v_mfma_f32_16x16x32_bf16 v[108:111], v[162:165], v[200:203], v[108:111]
	v_mfma_f32_16x16x32_bf16 v[96:99], v[154:157], v[208:211], v[96:99]
	v_mfma_f32_16x16x32_bf16 v[92:95], v[162:165], v[208:211], v[92:95]
	v_mfma_f32_16x16x32_bf16 v[80:83], v[154:157], v[216:219], v[80:83]
	v_mfma_f32_16x16x32_bf16 v[76:79], v[162:165], v[216:219], v[76:79]
	s_setprio 0
	s_setprio 1
	v_mfma_f32_16x16x32_bf16 v[120:123], v[166:169], v[188:191], v[120:123]
	v_mfma_f32_16x16x32_bf16 v[116:119], v[180:183], v[188:191], v[116:119]
	v_mfma_f32_16x16x32_bf16 v[104:107], v[166:169], v[196:199], v[104:107]
	v_mfma_f32_16x16x32_bf16 v[100:103], v[180:183], v[196:199], v[100:103]
	v_mfma_f32_16x16x32_bf16 v[88:91], v[166:169], v[204:207], v[88:91]
	v_mfma_f32_16x16x32_bf16 v[84:87], v[180:183], v[204:207], v[84:87]
	v_mfma_f32_16x16x32_bf16 v[72:75], v[166:169], v[212:215], v[72:75]
	v_mfma_f32_16x16x32_bf16 v[68:71], v[180:183], v[212:215], v[68:71]
	v_mfma_f32_16x16x32_bf16 v[120:123], v[176:179], v[192:195], v[120:123]
	v_mfma_f32_16x16x32_bf16 v[116:119], v[184:187], v[192:195], v[116:119]
	v_mfma_f32_16x16x32_bf16 v[104:107], v[176:179], v[200:203], v[104:107]
	v_mfma_f32_16x16x32_bf16 v[100:103], v[184:187], v[200:203], v[100:103]
	v_mfma_f32_16x16x32_bf16 v[88:91], v[176:179], v[208:211], v[88:91]
	v_mfma_f32_16x16x32_bf16 v[84:87], v[184:187], v[208:211], v[84:87]
	v_mfma_f32_16x16x32_bf16 v[72:75], v[176:179], v[216:219], v[72:75]
	v_mfma_f32_16x16x32_bf16 v[68:71], v[184:187], v[216:219], v[68:71]
	s_setprio 0
	s_barrier
	s_add_i32 s91, s79, s64
	v_lshl_add_u64 v[170:171], s[60:61], 0, v[136:137]
	s_mov_b32 m0, s91
	ds_read_b128 v[188:191], v174 offset:16384
	ds_read_b128 v[192:195], v174 offset:17408
	ds_read_b128 v[196:199], v174 offset:18432
	ds_read_b128 v[200:203], v174 offset:19456
	ds_read_b128 v[204:207], v174 offset:20480
	ds_read_b128 v[208:211], v174 offset:21504
	ds_read_b128 v[212:215], v174 offset:22528
	ds_read_b128 v[216:219], v174 offset:23552
	global_load_lds_dwordx4 v[170:171], off
	s_add_i32 m0, s91, 0x2000
	s_add_u32 s92, s60, 0x80000
	v_lshl_add_u64 v[220:221], s[60:61], 0, v[132:133]
	s_addc_u32 s93, s61, 0
	s_add_i32 s91, s80, s64
	global_load_lds_dwordx4 v[220:221], off
	v_lshl_add_u64 v[2:3], s[92:93], 0, v[136:137]
	s_mov_b32 m0, s91
	v_lshl_add_u64 v[222:223], s[62:63], 0, v[138:139]
	global_load_lds_dwordx4 v[2:3], off
	v_lshl_add_u64 v[2:3], s[92:93], 0, v[132:133]
	s_add_i32 m0, s91, 0x2000
	v_lshl_add_u64 v[224:225], s[62:63], 0, v[134:135]
	global_load_lds_dwordx4 v[2:3], off
	s_mov_b32 m0, s67
	s_nop 0
	global_load_lds_dwordx4 v[222:223], off
	s_mov_b32 m0, s68
	s_nop 0
	global_load_lds_dwordx4 v[224:225], off
	s_waitcnt vmcnt(8)
	s_waitcnt lgkmcnt(0)
	s_setprio 1
	s_barrier
; #define PG8_STAGE(bufoff, gbase, voff) do { _Pragma("unroll") for (int _i = 0; _i < 2; ++_i) \
;         __builtin_amdgcn_global_load_lds((const unsigned*)((const char*)(gbase) + (BYTE_ELEMS ? _i * r##voff + (v##voff)[0] : (v##voff)[_i])), (PG8_LAS unsigned*)(lds + (bufoff) + ldsw + _i * 8192), 16, 0, 0); } while (0)
; #define PG8_LDA(dst, b, h) do { _Pragma("unroll") for (int m = 0; m < 4; ++m) _Pragma("unroll") for (int k = 0; k < 2; ++k) dst[m][k] = *(const PG8_LAS bf16x8*)(lds + PG8_SA(b, h) + aoff + m * 2048 + k * 1024); } while (0)
; #define PG8_LDB(dst, b, h) do { _Pragma("unroll") for (int n = 0; n < 2; ++n) _Pragma("unroll") for (int k = 0; k < 2; ++k) dst[n][k] = *(const PG8_LAS bf16x8*)(lds + PG8_SB(b, h) + boff + n * 2048 + k * 1024); } while (0)
; #define PG8_WAIT_V(n) asm volatile("s_waitcnt vmcnt(" #n ")" ::: "memory")
; #define PG8_WAIT_L(n) asm volatile("s_waitcnt lgkmcnt(" #n ")" ::: "memory")
; #define PG8_BAR __builtin_amdgcn_s_barrier()
; #define PG8_SCHED __builtin_amdgcn_sched_barrier(0)
;     ...
;             PG8_LDB(B0, 0, 0); PG8_LDB(B1, 0, 1); PG8_SCHED; PG8_LDA(At, 0, 0); PG8_STAGE(PG8_SA(1, 1), a1 + hstepA, offA);
;             PG8_WAIT_V(8); PG8_WAIT_L(0); PG8_BAR; PG8_MMA(0, 0, At, B0); PG8_MMA(0, 1, At, B1); PG8_BAR; PG8_SCHED;
;             PG8_LDA(At, 0, 1); PG8_STAGE(PG8_SB(0, 0), b2, offB); PG8_STAGE(PG8_SB(0, 1), b2 + hstepB, offB); PG8_STAGE(PG8_SA(0, 0), a2, offA);
;             PG8_WAIT_V(8); PG8_WAIT_L(0); PG8_BAR; PG8_MMA(1, 0, At, B0); PG8_MMA(1, 1, At, B1); PG8_BAR; PG8_SCHED;
;             PG8_LDB(B0, 1, 0); PG8_LDB(B1, 1, 1); PG8_SCHED; PG8_LDA(At, 1, 0); PG8_STAGE(PG8_SA(0, 1), a2 + hstepA, offA);
;             PG8_WAIT_V(8); PG8_WAIT_L(0); PG8_BAR; PG8_MMA(0, 0, At, B0); PG8_MMA(0, 1, At, B1); PG8_BAR; PG8_SCHED;
;             PG8_LDA(At, 1, 1); PG8_STAGE(PG8_SB(1, 0), b3, offB); PG8_STAGE(PG8_SB(1, 1), b3 + hstepB, offB); PG8_STAGE(PG8_SA(1, 0), a3, offA);
;             PG8_WAIT_V(8); PG8_WAIT_L(0); PG8_BAR; PG8_MMA(1, 0, At, B0); PG8_MMA(1, 1, At, B1); PG8_BAR; PG8_SCHED;
	v_mfma_f32_16x16x32_bf16 v[64:67], v[150:153], v[188:191], v[64:67]
	v_mfma_f32_16x16x32_bf16 v[60:63], v[158:161], v[188:191], v[60:63]
	v_mfma_f32_16x16x32_bf16 v[48:51], v[150:153], v[196:199], v[48:51]
	v_mfma_f32_16x16x32_bf16 v[44:47], v[158:161], v[196:199], v[44:47]
	v_mfma_f32_16x16x32_bf16 v[32:35], v[150:153], v[204:207], v[32:35]
	v_mfma_f32_16x16x32_bf16 v[28:31], v[158:161], v[204:207], v[28:31]
	v_mfma_f32_16x16x32_bf16 v[16:19], v[150:153], v[212:215], v[16:19]
	v_mfma_f32_16x16x32_bf16 v[12:15], v[158:161], v[212:215], v[12:15]
	v_mfma_f32_16x16x32_bf16 v[64:67], v[154:157], v[192:195], v[64:67]
	v_mfma_f32_16x16x32_bf16 v[60:63], v[162:165], v[192:195], v[60:63]
	v_mfma_f32_16x16x32_bf16 v[48:51], v[154:157], v[200:203], v[48:51]
	v_mfma_f32_16x16x32_bf16 v[44:47], v[162:165], v[200:203], v[44:47]
	v_mfma_f32_16x16x32_bf16 v[32:35], v[154:157], v[208:211], v[32:35]
	v_mfma_f32_16x16x32_bf16 v[28:31], v[162:165], v[208:211], v[28:31]
	v_mfma_f32_16x16x32_bf16 v[16:19], v[154:157], v[216:219], v[16:19]
	v_mfma_f32_16x16x32_bf16 v[12:15], v[162:165], v[216:219], v[12:15]
	s_setprio 0
	s_setprio 1
	v_mfma_f32_16x16x32_bf16 v[56:59], v[166:169], v[188:191], v[56:59]
	v_mfma_f32_16x16x32_bf16 v[52:55], v[180:183], v[188:191], v[52:55]
	v_mfma_f32_16x16x32_bf16 v[40:43], v[166:169], v[196:199], v[40:43]
	v_mfma_f32_16x16x32_bf16 v[36:39], v[180:183], v[196:199], v[36:39]
	v_mfma_f32_16x16x32_bf16 v[24:27], v[166:169], v[204:207], v[24:27]
	v_mfma_f32_16x16x32_bf16 v[20:23], v[180:183], v[204:207], v[20:23]
	v_mfma_f32_16x16x32_bf16 v[8:11], v[166:169], v[212:215], v[8:11]
	v_mfma_f32_16x16x32_bf16 v[2:5], v[180:183], v[212:215], v[4:7]
	v_mfma_f32_16x16x32_bf16 v[56:59], v[176:179], v[192:195], v[56:59]
	v_mfma_f32_16x16x32_bf16 v[52:55], v[184:187], v[192:195], v[52:55]
	v_mfma_f32_16x16x32_bf16 v[40:43], v[176:179], v[200:203], v[40:43]
	v_mfma_f32_16x16x32_bf16 v[36:39], v[184:187], v[200:203], v[36:39]
	v_mfma_f32_16x16x32_bf16 v[24:27], v[176:179], v[208:211], v[24:27]
	v_mfma_f32_16x16x32_bf16 v[20:23], v[184:187], v[208:211], v[20:23]
	v_mfma_f32_16x16x32_bf16 v[8:11], v[176:179], v[216:219], v[8:11]
	v_mfma_f32_16x16x32_bf16 v[2:5], v[184:187], v[216:219], v[2:5]
	s_setprio 0
	s_barrier
	s_add_i32 s91, 0, 0x18000
	v_add_u32_e32 v1, s91, v172
	s_add_i32 s92, 0, 0x1c000
	ds_read_b128 v[150:153], v1
	ds_read_b128 v[154:157], v1 offset:1024
	ds_read_b128 v[158:161], v1 offset:2048
	ds_read_b128 v[162:165], v1 offset:3072
	v_add_u32_e32 v1, s92, v172
	ds_read_b128 v[166:169], v1
	ds_read_b128 v[176:179], v1 offset:1024
	ds_read_b128 v[180:183], v1 offset:2048
	ds_read_b128 v[184:187], v1 offset:3072
	s_add_u32 s62, s62, 0x80000
	s_addc_u32 s63, s63, 0
	s_mov_b32 m0, s69
	v_lshl_add_u64 v[6:7], s[62:63], 0, v[138:139]
	ds_read_b128 v[188:191], v174 offset:32768
	ds_read_b128 v[192:195], v174 offset:33792
	ds_read_b128 v[196:199], v174 offset:34816
	ds_read_b128 v[200:203], v174 offset:35840
	ds_read_b128 v[204:207], v174 offset:36864
	ds_read_b128 v[208:211], v174 offset:37888
	ds_read_b128 v[212:215], v174 offset:38912
	ds_read_b128 v[216:219], v174 offset:39936
	global_load_lds_dwordx4 v[6:7], off
	v_lshl_add_u64 v[6:7], s[62:63], 0, v[134:135]
	s_mov_b32 m0, s70
	s_nop 0
	global_load_lds_dwordx4 v[6:7], off
	s_waitcnt vmcnt(8)
	s_waitcnt lgkmcnt(0)
	s_setprio 1
	s_barrier
	v_mfma_f32_16x16x32_bf16 v[128:131], v[150:153], v[188:191], v[128:131]
	v_mfma_f32_16x16x32_bf16 v[124:127], v[158:161], v[188:191], v[124:127]
	v_mfma_f32_16x16x32_bf16 v[112:115], v[150:153], v[196:199], v[112:115]
	v_mfma_f32_16x16x32_bf16 v[108:111], v[158:161], v[196:199], v[108:111]
	v_mfma_f32_16x16x32_bf16 v[96:99], v[150:153], v[204:207], v[96:99]
	v_mfma_f32_16x16x32_bf16 v[92:95], v[158:161], v[204:207], v[92:95]
	v_mfma_f32_16x16x32_bf16 v[80:83], v[150:153], v[212:215], v[80:83]
	v_mfma_f32_16x16x32_bf16 v[76:79], v[158:161], v[212:215], v[76:79]
	v_mfma_f32_16x16x32_bf16 v[128:131], v[154:157], v[192:195], v[128:131]
	v_mfma_f32_16x16x32_bf16 v[124:127], v[162:165], v[192:195], v[124:127]
	v_mfma_f32_16x16x32_bf16 v[112:115], v[154:157], v[200:203], v[112:115]
	v_mfma_f32_16x16x32_bf16 v[108:111], v[162:165], v[200:203], v[108:111]
	v_mfma_f32_16x16x32_bf16 v[96:99], v[154:157], v[208:211], v[96:99]
	v_mfma_f32_16x16x32_bf16 v[92:95], v[162:165], v[208:211], v[92:95]
	v_mfma_f32_16x16x32_bf16 v[80:83], v[154:157], v[216:219], v[80:83]
	v_mfma_f32_16x16x32_bf16 v[76:79], v[162:165], v[216:219], v[76:79]
	s_setprio 0
	s_setprio 1
	v_mfma_f32_16x16x32_bf16 v[120:123], v[166:169], v[188:191], v[120:123]
	v_mfma_f32_16x16x32_bf16 v[116:119], v[180:183], v[188:191], v[116:119]
	v_mfma_f32_16x16x32_bf16 v[104:107], v[166:169], v[196:199], v[104:107]
	v_mfma_f32_16x16x32_bf16 v[100:103], v[180:183], v[196:199], v[100:103]
	v_mfma_f32_16x16x32_bf16 v[88:91], v[166:169], v[204:207], v[88:91]
	v_mfma_f32_16x16x32_bf16 v[84:87], v[180:183], v[204:207], v[84:87]
	v_mfma_f32_16x16x32_bf16 v[72:75], v[166:169], v[212:215], v[72:75]
	v_mfma_f32_16x16x32_bf16 v[68:71], v[180:183], v[212:215], v[68:71]
	v_mfma_f32_16x16x32_bf16 v[120:123], v[176:179], v[192:195], v[120:123]
	v_mfma_f32_16x16x32_bf16 v[116:119], v[184:187], v[192:195], v[116:119]
	v_mfma_f32_16x16x32_bf16 v[104:107], v[176:179], v[200:203], v[104:107]
	v_mfma_f32_16x16x32_bf16 v[100:103], v[184:187], v[200:203], v[100:103]
	v_mfma_f32_16x16x32_bf16 v[88:91], v[176:179], v[208:211], v[88:91]
	v_mfma_f32_16x16x32_bf16 v[84:87], v[184:187], v[208:211], v[84:87]
	v_mfma_f32_16x16x32_bf16 v[72:75], v[176:179], v[216:219], v[72:75]
	v_mfma_f32_16x16x32_bf16 v[68:71], v[184:187], v[216:219], v[68:71]
	s_setprio 0
	s_barrier
; #define PG8_STAGE(bufoff, gbase, voff) do { _Pragma("unroll") for (int _i = 0; _i < 2; ++_i) \
;         __builtin_amdgcn_global_load_lds((const unsigned*)((const char*)(gbase) + (BYTE_ELEMS ? _i * r##voff + (v##voff)[0] : (v##voff)[_i])), (PG8_LAS unsigned*)(lds + (bufoff) + ldsw + _i * 8192), 16, 0, 0); } while (0)
; #define PG8_LDA(dst, b, h) do { _Pragma("unroll") for (int m = 0; m < 4; ++m) _Pragma("unroll") for (int k = 0; k < 2; ++k) dst[m][k] = *(const PG8_LAS bf16x8*)(lds + PG8_SA(b, h) + aoff + m * 2048 + k * 1024); } while (0)
; #define PG8_WAIT_V(n) asm volatile("s_waitcnt vmcnt(" #n ")" ::: "memory")
; #define PG8_WAIT_L(n) asm volatile("s_waitcnt lgkmcnt(" #n ")" ::: "memory")
; #define PG8_BAR __builtin_amdgcn_s_barrier()
; #define PG8_SCHED __builtin_amdgcn_sched_barrier(0)
;     ...
;         for (int t = 0; t < nt; t += 2) {
;     ...
;             PG8_LDA(At, 1, 1); PG8_STAGE(PG8_SB(1, 0), b3, offB); PG8_STAGE(PG8_SB(1, 1), b3 + hstepB, offB); PG8_STAGE(PG8_SA(1, 0), a3, offA);
;             PG8_WAIT_V(8); PG8_WAIT_L(0); PG8_BAR; PG8_MMA(1, 0, At, B0); PG8_MMA(1, 1, At, B1); PG8_BAR; PG8_SCHED;
	s_add_i32 s62, s91, s64
	v_lshl_add_u64 v[6:7], v[170:171], 0, s[36:37]
	s_mov_b32 m0, s62
	ds_read_b128 v[188:191], v174 offset:49152
	ds_read_b128 v[192:195], v174 offset:50176
	ds_read_b128 v[196:199], v174 offset:51200
	ds_read_b128 v[200:203], v174 offset:52224
	ds_read_b128 v[204:207], v174 offset:53248
	ds_read_b128 v[208:211], v174 offset:54272
	ds_read_b128 v[212:215], v174 offset:55296
	ds_read_b128 v[216:219], v174 offset:56320
	global_load_lds_dwordx4 v[6:7], off
	s_add_i32 m0, s62, 0x2000
	s_add_u32 s60, s60, 0x80080
	v_lshl_add_u64 v[6:7], v[220:221], 0, s[36:37]
	s_addc_u32 s61, s61, 0
	s_add_i32 s62, s92, s64
	global_load_lds_dwordx4 v[6:7], off
	v_lshl_add_u64 v[6:7], s[60:61], 0, v[136:137]
	s_mov_b32 m0, s62
	s_nop 0
	global_load_lds_dwordx4 v[6:7], off
	v_lshl_add_u64 v[6:7], s[60:61], 0, v[132:133]
	s_add_i32 m0, s62, 0x2000
	s_nop 0
	global_load_lds_dwordx4 v[6:7], off
	v_lshl_add_u64 v[6:7], v[222:223], 0, s[36:37]
	s_mov_b32 m0, s76
	s_nop 0
	global_load_lds_dwordx4 v[6:7], off
	v_lshl_add_u64 v[6:7], v[224:225], 0, s[36:37]
	s_mov_b32 m0, s77
	s_nop 0
	global_load_lds_dwordx4 v[6:7], off
	s_waitcnt vmcnt(8)
	s_waitcnt lgkmcnt(0)
	s_setprio 1
	s_barrier
	v_mfma_f32_16x16x32_bf16 v[64:67], v[150:153], v[188:191], v[64:67]
	v_mfma_f32_16x16x32_bf16 v[60:63], v[158:161], v[188:191], v[60:63]
	v_mfma_f32_16x16x32_bf16 v[48:51], v[150:153], v[196:199], v[48:51]
	v_mfma_f32_16x16x32_bf16 v[44:47], v[158:161], v[196:199], v[44:47]
	v_mfma_f32_16x16x32_bf16 v[32:35], v[150:153], v[204:207], v[32:35]
	v_mfma_f32_16x16x32_bf16 v[28:31], v[158:161], v[204:207], v[28:31]
	v_mfma_f32_16x16x32_bf16 v[16:19], v[150:153], v[212:215], v[16:19]
	v_mfma_f32_16x16x32_bf16 v[12:15], v[158:161], v[212:215], v[12:15]
	v_mfma_f32_16x16x32_bf16 v[64:67], v[154:157], v[192:195], v[64:67]
	v_mfma_f32_16x16x32_bf16 v[60:63], v[162:165], v[192:195], v[60:63]
	v_mfma_f32_16x16x32_bf16 v[48:51], v[154:157], v[200:203], v[48:51]
	v_mfma_f32_16x16x32_bf16 v[44:47], v[162:165], v[200:203], v[44:47]
	v_mfma_f32_16x16x32_bf16 v[32:35], v[154:157], v[208:211], v[32:35]
	v_mfma_f32_16x16x32_bf16 v[28:31], v[162:165], v[208:211], v[28:31]
	v_mfma_f32_16x16x32_bf16 v[16:19], v[154:157], v[216:219], v[16:19]
	v_mfma_f32_16x16x32_bf16 v[12:15], v[162:165], v[216:219], v[12:15]
	s_setprio 0
	s_setprio 1
	v_mfma_f32_16x16x32_bf16 v[56:59], v[166:169], v[188:191], v[56:59]
	v_mfma_f32_16x16x32_bf16 v[52:55], v[180:183], v[188:191], v[52:55]
	v_mfma_f32_16x16x32_bf16 v[40:43], v[166:169], v[196:199], v[40:43]
	v_mfma_f32_16x16x32_bf16 v[36:39], v[180:183], v[196:199], v[36:39]
	v_mfma_f32_16x16x32_bf16 v[24:27], v[166:169], v[204:207], v[24:27]
	v_mfma_f32_16x16x32_bf16 v[20:23], v[180:183], v[204:207], v[20:23]
	v_mfma_f32_16x16x32_bf16 v[6:9], v[166:169], v[212:215], v[8:11]
	v_mfma_f32_16x16x32_bf16 v[2:5], v[180:183], v[212:215], v[2:5]
	v_mfma_f32_16x16x32_bf16 v[56:59], v[176:179], v[192:195], v[56:59]
	v_mfma_f32_16x16x32_bf16 v[52:55], v[184:187], v[192:195], v[52:55]
	v_mfma_f32_16x16x32_bf16 v[40:43], v[176:179], v[200:203], v[40:43]
	v_mfma_f32_16x16x32_bf16 v[36:39], v[184:187], v[200:203], v[36:39]
	v_mfma_f32_16x16x32_bf16 v[24:27], v[176:179], v[208:211], v[24:27]
	v_mfma_f32_16x16x32_bf16 v[20:23], v[184:187], v[208:211], v[20:23]
	v_mfma_f32_16x16x32_bf16 v[8:11], v[176:179], v[216:219], v[6:9]
	v_mfma_f32_16x16x32_bf16 v[4:7], v[184:187], v[216:219], v[2:5]
	s_setprio 0
	s_barrier
	s_add_i32 s90, s90, 2
	s_add_u32 s58, s58, 0x100
	s_addc_u32 s59, s59, 0
	s_cmp_gt_u32 s90, 29
	s_cbranch_scc1 .LBB0_1266

; __device__ __forceinline__ int tid_of(int wv) { int l; asm volatile("v_mbcnt_lo_u32_b32 %0, -1, 0\n\tv_mbcnt_hi_u32_b32 %0, -1, %0" : "=v"(l)); return wv * 64 + l; }
; #define PG8_STAGE(bufoff, gbase, voff) do { _Pragma("unroll") for (int _i = 0; _i < 2; ++_i) \
;         __builtin_amdgcn_global_load_lds((const unsigned*)((const char*)(gbase) + (BYTE_ELEMS ? _i * r##voff + (v##voff)[0] : (v##voff)[_i])), (PG8_LAS unsigned*)(lds + (bufoff) + ldsw + _i * 8192), 16, 0, 0); } while (0)
; #define PG8_WAIT_V(n) asm volatile("s_waitcnt vmcnt(" #n ")" ::: "memory")
;     ...
;         const bool has_next = S.next(ui + 1, nxt);
;         const char* nA = has_next ? (const char*)g.A + (size_t)nxt.pm * tstepA : cA; const char* nB = has_next ? (const char*)g.Bt + (size_t)nxt.pn * tstepB : cB;
;         for (int t = 0; t < nt; t += 2) {
;             const bool last = (t == nt - 2);
;             const char* a1 = cA + (size_t)(t + 1) * kstep;
;             const char* a2 = last ? nA : cA + (size_t)(t + 2) * kstep; const char* b2 = last ? nB : cB + (size_t)(t + 2) * kstep;
;             const char* a3 = a2 + kstep; const char* b3 = b2 + kstep;
;             if (last && has_next) S.a_ready(nxt);
;             if constexpr (MID) { if (t == nt / 2) { const int t3 = tid_of(wv); E.mid(acc, cur, wid >> 2, t3 & 15); } }
;             if constexpr (SP2) {
;             PG8_LDB(B0, 0, 0); PG8_LDB(B1, 0, 1); PG8_SCHED; PG8_LDA(At, 0, 0); PG8_STAGE(PG8_SA(1, 1), a1 + hstepA, offA);
;             PG8_WAIT_V(8); PG8_WAIT_L(0); PG8_BAR; PG8_MMA(0, 0, At, B0); PG8_MMA(0, 1, At, B1); PG8_BAR; PG8_SCHED;
;             PG8_LDA(At, 0, 1); PG8_STAGE(PG8_SB(0, 0), b2, offB); PG8_STAGE(PG8_SB(0, 1), b2 + hstepB, offB); PG8_STAGE(PG8_SA(0, 0), a2, offA);
;             PG8_WAIT_V(8); PG8_WAIT_L(0); PG8_BAR; PG8_MMA(1, 0, At, B0); PG8_MMA(1, 1, At, B1); PG8_BAR; PG8_SCHED;
;             PG8_LDB(B0, 1, 0); PG8_LDB(B1, 1, 1); PG8_SCHED; PG8_LDA(At, 1, 0); PG8_STAGE(PG8_SA(0, 1), a2 + hstepA, offA);
;             PG8_WAIT_V(8); PG8_WAIT_L(0); PG8_BAR; PG8_MMA(0, 0, At, B0); PG8_MMA(0, 1, At, B1); PG8_BAR; PG8_SCHED;
;             PG8_LDA(At, 1, 1); PG8_STAGE(PG8_SB(1, 0), b3, offB); PG8_STAGE(PG8_SB(1, 1), b3 + hstepB, offB); PG8_STAGE(PG8_SA(1, 0), a3, offA);
;             PG8_WAIT_V(8); PG8_WAIT_L(0); PG8_BAR; PG8_MMA(1, 0, At, B0); PG8_MMA(1, 1, At, B1); PG8_BAR; PG8_SCHED;
.LBB0_1391:
	ds_read_b128 v[128:131], v159
	ds_read_b128 v[132:135], v159 offset:1024
	ds_read_b128 v[136:139], v159 offset:2048
	ds_read_b128 v[140:143], v159 offset:3072
	ds_read_b128 v[160:163], v170
	ds_read_b128 v[164:167], v170 offset:1024
	ds_read_b128 v[174:177], v170 offset:2048
	ds_read_b128 v[178:181], v170 offset:3072
	s_add_u32 s89, s64, 0xfffc0080
	s_addc_u32 s90, s65, -1
	s_cmp_eq_u32 s88, 12
	s_cselect_b32 s91, s55, s90
	s_cselect_b32 s90, s86, s89
	s_cselect_b32 s93, s53, s67
	s_cselect_b32 s92, s87, s66
	v_lshl_add_u64 v[152:153], s[64:65], 0, v[148:149]
	s_add_i32 m0, s63, 0xc000
	ds_read_b128 v[182:185], v171
	ds_read_b128 v[186:189], v171 offset:1024
	ds_read_b128 v[190:193], v171 offset:2048
	ds_read_b128 v[194:197], v171 offset:3072
	ds_read_b128 v[198:201], v171 offset:4096
	ds_read_b128 v[202:205], v171 offset:5120
	ds_read_b128 v[206:209], v171 offset:6144
	ds_read_b128 v[210:213], v171 offset:7168
	global_load_lds_dwordx4 v[152:153], off
	v_lshl_add_u64 v[152:153], v[152:153], 0, s[4:5]
	s_add_i32 m0, s63, 0xe000
	s_nop 0
	global_load_lds_dwordx4 v[152:153], off
	s_waitcnt vmcnt(8)
	s_waitcnt lgkmcnt(0)
	s_setprio 1
	s_barrier
	v_mfma_i32_16x16x64_i8 v[124:127], v[128:131], v[182:185], v[124:127]
	v_mfma_i32_16x16x64_i8 v[116:119], v[136:139], v[182:185], v[116:119]
	v_mfma_i32_16x16x64_i8 v[108:111], v[128:131], v[190:193], v[108:111]
	v_mfma_i32_16x16x64_i8 v[100:103], v[136:139], v[190:193], v[100:103]
	v_mfma_i32_16x16x64_i8 v[92:95], v[128:131], v[198:201], v[92:95]
	v_mfma_i32_16x16x64_i8 v[84:87], v[136:139], v[198:201], v[84:87]
	v_mfma_i32_16x16x64_i8 v[76:79], v[128:131], v[206:209], v[76:79]
	v_mfma_i32_16x16x64_i8 v[68:71], v[136:139], v[206:209], v[68:71]
	v_mfma_i32_16x16x64_i8 v[124:127], v[132:135], v[186:189], v[124:127]
	v_mfma_i32_16x16x64_i8 v[116:119], v[140:143], v[186:189], v[116:119]
	v_mfma_i32_16x16x64_i8 v[108:111], v[132:135], v[194:197], v[108:111]
	v_mfma_i32_16x16x64_i8 v[100:103], v[140:143], v[194:197], v[100:103]
	v_mfma_i32_16x16x64_i8 v[92:95], v[132:135], v[202:205], v[92:95]
	v_mfma_i32_16x16x64_i8 v[84:87], v[140:143], v[202:205], v[84:87]
	v_mfma_i32_16x16x64_i8 v[76:79], v[132:135], v[210:213], v[76:79]
	v_mfma_i32_16x16x64_i8 v[68:71], v[140:143], v[210:213], v[68:71]
	s_setprio 0
	s_setprio 1
	v_mfma_i32_16x16x64_i8 v[120:123], v[160:163], v[182:185], v[120:123]
	v_mfma_i32_16x16x64_i8 v[112:115], v[174:177], v[182:185], v[112:115]
	v_mfma_i32_16x16x64_i8 v[104:107], v[160:163], v[190:193], v[104:107]
	v_mfma_i32_16x16x64_i8 v[96:99], v[174:177], v[190:193], v[96:99]
	v_mfma_i32_16x16x64_i8 v[88:91], v[160:163], v[198:201], v[88:91]
	v_mfma_i32_16x16x64_i8 v[80:83], v[174:177], v[198:201], v[80:83]
	v_mfma_i32_16x16x64_i8 v[72:75], v[160:163], v[206:209], v[72:75]
	v_mfma_i32_16x16x64_i8 v[64:67], v[174:177], v[206:209], v[64:67]
	v_mfma_i32_16x16x64_i8 v[120:123], v[164:167], v[186:189], v[120:123]
	v_mfma_i32_16x16x64_i8 v[112:115], v[178:181], v[186:189], v[112:115]
	v_mfma_i32_16x16x64_i8 v[104:107], v[164:167], v[194:197], v[104:107]
	v_mfma_i32_16x16x64_i8 v[96:99], v[178:181], v[194:197], v[96:99]
	v_mfma_i32_16x16x64_i8 v[88:91], v[164:167], v[202:205], v[88:91]
	v_mfma_i32_16x16x64_i8 v[80:83], v[178:181], v[202:205], v[80:83]
	v_mfma_i32_16x16x64_i8 v[72:75], v[164:167], v[210:213], v[72:75]
	v_mfma_i32_16x16x64_i8 v[64:67], v[178:181], v[210:213], v[64:67]
	s_setprio 0
	s_barrier
	s_add_i32 s89, s81, s51
	v_lshl_add_u64 v[152:153], s[92:93], 0, v[144:145]
	s_mov_b32 m0, s89
	ds_read_b128 v[182:185], v171 offset:16384
	ds_read_b128 v[186:189], v171 offset:17408
	ds_read_b128 v[190:193], v171 offset:18432
	ds_read_b128 v[194:197], v171 offset:19456
	ds_read_b128 v[198:201], v171 offset:20480
	ds_read_b128 v[202:205], v171 offset:21504
	ds_read_b128 v[206:209], v171 offset:22528
	ds_read_b128 v[210:213], v171 offset:23552
	global_load_lds_dwordx4 v[152:153], off
	v_lshl_add_u64 v[156:157], v[152:153], 0, s[4:5]
	s_add_i32 m0, s89, 0x2000
	s_add_i32 s89, s82, s51
	global_load_lds_dwordx4 v[156:157], off
	v_lshl_add_u64 v[156:157], v[152:153], 0, s[18:19]
	s_mov_b32 m0, s89
	s_nop 0
	global_load_lds_dwordx4 v[156:157], off
	v_lshl_add_u64 v[156:157], v[152:153], 0, s[20:21]
	s_add_i32 m0, s89, 0x2000
	s_nop 0
	global_load_lds_dwordx4 v[156:157], off
	v_lshl_add_u64 v[156:157], s[90:91], 0, v[146:147]
	s_mov_b32 m0, s63
	v_lshl_add_u64 v[168:169], v[156:157], 0, s[4:5]
	global_load_lds_dwordx4 v[156:157], off
	s_mov_b32 m0, s70
	s_nop 0
	global_load_lds_dwordx4 v[168:169], off
	s_waitcnt vmcnt(8)
	s_waitcnt lgkmcnt(0)
	s_setprio 1
	s_barrier
; #define PG8_STAGE(bufoff, gbase, voff) do { _Pragma("unroll") for (int _i = 0; _i < 2; ++_i) \
;         __builtin_amdgcn_global_load_lds((const unsigned*)((const char*)(gbase) + (BYTE_ELEMS ? _i * r##voff + (v##voff)[0] : (v##voff)[_i])), (PG8_LAS unsigned*)(lds + (bufoff) + ldsw + _i * 8192), 16, 0, 0); } while (0)
; #define PG8_LDA(dst, b, h) do { _Pragma("unroll") for (int m = 0; m < 4; ++m) _Pragma("unroll") for (int k = 0; k < 2; ++k) dst[m][k] = *(const PG8_LAS bf16x8*)(lds + PG8_SA(b, h) + aoff + m * 2048 + k * 1024); } while (0)
; #define PG8_LDB(dst, b, h) do { _Pragma("unroll") for (int n = 0; n < 2; ++n) _Pragma("unroll") for (int k = 0; k < 2; ++k) dst[n][k] = *(const PG8_LAS bf16x8*)(lds + PG8_SB(b, h) + boff + n * 2048 + k * 1024); } while (0)
; #define PG8_WAIT_V(n) asm volatile("s_waitcnt vmcnt(" #n ")" ::: "memory")
; #define PG8_WAIT_L(n) asm volatile("s_waitcnt lgkmcnt(" #n ")" ::: "memory")
; #define PG8_BAR __builtin_amdgcn_s_barrier()
; #define PG8_SCHED __builtin_amdgcn_sched_barrier(0)
;     ...
;             PG8_LDB(B0, 0, 0); PG8_LDB(B1, 0, 1); PG8_SCHED; PG8_LDA(At, 0, 0); PG8_STAGE(PG8_SA(1, 1), a1 + hstepA, offA);
;             PG8_WAIT_V(8); PG8_WAIT_L(0); PG8_BAR; PG8_MMA(0, 0, At, B0); PG8_MMA(0, 1, At, B1); PG8_BAR; PG8_SCHED;
;             PG8_LDA(At, 0, 1); PG8_STAGE(PG8_SB(0, 0), b2, offB); PG8_STAGE(PG8_SB(0, 1), b2 + hstepB, offB); PG8_STAGE(PG8_SA(0, 0), a2, offA);
;             PG8_WAIT_V(8); PG8_WAIT_L(0); PG8_BAR; PG8_MMA(1, 0, At, B0); PG8_MMA(1, 1, At, B1); PG8_BAR; PG8_SCHED;
;             PG8_LDB(B0, 1, 0); PG8_LDB(B1, 1, 1); PG8_SCHED; PG8_LDA(At, 1, 0); PG8_STAGE(PG8_SA(0, 1), a2 + hstepA, offA);
;             PG8_WAIT_V(8); PG8_WAIT_L(0); PG8_BAR; PG8_MMA(0, 0, At, B0); PG8_MMA(0, 1, At, B1); PG8_BAR; PG8_SCHED;
;             PG8_LDA(At, 1, 1); PG8_STAGE(PG8_SB(1, 0), b3, offB); PG8_STAGE(PG8_SB(1, 1), b3 + hstepB, offB); PG8_STAGE(PG8_SA(1, 0), a3, offA);
;             PG8_WAIT_V(8); PG8_WAIT_L(0); PG8_BAR; PG8_MMA(1, 0, At, B0); PG8_MMA(1, 1, At, B1); PG8_BAR; PG8_SCHED;
	v_mfma_i32_16x16x64_i8 v[20:23], v[128:131], v[182:185], v[20:23]
	v_mfma_i32_16x16x64_i8 v[28:31], v[136:139], v[182:185], v[28:31]
	v_mfma_i32_16x16x64_i8 v[36:39], v[128:131], v[190:193], v[36:39]
	v_mfma_i32_16x16x64_i8 v[44:47], v[136:139], v[190:193], v[44:47]
	v_mfma_i32_16x16x64_i8 v[52:55], v[128:131], v[198:201], v[52:55]
	v_mfma_i32_16x16x64_i8 v[60:63], v[136:139], v[198:201], v[60:63]
	v_mfma_i32_16x16x64_i8 v[12:15], v[128:131], v[206:209], v[12:15]
	v_mfma_i32_16x16x64_i8 v[4:7], v[136:139], v[206:209], v[4:7]
	v_mfma_i32_16x16x64_i8 v[20:23], v[132:135], v[186:189], v[20:23]
	v_mfma_i32_16x16x64_i8 v[28:31], v[140:143], v[186:189], v[28:31]
	v_mfma_i32_16x16x64_i8 v[36:39], v[132:135], v[194:197], v[36:39]
	v_mfma_i32_16x16x64_i8 v[44:47], v[140:143], v[194:197], v[44:47]
	v_mfma_i32_16x16x64_i8 v[52:55], v[132:135], v[202:205], v[52:55]
	v_mfma_i32_16x16x64_i8 v[60:63], v[140:143], v[202:205], v[60:63]
	v_mfma_i32_16x16x64_i8 v[12:15], v[132:135], v[210:213], v[12:15]
	v_mfma_i32_16x16x64_i8 v[4:7], v[140:143], v[210:213], v[4:7]
	s_setprio 0
	s_setprio 1
	v_mfma_i32_16x16x64_i8 v[16:19], v[160:163], v[182:185], v[16:19]
	v_mfma_i32_16x16x64_i8 v[24:27], v[174:177], v[182:185], v[24:27]
	v_mfma_i32_16x16x64_i8 v[32:35], v[160:163], v[190:193], v[32:35]
	v_mfma_i32_16x16x64_i8 v[40:43], v[174:177], v[190:193], v[40:43]
	v_mfma_i32_16x16x64_i8 v[48:51], v[160:163], v[198:201], v[48:51]
	v_mfma_i32_16x16x64_i8 v[56:59], v[174:177], v[198:201], v[56:59]
	v_mfma_i32_16x16x64_i8 v[8:11], v[160:163], v[206:209], v[8:11]
	v_mfma_i32_16x16x64_i8 v[0:3], v[174:177], v[206:209], v[0:3]
	v_mfma_i32_16x16x64_i8 v[16:19], v[164:167], v[186:189], v[16:19]
	v_mfma_i32_16x16x64_i8 v[24:27], v[178:181], v[186:189], v[24:27]
	v_mfma_i32_16x16x64_i8 v[32:35], v[164:167], v[194:197], v[32:35]
	v_mfma_i32_16x16x64_i8 v[40:43], v[178:181], v[194:197], v[40:43]
	v_mfma_i32_16x16x64_i8 v[48:51], v[164:167], v[202:205], v[48:51]
	v_mfma_i32_16x16x64_i8 v[56:59], v[178:181], v[202:205], v[56:59]
	v_mfma_i32_16x16x64_i8 v[8:11], v[164:167], v[210:213], v[8:11]
	v_mfma_i32_16x16x64_i8 v[0:3], v[178:181], v[210:213], v[0:3]
	s_setprio 0
	s_barrier
	s_add_i32 s89, 0, 0x18000
	s_add_i32 s90, 0, 0x1c000
	v_add_u32_e32 v140, s89, v155
	v_add_u32_e32 v154, s90, v155
	ds_read_b128 v[128:131], v140
	ds_read_b128 v[132:135], v140 offset:1024
	ds_read_b128 v[136:139], v140 offset:2048
	ds_read_b128 v[140:143], v140 offset:3072
	ds_read_b128 v[160:163], v154
	ds_read_b128 v[164:167], v154 offset:1024
	ds_read_b128 v[174:177], v154 offset:2048
	ds_read_b128 v[178:181], v154 offset:3072
	s_mov_b32 m0, s71
	v_lshl_add_u64 v[168:169], v[156:157], 0, s[18:19]
	ds_read_b128 v[182:185], v171 offset:32768
	ds_read_b128 v[186:189], v171 offset:33792
	ds_read_b128 v[190:193], v171 offset:34816
	ds_read_b128 v[194:197], v171 offset:35840
	ds_read_b128 v[198:201], v171 offset:36864
	ds_read_b128 v[202:205], v171 offset:37888
	ds_read_b128 v[206:209], v171 offset:38912
	ds_read_b128 v[210:213], v171 offset:39936
	global_load_lds_dwordx4 v[168:169], off
	v_lshl_add_u64 v[168:169], v[156:157], 0, s[20:21]
	s_mov_b32 m0, s72
	s_nop 0
	global_load_lds_dwordx4 v[168:169], off
	s_waitcnt vmcnt(8)
	s_waitcnt lgkmcnt(0)
	s_setprio 1
	s_barrier
	v_mfma_i32_16x16x64_i8 v[124:127], v[128:131], v[182:185], v[124:127]
	v_mfma_i32_16x16x64_i8 v[116:119], v[136:139], v[182:185], v[116:119]
	v_mfma_i32_16x16x64_i8 v[108:111], v[128:131], v[190:193], v[108:111]
	v_mfma_i32_16x16x64_i8 v[100:103], v[136:139], v[190:193], v[100:103]
	v_mfma_i32_16x16x64_i8 v[92:95], v[128:131], v[198:201], v[92:95]
	v_mfma_i32_16x16x64_i8 v[84:87], v[136:139], v[198:201], v[84:87]
	v_mfma_i32_16x16x64_i8 v[76:79], v[128:131], v[206:209], v[76:79]
	v_mfma_i32_16x16x64_i8 v[68:71], v[136:139], v[206:209], v[68:71]
	v_mfma_i32_16x16x64_i8 v[124:127], v[132:135], v[186:189], v[124:127]
	v_mfma_i32_16x16x64_i8 v[116:119], v[140:143], v[186:189], v[116:119]
	v_mfma_i32_16x16x64_i8 v[108:111], v[132:135], v[194:197], v[108:111]
	v_mfma_i32_16x16x64_i8 v[100:103], v[140:143], v[194:197], v[100:103]
	v_mfma_i32_16x16x64_i8 v[92:95], v[132:135], v[202:205], v[92:95]
	v_mfma_i32_16x16x64_i8 v[84:87], v[140:143], v[202:205], v[84:87]
	v_mfma_i32_16x16x64_i8 v[76:79], v[132:135], v[210:213], v[76:79]
	v_mfma_i32_16x16x64_i8 v[68:71], v[140:143], v[210:213], v[68:71]
	s_setprio 0
	s_setprio 1
	v_mfma_i32_16x16x64_i8 v[120:123], v[160:163], v[182:185], v[120:123]
	v_mfma_i32_16x16x64_i8 v[112:115], v[174:177], v[182:185], v[112:115]
	v_mfma_i32_16x16x64_i8 v[104:107], v[160:163], v[190:193], v[104:107]
	v_mfma_i32_16x16x64_i8 v[96:99], v[174:177], v[190:193], v[96:99]
	v_mfma_i32_16x16x64_i8 v[88:91], v[160:163], v[198:201], v[88:91]
	v_mfma_i32_16x16x64_i8 v[80:83], v[174:177], v[198:201], v[80:83]
	v_mfma_i32_16x16x64_i8 v[72:75], v[160:163], v[206:209], v[72:75]
	v_mfma_i32_16x16x64_i8 v[64:67], v[174:177], v[206:209], v[64:67]
	v_mfma_i32_16x16x64_i8 v[120:123], v[164:167], v[186:189], v[120:123]
	v_mfma_i32_16x16x64_i8 v[112:115], v[178:181], v[186:189], v[112:115]
	v_mfma_i32_16x16x64_i8 v[104:107], v[164:167], v[194:197], v[104:107]
	v_mfma_i32_16x16x64_i8 v[96:99], v[178:181], v[194:197], v[96:99]
	v_mfma_i32_16x16x64_i8 v[88:91], v[164:167], v[202:205], v[88:91]
	v_mfma_i32_16x16x64_i8 v[80:83], v[178:181], v[202:205], v[80:83]
	v_mfma_i32_16x16x64_i8 v[72:75], v[164:167], v[210:213], v[72:75]
	v_mfma_i32_16x16x64_i8 v[64:67], v[178:181], v[210:213], v[64:67]
	s_setprio 0
	s_barrier
; #define PG8_STAGE(bufoff, gbase, voff) do { _Pragma("unroll") for (int _i = 0; _i < 2; ++_i) \
;         __builtin_amdgcn_global_load_lds((const unsigned*)((const char*)(gbase) + (BYTE_ELEMS ? _i * r##voff + (v##voff)[0] : (v##voff)[_i])), (PG8_LAS unsigned*)(lds + (bufoff) + ldsw + _i * 8192), 16, 0, 0); } while (0)
; #define PG8_LDA(dst, b, h) do { _Pragma("unroll") for (int m = 0; m < 4; ++m) _Pragma("unroll") for (int k = 0; k < 2; ++k) dst[m][k] = *(const PG8_LAS bf16x8*)(lds + PG8_SA(b, h) + aoff + m * 2048 + k * 1024); } while (0)
; #define PG8_WAIT_V(n) asm volatile("s_waitcnt vmcnt(" #n ")" ::: "memory")
; #define PG8_WAIT_L(n) asm volatile("s_waitcnt lgkmcnt(" #n ")" ::: "memory")
; #define PG8_BAR __builtin_amdgcn_s_barrier()
; #define PG8_SCHED __builtin_amdgcn_sched_barrier(0)
;     ...
;         for (int t = 0; t < nt; t += 2) {
;     ...
;             PG8_LDA(At, 1, 1); PG8_STAGE(PG8_SB(1, 0), b3, offB); PG8_STAGE(PG8_SB(1, 1), b3 + hstepB, offB); PG8_STAGE(PG8_SA(1, 0), a3, offA);
;             PG8_WAIT_V(8); PG8_WAIT_L(0); PG8_BAR; PG8_MMA(1, 0, At, B0); PG8_MMA(1, 1, At, B1); PG8_BAR; PG8_SCHED;
	s_add_i32 s89, s89, s51
	v_lshl_add_u64 v[168:169], v[152:153], 0, s[40:41]
	s_mov_b32 m0, s89
	ds_read_b128 v[182:185], v171 offset:49152
	ds_read_b128 v[186:189], v171 offset:50176
	ds_read_b128 v[190:193], v171 offset:51200
	ds_read_b128 v[194:197], v171 offset:52224
	ds_read_b128 v[198:201], v171 offset:53248
	ds_read_b128 v[202:205], v171 offset:54272
	ds_read_b128 v[206:209], v171 offset:55296
	ds_read_b128 v[210:213], v171 offset:56320
	global_load_lds_dwordx4 v[168:169], off
	v_lshl_add_u64 v[168:169], v[152:153], 0, s[42:43]
	s_add_i32 m0, s89, 0x2000
	s_add_i32 s89, s90, s51
	global_load_lds_dwordx4 v[168:169], off
	v_lshl_add_u64 v[168:169], v[152:153], 0, s[44:45]
	s_mov_b32 m0, s89
	v_lshl_add_u64 v[152:153], v[152:153], 0, s[46:47]
	global_load_lds_dwordx4 v[168:169], off
	s_add_i32 m0, s89, 0x2000
	s_nop 0
	global_load_lds_dwordx4 v[152:153], off
	v_lshl_add_u64 v[152:153], v[156:157], 0, s[40:41]
	s_mov_b32 m0, s76
	s_nop 0
	global_load_lds_dwordx4 v[152:153], off
	v_lshl_add_u64 v[152:153], v[156:157], 0, s[42:43]
	s_mov_b32 m0, s77
	s_nop 0
	global_load_lds_dwordx4 v[152:153], off
	s_waitcnt vmcnt(8)
	s_waitcnt lgkmcnt(0)
	s_setprio 1
	s_barrier
	v_mfma_i32_16x16x64_i8 v[20:23], v[128:131], v[182:185], v[20:23]
	v_mfma_i32_16x16x64_i8 v[28:31], v[136:139], v[182:185], v[28:31]
	v_mfma_i32_16x16x64_i8 v[36:39], v[128:131], v[190:193], v[36:39]
	v_mfma_i32_16x16x64_i8 v[44:47], v[136:139], v[190:193], v[44:47]
	v_mfma_i32_16x16x64_i8 v[52:55], v[128:131], v[198:201], v[52:55]
	v_mfma_i32_16x16x64_i8 v[60:63], v[136:139], v[198:201], v[60:63]
	v_mfma_i32_16x16x64_i8 v[12:15], v[128:131], v[206:209], v[12:15]
	v_mfma_i32_16x16x64_i8 v[4:7], v[136:139], v[206:209], v[4:7]
	v_mfma_i32_16x16x64_i8 v[20:23], v[132:135], v[186:189], v[20:23]
	v_mfma_i32_16x16x64_i8 v[28:31], v[140:143], v[186:189], v[28:31]
	v_mfma_i32_16x16x64_i8 v[36:39], v[132:135], v[194:197], v[36:39]
	v_mfma_i32_16x16x64_i8 v[44:47], v[140:143], v[194:197], v[44:47]
	v_mfma_i32_16x16x64_i8 v[52:55], v[132:135], v[202:205], v[52:55]
	v_mfma_i32_16x16x64_i8 v[60:63], v[140:143], v[202:205], v[60:63]
	v_mfma_i32_16x16x64_i8 v[12:15], v[132:135], v[210:213], v[12:15]
	v_mfma_i32_16x16x64_i8 v[4:7], v[140:143], v[210:213], v[4:7]
	s_setprio 0
	s_setprio 1
	v_mfma_i32_16x16x64_i8 v[16:19], v[160:163], v[182:185], v[16:19]
	v_mfma_i32_16x16x64_i8 v[24:27], v[174:177], v[182:185], v[24:27]
	v_mfma_i32_16x16x64_i8 v[32:35], v[160:163], v[190:193], v[32:35]
	v_mfma_i32_16x16x64_i8 v[40:43], v[174:177], v[190:193], v[40:43]
	v_mfma_i32_16x16x64_i8 v[48:51], v[160:163], v[198:201], v[48:51]
	v_mfma_i32_16x16x64_i8 v[56:59], v[174:177], v[198:201], v[56:59]
	v_mfma_i32_16x16x64_i8 v[8:11], v[160:163], v[206:209], v[8:11]
	v_mfma_i32_16x16x64_i8 v[0:3], v[174:177], v[206:209], v[0:3]
	v_mfma_i32_16x16x64_i8 v[16:19], v[164:167], v[186:189], v[16:19]
	v_mfma_i32_16x16x64_i8 v[24:27], v[178:181], v[186:189], v[24:27]
	v_mfma_i32_16x16x64_i8 v[32:35], v[164:167], v[194:197], v[32:35]
	v_mfma_i32_16x16x64_i8 v[40:43], v[178:181], v[194:197], v[40:43]
	v_mfma_i32_16x16x64_i8 v[48:51], v[164:167], v[202:205], v[48:51]
	v_mfma_i32_16x16x64_i8 v[56:59], v[178:181], v[202:205], v[56:59]
	v_mfma_i32_16x16x64_i8 v[8:11], v[164:167], v[210:213], v[8:11]
	v_mfma_i32_16x16x64_i8 v[0:3], v[178:181], v[210:213], v[0:3]
	s_setprio 0
	s_barrier
	s_add_i32 s88, s88, 2
	s_add_u32 s64, s64, 0x100
	s_addc_u32 s65, s65, 0
	s_add_u32 s66, s66, 0x100
	s_addc_u32 s67, s67, 0
	s_cmp_gt_u32 s88, 13
	s_cbranch_scc0 .LBB0_1391
	s_and_b64 vcc, exec, s[48:49]
	s_cbranch_vccz .LBB0_1394
	s_barrier

; __device__ __forceinline__ int tid_of(int wv) { int l; asm volatile("v_mbcnt_lo_u32_b32 %0, -1, 0\n\tv_mbcnt_hi_u32_b32 %0, -1, %0" : "=v"(l)); return wv * 64 + l; }
; #define PG8_STAGE(bufoff, gbase, voff) do { _Pragma("unroll") for (int _i = 0; _i < 2; ++_i) \
;         __builtin_amdgcn_global_load_lds((const unsigned*)((const char*)(gbase) + (BYTE_ELEMS ? _i * r##voff + (v##voff)[0] : (v##voff)[_i])), (PG8_LAS unsigned*)(lds + (bufoff) + ldsw + _i * 8192), 16, 0, 0); } while (0)
; #define PG8_WAIT_V(n) asm volatile("s_waitcnt vmcnt(" #n ")" ::: "memory")
;     ...
;         const bool has_next = S.next(ui + 1, nxt);
;         const char* nA = has_next ? (const char*)g.A + (size_t)nxt.pm * tstepA : cA; const char* nB = has_next ? (const char*)g.Bt + (size_t)nxt.pn * tstepB : cB;
;         for (int t = 0; t < nt; t += 2) {
;             const bool last = (t == nt - 2);
;             const char* a1 = cA + (size_t)(t + 1) * kstep;
;             const char* a2 = last ? nA : cA + (size_t)(t + 2) * kstep; const char* b2 = last ? nB : cB + (size_t)(t + 2) * kstep;
;             const char* a3 = a2 + kstep; const char* b3 = b2 + kstep;
;             if (last && has_next) S.a_ready(nxt);
;             if constexpr (MID) { if (t == nt / 2) { const int t3 = tid_of(wv); E.mid(acc, cur, wid >> 2, t3 & 15); } }
;             if constexpr (SP2) {
;             PG8_LDB(B0, 0, 0); PG8_LDB(B1, 0, 1); PG8_SCHED; PG8_LDA(At, 0, 0); PG8_STAGE(PG8_SA(1, 1), a1 + hstepA, offA);
;             PG8_WAIT_V(8); PG8_WAIT_L(0); PG8_BAR; PG8_MMA(0, 0, At, B0); PG8_MMA(0, 1, At, B1); PG8_BAR; PG8_SCHED;
;             PG8_LDA(At, 0, 1); PG8_STAGE(PG8_SB(0, 0), b2, offB); PG8_STAGE(PG8_SB(0, 1), b2 + hstepB, offB); PG8_STAGE(PG8_SA(0, 0), a2, offA);
;             PG8_WAIT_V(8); PG8_WAIT_L(0); PG8_BAR; PG8_MMA(1, 0, At, B0); PG8_MMA(1, 1, At, B1); PG8_BAR; PG8_SCHED;
;             PG8_LDB(B0, 1, 0); PG8_LDB(B1, 1, 1); PG8_SCHED; PG8_LDA(At, 1, 0); PG8_STAGE(PG8_SA(0, 1), a2 + hstepA, offA);
;             PG8_WAIT_V(8); PG8_WAIT_L(0); PG8_BAR; PG8_MMA(0, 0, At, B0); PG8_MMA(0, 1, At, B1); PG8_BAR; PG8_SCHED;
;             PG8_LDA(At, 1, 1); PG8_STAGE(PG8_SB(1, 0), b3, offB); PG8_STAGE(PG8_SB(1, 1), b3 + hstepB, offB); PG8_STAGE(PG8_SA(1, 0), a3, offA);
;             PG8_WAIT_V(8); PG8_WAIT_L(0); PG8_BAR; PG8_MMA(1, 0, At, B0); PG8_MMA(1, 1, At, B1); PG8_BAR; PG8_SCHED;
.LBB0_1466:
	ds_read_b128 v[136:139], v149
	ds_read_b128 v[140:143], v149 offset:1024
	ds_read_b128 v[152:155], v149 offset:2048
	ds_read_b128 v[156:159], v149 offset:3072
	ds_read_b128 v[160:163], v150
	ds_read_b128 v[164:167], v150 offset:1024
	ds_read_b128 v[168:171], v150 offset:2048
	ds_read_b128 v[172:175], v150 offset:3072
	s_add_u32 s56, s54, 0xfff50080
	s_addc_u32 s57, s55, -1
	s_cmp_eq_u32 s81, 40
	s_cselect_b32 s57, s51, s57
	s_cselect_b32 s56, s50, s56
	s_cselect_b32 s59, s53, s80
	s_cselect_b32 s58, s52, s79
	v_lshl_add_u64 v[144:145], s[54:55], 0, v[132:133]
	s_add_i32 m0, s49, 0xc000
	ds_read_b128 v[176:179], v151
	ds_read_b128 v[180:183], v151 offset:1024
	ds_read_b128 v[184:187], v151 offset:2048
	ds_read_b128 v[188:191], v151 offset:3072
	ds_read_b128 v[192:195], v151 offset:4096
	ds_read_b128 v[196:199], v151 offset:5120
	ds_read_b128 v[200:203], v151 offset:6144
	ds_read_b128 v[204:207], v151 offset:7168
	global_load_lds_dwordx4 v[144:145], off
	v_lshl_add_u64 v[144:145], v[144:145], 0, s[4:5]
	s_add_i32 m0, s49, 0xe000
	s_nop 0
	global_load_lds_dwordx4 v[144:145], off
	s_waitcnt vmcnt(8)
	s_waitcnt lgkmcnt(0)
	s_setprio 1
	s_barrier
	v_mfma_f32_16x16x128_f8f6f4 v[124:127], v[136:143], v[176:183], v[124:127]
	v_mfma_f32_16x16x128_f8f6f4 v[120:123], v[152:159], v[176:183], v[120:123]
	v_mfma_f32_16x16x128_f8f6f4 v[108:111], v[136:143], v[184:191], v[108:111]
	v_mfma_f32_16x16x128_f8f6f4 v[104:107], v[152:159], v[184:191], v[104:107]
	v_mfma_f32_16x16x128_f8f6f4 v[144:147], v[136:143], v[192:199], v[92:95]
	v_mfma_f32_16x16x128_f8f6f4 v[208:211], v[152:159], v[192:199], v[88:91]
	v_mfma_f32_16x16x128_f8f6f4 v[212:215], v[136:143], v[200:207], v[76:79]
	v_mfma_f32_16x16x128_f8f6f4 v[216:219], v[152:159], v[200:207], v[72:75]
	s_setprio 0
	s_setprio 1
	v_mfma_f32_16x16x128_f8f6f4 v[116:119], v[160:167], v[176:183], v[116:119]
	v_mfma_f32_16x16x128_f8f6f4 v[112:115], v[168:175], v[176:183], v[112:115]
	v_mfma_f32_16x16x128_f8f6f4 v[100:103], v[160:167], v[184:191], v[100:103]
	v_mfma_f32_16x16x128_f8f6f4 v[96:99], v[168:175], v[184:191], v[96:99]
	v_mfma_f32_16x16x128_f8f6f4 v[176:179], v[160:167], v[192:199], v[84:87]
	v_mfma_f32_16x16x128_f8f6f4 v[180:183], v[168:175], v[192:199], v[80:83]
	v_mfma_f32_16x16x128_f8f6f4 v[184:187], v[160:167], v[200:207], v[68:71]
	v_mfma_f32_16x16x128_f8f6f4 v[188:191], v[168:175], v[200:207], v[64:67]
	s_setprio 0
	s_barrier
	v_lshl_add_u64 v[252:253], s[58:59], 0, v[130:131]
	s_add_i32 s58, s71, s33
	s_mov_b32 m0, s58
	s_nop 1
	ds_read_b128 v[64:67], v151 offset:16384
	ds_read_b128 v[68:71], v151 offset:17408
	ds_read_b128 v[72:75], v151 offset:18432
	ds_read_b128 v[76:79], v151 offset:19456
	ds_read_b128 v[80:83], v151 offset:20480
	ds_read_b128 v[84:87], v151 offset:21504
	ds_read_b128 v[88:91], v151 offset:22528
	ds_read_b128 v[92:95], v151 offset:23552
	global_load_lds_dwordx4 v[252:253], off
	v_lshl_add_u64 v[192:193], v[252:253], 0, s[4:5]
	s_add_i32 m0, s58, 0x2000
	s_add_i32 s58, s72, s33
	global_load_lds_dwordx4 v[192:193], off
	v_lshl_add_u64 v[192:193], v[252:253], 0, s[16:17]
	s_mov_b32 m0, s58
	v_lshl_add_u64 v[254:255], s[56:57], 0, v[128:129]
	global_load_lds_dwordx4 v[192:193], off
	v_lshl_add_u64 v[192:193], v[252:253], 0, s[18:19]
	s_add_i32 m0, s58, 0x2000
	s_nop 0
	global_load_lds_dwordx4 v[192:193], off
	s_mov_b32 m0, s49
	v_lshl_add_u64 v[192:193], v[254:255], 0, s[4:5]
	global_load_lds_dwordx4 v[254:255], off
	s_mov_b32 m0, s60
	s_nop 0
	global_load_lds_dwordx4 v[192:193], off
	s_waitcnt vmcnt(8)
	s_waitcnt lgkmcnt(0)
	s_setprio 1
	s_barrier
	v_mfma_f32_16x16x128_f8f6f4 v[60:63], v[136:143], v[64:71], v[60:63]
	v_mfma_f32_16x16x128_f8f6f4 v[56:59], v[152:159], v[64:71], v[56:59]
	v_mfma_f32_16x16x128_f8f6f4 v[192:195], v[136:143], v[72:79], v[44:47]
	v_mfma_f32_16x16x128_f8f6f4 v[196:199], v[152:159], v[72:79], v[40:43]
	v_mfma_f32_16x16x128_f8f6f4 v[200:203], v[136:143], v[80:87], v[28:31]
	v_mfma_f32_16x16x128_f8f6f4 v[204:207], v[152:159], v[80:87], v[24:27]
	v_mfma_f32_16x16x128_f8f6f4 v[220:223], v[136:143], v[88:95], v[12:15]
	v_mfma_f32_16x16x128_f8f6f4 v[224:227], v[152:159], v[88:95], v[8:11]
	s_setprio 0
	s_setprio 1
	v_mfma_f32_16x16x128_f8f6f4 v[52:55], v[160:167], v[64:71], v[52:55]
	v_mfma_f32_16x16x128_f8f6f4 v[48:51], v[168:175], v[64:71], v[48:51]
	v_mfma_f32_16x16x128_f8f6f4 v[228:231], v[160:167], v[72:79], v[36:39]
	v_mfma_f32_16x16x128_f8f6f4 v[232:235], v[168:175], v[72:79], v[32:35]
	v_mfma_f32_16x16x128_f8f6f4 v[236:239], v[160:167], v[80:87], v[20:23]
	v_mfma_f32_16x16x128_f8f6f4 v[240:243], v[168:175], v[80:87], v[16:19]
	v_mfma_f32_16x16x128_f8f6f4 v[244:247], v[160:167], v[88:95], v[4:7]
	v_mfma_f32_16x16x128_f8f6f4 v[248:251], v[168:175], v[88:95], v[0:3]
	s_setprio 0
	s_barrier
; #define PG8_STAGE(bufoff, gbase, voff) do { _Pragma("unroll") for (int _i = 0; _i < 2; ++_i) \
;         __builtin_amdgcn_global_load_lds((const unsigned*)((const char*)(gbase) + (BYTE_ELEMS ? _i * r##voff + (v##voff)[0] : (v##voff)[_i])), (PG8_LAS unsigned*)(lds + (bufoff) + ldsw + _i * 8192), 16, 0, 0); } while (0)
; #define PG8_LDA(dst, b, h) do { _Pragma("unroll") for (int m = 0; m < 4; ++m) _Pragma("unroll") for (int k = 0; k < 2; ++k) dst[m][k] = *(const PG8_LAS bf16x8*)(lds + PG8_SA(b, h) + aoff + m * 2048 + k * 1024); } while (0)
; #define PG8_LDB(dst, b, h) do { _Pragma("unroll") for (int n = 0; n < 2; ++n) _Pragma("unroll") for (int k = 0; k < 2; ++k) dst[n][k] = *(const PG8_LAS bf16x8*)(lds + PG8_SB(b, h) + boff + n * 2048 + k * 1024); } while (0)
; #define PG8_WAIT_V(n) asm volatile("s_waitcnt vmcnt(" #n ")" ::: "memory")
; #define PG8_WAIT_L(n) asm volatile("s_waitcnt lgkmcnt(" #n ")" ::: "memory")
; #define PG8_BAR __builtin_amdgcn_s_barrier()
; #define PG8_SCHED __builtin_amdgcn_sched_barrier(0)
;     ...
;         for (int t = 0; t < nt; t += 2) {
;     ...
;             PG8_LDB(B0, 0, 0); PG8_LDB(B1, 0, 1); PG8_SCHED; PG8_LDA(At, 0, 0); PG8_STAGE(PG8_SA(1, 1), a1 + hstepA, offA);
;             PG8_WAIT_V(8); PG8_WAIT_L(0); PG8_BAR; PG8_MMA(0, 0, At, B0); PG8_MMA(0, 1, At, B1); PG8_BAR; PG8_SCHED;
;             PG8_LDA(At, 0, 1); PG8_STAGE(PG8_SB(0, 0), b2, offB); PG8_STAGE(PG8_SB(0, 1), b2 + hstepB, offB); PG8_STAGE(PG8_SA(0, 0), a2, offA);
;             PG8_WAIT_V(8); PG8_WAIT_L(0); PG8_BAR; PG8_MMA(1, 0, At, B0); PG8_MMA(1, 1, At, B1); PG8_BAR; PG8_SCHED;
;             PG8_LDB(B0, 1, 0); PG8_LDB(B1, 1, 1); PG8_SCHED; PG8_LDA(At, 1, 0); PG8_STAGE(PG8_SA(0, 1), a2 + hstepA, offA);
;             PG8_WAIT_V(8); PG8_WAIT_L(0); PG8_BAR; PG8_MMA(0, 0, At, B0); PG8_MMA(0, 1, At, B1); PG8_BAR; PG8_SCHED;
;             PG8_LDA(At, 1, 1); PG8_STAGE(PG8_SB(1, 0), b3, offB); PG8_STAGE(PG8_SB(1, 1), b3 + hstepB, offB); PG8_STAGE(PG8_SA(1, 0), a3, offA);
;             PG8_WAIT_V(8); PG8_WAIT_L(0); PG8_BAR; PG8_MMA(1, 0, At, B0); PG8_MMA(1, 1, At, B1); PG8_BAR; PG8_SCHED;
	s_add_i32 s56, 0, 0x18000
	v_add_u32_e32 v8, s56, v148
	s_add_i32 s57, 0, 0x1c000
	s_nop 1
	ds_read_b128 v[0:3], v8
	ds_read_b128 v[4:7], v8 offset:1024
	ds_read_b128 v[16:19], v8 offset:2048
	ds_read_b128 v[20:23], v8 offset:3072
	v_add_u32_e32 v8, s57, v148
	ds_read_b128 v[136:139], v8
	ds_read_b128 v[140:143], v8 offset:1024
	ds_read_b128 v[152:155], v8 offset:2048
	ds_read_b128 v[156:159], v8 offset:3072
	s_mov_b32 m0, s61
	v_lshl_add_u64 v[64:65], v[254:255], 0, s[16:17]
	ds_read_b128 v[8:11], v151 offset:32768
	ds_read_b128 v[12:15], v151 offset:33792
	ds_read_b128 v[24:27], v151 offset:34816
	ds_read_b128 v[28:31], v151 offset:35840
	ds_read_b128 v[32:35], v151 offset:36864
	ds_read_b128 v[36:39], v151 offset:37888
	ds_read_b128 v[40:43], v151 offset:38912
	ds_read_b128 v[44:47], v151 offset:39936
	global_load_lds_dwordx4 v[64:65], off
	v_lshl_add_u64 v[64:65], v[254:255], 0, s[18:19]
	s_mov_b32 m0, s62
	s_nop 0
	global_load_lds_dwordx4 v[64:65], off
	s_waitcnt vmcnt(8)
	s_waitcnt lgkmcnt(0)
	s_setprio 1
	s_barrier
	v_mfma_f32_16x16x128_f8f6f4 v[124:127], v[0:7], v[8:15], v[124:127]
	v_mfma_f32_16x16x128_f8f6f4 v[120:123], v[16:23], v[8:15], v[120:123]
	v_mfma_f32_16x16x128_f8f6f4 v[108:111], v[0:7], v[24:31], v[108:111]
	v_mfma_f32_16x16x128_f8f6f4 v[104:107], v[16:23], v[24:31], v[104:107]
	v_mfma_f32_16x16x128_f8f6f4 v[92:95], v[0:7], v[32:39], v[144:147]
	v_mfma_f32_16x16x128_f8f6f4 v[88:91], v[16:23], v[32:39], v[208:211]
	v_mfma_f32_16x16x128_f8f6f4 v[76:79], v[0:7], v[40:47], v[212:215]
	v_mfma_f32_16x16x128_f8f6f4 v[72:75], v[16:23], v[40:47], v[216:219]
	s_setprio 0
	s_setprio 1
	v_mfma_f32_16x16x128_f8f6f4 v[116:119], v[136:143], v[8:15], v[116:119]
	v_mfma_f32_16x16x128_f8f6f4 v[112:115], v[152:159], v[8:15], v[112:115]
	v_mfma_f32_16x16x128_f8f6f4 v[100:103], v[136:143], v[24:31], v[100:103]
	v_mfma_f32_16x16x128_f8f6f4 v[96:99], v[152:159], v[24:31], v[96:99]
	v_mfma_f32_16x16x128_f8f6f4 v[84:87], v[136:143], v[32:39], v[176:179]
	v_mfma_f32_16x16x128_f8f6f4 v[80:83], v[152:159], v[32:39], v[180:183]
	v_mfma_f32_16x16x128_f8f6f4 v[68:71], v[136:143], v[40:47], v[184:187]
	v_mfma_f32_16x16x128_f8f6f4 v[64:67], v[152:159], v[40:47], v[188:191]
	s_setprio 0
	s_barrier
	s_add_i32 s56, s56, s33
	v_lshl_add_u64 v[8:9], v[252:253], 0, s[38:39]
	s_mov_b32 m0, s56
	ds_read_b128 v[32:35], v151 offset:49152
	ds_read_b128 v[36:39], v151 offset:50176
	ds_read_b128 v[160:163], v151 offset:51200
	ds_read_b128 v[164:167], v151 offset:52224
	ds_read_b128 v[168:171], v151 offset:53248
	ds_read_b128 v[172:175], v151 offset:54272
	ds_read_b128 v[176:179], v151 offset:55296
	ds_read_b128 v[180:183], v151 offset:56320
	global_load_lds_dwordx4 v[8:9], off
	v_lshl_add_u64 v[8:9], v[252:253], 0, s[40:41]
	s_add_i32 m0, s56, 0x2000
	s_add_i32 s56, s57, s33
	global_load_lds_dwordx4 v[8:9], off
	v_lshl_add_u64 v[8:9], v[252:253], 0, s[42:43]
	s_mov_b32 m0, s56
	s_nop 0
	global_load_lds_dwordx4 v[8:9], off
	v_lshl_add_u64 v[8:9], v[252:253], 0, s[44:45]
	s_add_i32 m0, s56, 0x2000
	s_nop 0
	global_load_lds_dwordx4 v[8:9], off
	v_lshl_add_u64 v[8:9], v[254:255], 0, s[38:39]
	s_mov_b32 m0, s64
	s_nop 0
	global_load_lds_dwordx4 v[8:9], off
	v_lshl_add_u64 v[8:9], v[254:255], 0, s[40:41]
	s_mov_b32 m0, s65
	s_nop 0
	global_load_lds_dwordx4 v[8:9], off
	s_waitcnt vmcnt(8)
	s_waitcnt lgkmcnt(0)
	s_setprio 1
	s_barrier
	v_mfma_f32_16x16x128_f8f6f4 v[60:63], v[0:7], v[32:39], v[60:63]
	v_mfma_f32_16x16x128_f8f6f4 v[56:59], v[16:23], v[32:39], v[56:59]
	v_mfma_f32_16x16x128_f8f6f4 v[44:47], v[0:7], v[160:167], v[192:195]
	v_mfma_f32_16x16x128_f8f6f4 v[40:43], v[16:23], v[160:167], v[196:199]
	v_mfma_f32_16x16x128_f8f6f4 v[28:31], v[0:7], v[168:175], v[200:203]
	v_mfma_f32_16x16x128_f8f6f4 v[24:27], v[16:23], v[168:175], v[204:207]
	v_mfma_f32_16x16x128_f8f6f4 v[12:15], v[0:7], v[176:183], v[220:223]
	v_mfma_f32_16x16x128_f8f6f4 v[8:11], v[16:23], v[176:183], v[224:227]
	s_setprio 0
	s_setprio 1
	v_mfma_f32_16x16x128_f8f6f4 v[52:55], v[136:143], v[32:39], v[52:55]
	v_mfma_f32_16x16x128_f8f6f4 v[48:51], v[152:159], v[32:39], v[48:51]
	v_mfma_f32_16x16x128_f8f6f4 v[36:39], v[136:143], v[160:167], v[228:231]
	v_mfma_f32_16x16x128_f8f6f4 v[32:35], v[152:159], v[160:167], v[232:235]
	v_mfma_f32_16x16x128_f8f6f4 v[20:23], v[136:143], v[168:175], v[236:239]
	v_mfma_f32_16x16x128_f8f6f4 v[16:19], v[152:159], v[168:175], v[240:243]
	v_mfma_f32_16x16x128_f8f6f4 v[4:7], v[136:143], v[176:183], v[244:247]
	v_mfma_f32_16x16x128_f8f6f4 v[0:3], v[152:159], v[176:183], v[248:251]
	s_setprio 0
	s_barrier
	s_add_i32 s81, s81, 2
	s_add_u32 s54, s54, 0x100
	s_addc_u32 s55, s55, 0
	s_add_u32 s79, s79, 0x100
	s_addc_u32 s80, s80, 0
	s_cmp_gt_u32 s81, 41
	s_cbranch_scc0 .LBB0_1466
	s_and_b64 vcc, exec, s[46:47]
	s_cbranch_vccz .LBB0_1469
	s_barrier
